# redundant-wait trimming: back-to-back duplicate s_waitcnt lgkmcnt(0) removed at the head of every K-loop MFMA cluster (after the setprio flip deletion)
# speedup vs baseline: 1.0009x; 1.0009x over previous
; #define LDA(dst, b, h) for (int m = 0; m < 4; ++m) for (int k = 0; k < 2; ++k) \
;     dst[m][k] = *reinterpret_cast<const bf16x8*>((char*)SA(b, h) + lds_byte(wr * 64 + m * 16 + fr, k * 32 + fq * 8))
; #define LDB(dst, b, h) for (int n = 0; n < 2; ++n) for (int k = 0; k < 2; ++k) \
;     dst[n][k] = *reinterpret_cast<const bf16x8*>((char*)SB(b, h) + lds_byte(wc * 32 + n * 16 + fr, k * 32 + fq * 8))
; #define MMA(ai, bj, At_, Bt_) do { __builtin_amdgcn_s_setprio(1); \
;     for (int m = 0; m < 4; ++m) for (int n = 0; n < 2; ++n) for (int k = 0; k < 2; ++k) \
;       acc[ai][bj][m][n] = MFMA16(Bt_[n][k], At_[m][k], acc[ai][bj][m][n]); \
;     __builtin_amdgcn_s_setprio(0); } while (0)
; #define WAIT_L(n) asm volatile("s_waitcnt lgkmcnt(" #n ")" ::: "memory")
; #define BAR __builtin_amdgcn_s_barrier()
; #define SCHED __builtin_amdgcn_sched_barrier(0)
; template <int PART  , bool SYNC_FIRST = true>
; __device__ __forceinline__ void kloop_t(const u16* __restrict__ A, int lda, const u16* __restrict__ Bt, int ldb, int K, Acc& acc, const int wv) {
;     ...
;     LDB(B0, 0, 0); SCHED; LDA(At, 0, 0); STAGE(SA(1, 1), A, lda, HALF, t + 1);
;     WAIT_L(8); BAR; WAIT_L(0); MMA(0, 0, At, B0); BAR; SCHED;
;     LDB(B1, 0, 1); STAGE(SB(0, 0), Bt, ldb, 0, t + 2);
;     BAR; WAIT_L(0); MMA(0, 1, At, B1); BAR;
;     LDA(At, 0, 1); STAGE(SA(0, 0), A, lda, 0, t + 2);
.LBB0_193:
	v_add_u32_e32 v157, v149, v153
	v_add_u32_e32 v159, v149, v155
	v_add_u32_e32 v158, v149, v154
	ds_read_b128 v[168:171], v157
	ds_read_b128 v[172:175], v158
	v_add_u32_e32 v160, v149, v156
	ds_read_b128 v[176:179], v159
	ds_read_b128 v[180:183], v160
	s_add_u32 s42, s4, s40
	v_mov_b32_e32 v162, v141
	v_mov_b32_e32 v128, v139
	s_addc_u32 s43, s5, s41
	v_add_u32_e32 v161, 0xc000, v144
	ds_read_b128 v[184:187], v130
	ds_read_b128 v[188:191], v131
	ds_read_b128 v[192:195], v132
	ds_read_b128 v[196:199], v133
	ds_read_b128 v[200:203], v134
	ds_read_b128 v[204:207], v135
	ds_read_b128 v[208:211], v137
	ds_read_b128 v[212:215], v138
	v_readfirstlane_b32 s44, v161
	v_lshl_add_u64 v[164:165], s[42:43], 0, v[128:129]
	v_mov_b32_e32 v163, v129
	v_lshl_add_u64 v[164:165], v[164:165], 0, s[14:15]
	s_mov_b32 m0, s44
	v_lshl_add_u64 v[162:163], s[42:43], 0, v[162:163]
	global_load_lds_dwordx4 v[164:165], off
	v_lshl_add_u64 v[164:165], v[162:163], 0, s[14:15]
	v_add_u32_e32 v162, 0xe000, v144
	s_nop 0
	v_readfirstlane_b32 s44, v162
	s_mov_b32 m0, s44
	s_nop 0
	global_load_lds_dwordx4 v[164:165], off
	s_waitcnt lgkmcnt(8)
	s_barrier
	s_waitcnt lgkmcnt(0)
	v_mfma_f32_16x16x32_bf16 v[124:127], v[168:171], v[184:187], v[124:127]
	v_mfma_f32_16x16x32_bf16 v[120:123], v[176:179], v[184:187], v[120:123]
	v_mfma_f32_16x16x32_bf16 v[116:119], v[168:171], v[192:195], v[116:119]
	v_mfma_f32_16x16x32_bf16 v[112:115], v[176:179], v[192:195], v[112:115]
	v_mfma_f32_16x16x32_bf16 v[108:111], v[168:171], v[200:203], v[108:111]
	v_mfma_f32_16x16x32_bf16 v[104:107], v[176:179], v[200:203], v[104:107]
	v_mfma_f32_16x16x32_bf16 v[100:103], v[168:171], v[208:211], v[100:103]
	v_mfma_f32_16x16x32_bf16 v[96:99], v[176:179], v[208:211], v[96:99]
	v_mfma_f32_16x16x32_bf16 v[124:127], v[172:175], v[188:191], v[124:127]
	v_mfma_f32_16x16x32_bf16 v[120:123], v[180:183], v[188:191], v[120:123]
	v_mfma_f32_16x16x32_bf16 v[116:119], v[172:175], v[196:199], v[116:119]
	v_mfma_f32_16x16x32_bf16 v[112:115], v[180:183], v[196:199], v[112:115]
	v_mfma_f32_16x16x32_bf16 v[108:111], v[172:175], v[204:207], v[108:111]
	v_mfma_f32_16x16x32_bf16 v[104:107], v[180:183], v[204:207], v[104:107]
	v_mfma_f32_16x16x32_bf16 v[100:103], v[172:175], v[212:215], v[100:103]
	v_mfma_f32_16x16x32_bf16 v[96:99], v[180:183], v[212:215], v[96:99]
	s_barrier
	v_add_u32_e32 v163, v150, v153
	v_add_u32_e32 v165, v150, v155
	v_mov_b32_e32 v232, v141
	v_mov_b32_e32 v128, v139
	s_add_u32 s44, s36, s40
	v_add_u32_e32 v164, v150, v154
	ds_read_b128 v[216:219], v163
	ds_read_b128 v[220:223], v164
	v_add_u32_e32 v166, v150, v156
	ds_read_b128 v[224:227], v165
	ds_read_b128 v[228:231], v166
	s_addc_u32 s45, s37, s41
	v_lshl_add_u64 v[234:235], s[44:45], 0, v[128:129]
	v_add_u32_e32 v128, s31, v140
	v_mov_b32_e32 v233, v129
	v_readfirstlane_b32 s53, v128
	v_add_u32_e32 v128, 0x2000, v128
	v_lshl_add_u64 v[234:235], v[234:235], 0, s[16:17]
	s_mov_b32 m0, s53
	v_lshl_add_u64 v[232:233], s[44:45], 0, v[232:233]
	v_readfirstlane_b32 s53, v128
	global_load_lds_dwordx4 v[234:235], off
	v_lshl_add_u64 v[232:233], v[232:233], 0, s[16:17]
	s_mov_b32 m0, s53
	s_nop 0
	global_load_lds_dwordx4 v[232:233], off
	s_barrier
	s_waitcnt lgkmcnt(0)
	v_mfma_f32_16x16x32_bf16 v[92:95], v[216:219], v[184:187], v[92:95]
	v_mfma_f32_16x16x32_bf16 v[88:91], v[224:227], v[184:187], v[88:91]
	v_mfma_f32_16x16x32_bf16 v[84:87], v[216:219], v[192:195], v[84:87]
	v_mfma_f32_16x16x32_bf16 v[80:83], v[224:227], v[192:195], v[80:83]
	v_mfma_f32_16x16x32_bf16 v[76:79], v[216:219], v[200:203], v[76:79]
	v_mfma_f32_16x16x32_bf16 v[72:75], v[224:227], v[200:203], v[72:75]
	v_mfma_f32_16x16x32_bf16 v[68:71], v[216:219], v[208:211], v[68:71]
	v_mfma_f32_16x16x32_bf16 v[64:67], v[224:227], v[208:211], v[64:67]
	v_mfma_f32_16x16x32_bf16 v[92:95], v[220:223], v[188:191], v[92:95]
	v_mfma_f32_16x16x32_bf16 v[88:91], v[228:231], v[188:191], v[88:91]
	v_mfma_f32_16x16x32_bf16 v[84:87], v[220:223], v[196:199], v[84:87]
	v_mfma_f32_16x16x32_bf16 v[80:83], v[228:231], v[196:199], v[80:83]
	v_mfma_f32_16x16x32_bf16 v[76:79], v[220:223], v[204:207], v[76:79]
	v_mfma_f32_16x16x32_bf16 v[72:75], v[228:231], v[204:207], v[72:75]
	v_mfma_f32_16x16x32_bf16 v[68:71], v[220:223], v[212:215], v[68:71]
	v_mfma_f32_16x16x32_bf16 v[64:67], v[228:231], v[212:215], v[64:67]
	v_mov_b32_e32 v232, v141
	v_mov_b32_e32 v128, v139
	s_barrier
	ds_read_b128 v[184:187], v130 offset:16384
	ds_read_b128 v[188:191], v131 offset:16384
	ds_read_b128 v[192:195], v132 offset:16384
	ds_read_b128 v[196:199], v133 offset:16384
	ds_read_b128 v[200:203], v134 offset:16384
	ds_read_b128 v[204:207], v135 offset:16384
	ds_read_b128 v[208:211], v137 offset:16384
	ds_read_b128 v[212:215], v138 offset:16384
	v_readfirstlane_b32 s53, v144
	v_lshl_add_u64 v[234:235], s[42:43], 0, v[128:129]
	v_mov_b32_e32 v233, v129
	v_add_u32_e32 v128, 0x2000, v144
	v_lshl_add_u64 v[234:235], v[234:235], 0, s[16:17]
	s_mov_b32 m0, s53
	v_lshl_add_u64 v[232:233], s[42:43], 0, v[232:233]
	v_readfirstlane_b32 s53, v128
	global_load_lds_dwordx4 v[234:235], off
	v_lshl_add_u64 v[232:233], v[232:233], 0, s[16:17]
	s_mov_b32 m0, s53
	s_nop 0
	global_load_lds_dwordx4 v[232:233], off
	s_barrier
; #define LDA(dst, b, h) for (int m = 0; m < 4; ++m) for (int k = 0; k < 2; ++k) \
;     dst[m][k] = *reinterpret_cast<const bf16x8*>((char*)SA(b, h) + lds_byte(wr * 64 + m * 16 + fr, k * 32 + fq * 8))
; #define LDB(dst, b, h) for (int n = 0; n < 2; ++n) for (int k = 0; k < 2; ++k) \
;     dst[n][k] = *reinterpret_cast<const bf16x8*>((char*)SB(b, h) + lds_byte(wc * 32 + n * 16 + fr, k * 32 + fq * 8))
; #define MMA(ai, bj, At_, Bt_) do { __builtin_amdgcn_s_setprio(1); \
;     for (int m = 0; m < 4; ++m) for (int n = 0; n < 2; ++n) for (int k = 0; k < 2; ++k) \
;       acc[ai][bj][m][n] = MFMA16(Bt_[n][k], At_[m][k], acc[ai][bj][m][n]); \
;     __builtin_amdgcn_s_setprio(0); } while (0)
; #define WAIT_V(n) asm volatile("s_waitcnt vmcnt(" #n ")" ::: "memory")
; #define WAIT_L(n) asm volatile("s_waitcnt lgkmcnt(" #n ")" ::: "memory")
; #define BAR __builtin_amdgcn_s_barrier()
; #define SCHED __builtin_amdgcn_sched_barrier(0)
; template <int PART  , bool SYNC_FIRST = true>
; __device__ __forceinline__ void kloop_t(const u16* __restrict__ A, int lda, const u16* __restrict__ Bt, int ldb, int K, Acc& acc, const int wv) {
;     ...
;     BAR; WAIT_L(0); MMA(1, 0, At, B0); BAR; SCHED;
;     STAGE(SB(0, 1), Bt, ldb, HALF, t + 2);
;     WAIT_V(6); BAR; MMA(1, 1, At, B1); BAR;
;     LDB(B0, 1, 0); SCHED; LDA(At, 1, 0); STAGE(SA(0, 1), A, lda, HALF, t + 2);
;     WAIT_L(8); BAR; WAIT_L(0); MMA(0, 0, At, B0); BAR; SCHED;
;     LDB(B1, 1, 1); STAGE(SB(1, 0), Bt, ldb, 0, t + 3);
;     BAR; WAIT_L(0); MMA(0, 1, At, B1); BAR;
	s_waitcnt lgkmcnt(0)
	v_mfma_f32_16x16x32_bf16 v[60:63], v[168:171], v[184:187], v[60:63]
	v_mfma_f32_16x16x32_bf16 v[56:59], v[176:179], v[184:187], v[56:59]
	v_mfma_f32_16x16x32_bf16 v[52:55], v[168:171], v[192:195], v[52:55]
	v_mfma_f32_16x16x32_bf16 v[48:51], v[176:179], v[192:195], v[48:51]
	v_mfma_f32_16x16x32_bf16 v[44:47], v[168:171], v[200:203], v[44:47]
	v_mfma_f32_16x16x32_bf16 v[40:43], v[176:179], v[200:203], v[40:43]
	v_mfma_f32_16x16x32_bf16 v[36:39], v[168:171], v[208:211], v[36:39]
	v_mfma_f32_16x16x32_bf16 v[32:35], v[176:179], v[208:211], v[32:35]
	v_mfma_f32_16x16x32_bf16 v[60:63], v[172:175], v[188:191], v[60:63]
	v_mfma_f32_16x16x32_bf16 v[56:59], v[180:183], v[188:191], v[56:59]
	v_mfma_f32_16x16x32_bf16 v[52:55], v[172:175], v[196:199], v[52:55]
	v_mfma_f32_16x16x32_bf16 v[48:51], v[180:183], v[196:199], v[48:51]
	v_mfma_f32_16x16x32_bf16 v[44:47], v[172:175], v[204:207], v[44:47]
	v_mfma_f32_16x16x32_bf16 v[40:43], v[180:183], v[204:207], v[40:43]
	v_mfma_f32_16x16x32_bf16 v[36:39], v[172:175], v[212:215], v[36:39]
	v_mfma_f32_16x16x32_bf16 v[32:35], v[180:183], v[212:215], v[32:35]
	s_barrier
	v_mov_b32_e32 v168, v141
	v_mov_b32_e32 v128, v139
	v_mov_b32_e32 v169, v129
	v_lshl_add_u64 v[170:171], s[44:45], 0, v[128:129]
	v_add_u32_e32 v128, s35, v140
	v_lshl_add_u64 v[170:171], v[170:171], 0, s[18:19]
	v_readfirstlane_b32 s53, v128
	v_add_u32_e32 v128, 0x2000, v128
	s_mov_b32 m0, s53
	v_lshl_add_u64 v[168:169], s[44:45], 0, v[168:169]
	v_readfirstlane_b32 s53, v128
	global_load_lds_dwordx4 v[170:171], off
	v_lshl_add_u64 v[168:169], v[168:169], 0, s[18:19]
	s_mov_b32 m0, s53
	s_nop 0
	global_load_lds_dwordx4 v[168:169], off
	s_waitcnt vmcnt(6)
	s_barrier
	v_mfma_f32_16x16x32_bf16 v[28:31], v[216:219], v[184:187], v[28:31]
	v_mfma_f32_16x16x32_bf16 v[24:27], v[224:227], v[184:187], v[24:27]
	v_mfma_f32_16x16x32_bf16 v[20:23], v[216:219], v[192:195], v[20:23]
	v_mfma_f32_16x16x32_bf16 v[16:19], v[224:227], v[192:195], v[16:19]
	v_mfma_f32_16x16x32_bf16 v[12:15], v[216:219], v[200:203], v[12:15]
	v_mfma_f32_16x16x32_bf16 v[8:11], v[224:227], v[200:203], v[8:11]
	v_mfma_f32_16x16x32_bf16 v[4:7], v[216:219], v[208:211], v[4:7]
	v_mfma_f32_16x16x32_bf16 v[0:3], v[224:227], v[208:211], v[0:3]
	v_mfma_f32_16x16x32_bf16 v[28:31], v[220:223], v[188:191], v[28:31]
	v_mfma_f32_16x16x32_bf16 v[24:27], v[228:231], v[188:191], v[24:27]
	v_mfma_f32_16x16x32_bf16 v[20:23], v[220:223], v[196:199], v[20:23]
	v_mfma_f32_16x16x32_bf16 v[16:19], v[228:231], v[196:199], v[16:19]
	v_mfma_f32_16x16x32_bf16 v[12:15], v[220:223], v[204:207], v[12:15]
	v_mfma_f32_16x16x32_bf16 v[8:11], v[228:231], v[204:207], v[8:11]
	v_mfma_f32_16x16x32_bf16 v[4:7], v[220:223], v[212:215], v[4:7]
	v_mfma_f32_16x16x32_bf16 v[0:3], v[228:231], v[212:215], v[0:3]
	v_add_u32_e32 v167, v151, v153
	v_add_u32_e32 v169, v151, v155
	s_barrier
	v_add_u32_e32 v168, v151, v154
	ds_read_b128 v[176:179], v167
	ds_read_b128 v[180:183], v168
	v_add_u32_e32 v170, v151, v156
	ds_read_b128 v[184:187], v169
	ds_read_b128 v[188:191], v170
	v_mov_b32_e32 v172, v141
	v_mov_b32_e32 v128, v139
	ds_read_b128 v[192:195], v130 offset:32768
	ds_read_b128 v[196:199], v131 offset:32768
	ds_read_b128 v[200:203], v132 offset:32768
	ds_read_b128 v[204:207], v133 offset:32768
	ds_read_b128 v[208:211], v134 offset:32768
	ds_read_b128 v[212:215], v135 offset:32768
	ds_read_b128 v[216:219], v137 offset:32768
	ds_read_b128 v[220:223], v138 offset:32768
	v_mov_b32_e32 v173, v129
	v_lshl_add_u64 v[174:175], s[42:43], 0, v[128:129]
	v_add_u32_e32 v128, 0x4000, v144
	v_lshl_add_u64 v[174:175], v[174:175], 0, s[18:19]
	v_readfirstlane_b32 s53, v128
	v_add_u32_e32 v128, 0x6000, v144
	s_mov_b32 m0, s53
	v_lshl_add_u64 v[172:173], s[42:43], 0, v[172:173]
	v_readfirstlane_b32 s53, v128
	global_load_lds_dwordx4 v[174:175], off
	v_lshl_add_u64 v[172:173], v[172:173], 0, s[18:19]
	s_mov_b32 m0, s53
	s_nop 0
	global_load_lds_dwordx4 v[172:173], off
	s_waitcnt lgkmcnt(8)
	s_barrier
	s_waitcnt lgkmcnt(0)
	v_mfma_f32_16x16x32_bf16 v[124:127], v[176:179], v[192:195], v[124:127]
	v_mfma_f32_16x16x32_bf16 v[120:123], v[184:187], v[192:195], v[120:123]
	v_mfma_f32_16x16x32_bf16 v[116:119], v[176:179], v[200:203], v[116:119]
	v_mfma_f32_16x16x32_bf16 v[112:115], v[184:187], v[200:203], v[112:115]
	v_mfma_f32_16x16x32_bf16 v[108:111], v[176:179], v[208:211], v[108:111]
	v_mfma_f32_16x16x32_bf16 v[104:107], v[184:187], v[208:211], v[104:107]
	v_mfma_f32_16x16x32_bf16 v[100:103], v[176:179], v[216:219], v[100:103]
	v_mfma_f32_16x16x32_bf16 v[96:99], v[184:187], v[216:219], v[96:99]
	v_mfma_f32_16x16x32_bf16 v[124:127], v[180:183], v[196:199], v[124:127]
	v_mfma_f32_16x16x32_bf16 v[120:123], v[188:191], v[196:199], v[120:123]
	v_mfma_f32_16x16x32_bf16 v[116:119], v[180:183], v[204:207], v[116:119]
	v_mfma_f32_16x16x32_bf16 v[112:115], v[188:191], v[204:207], v[112:115]
	v_mfma_f32_16x16x32_bf16 v[108:111], v[180:183], v[212:215], v[108:111]
	v_mfma_f32_16x16x32_bf16 v[104:107], v[188:191], v[212:215], v[104:107]
	v_mfma_f32_16x16x32_bf16 v[100:103], v[180:183], v[220:223], v[100:103]
	v_mfma_f32_16x16x32_bf16 v[96:99], v[188:191], v[220:223], v[96:99]
	s_barrier
	v_add_u32_e32 v171, v152, v153
	v_add_u32_e32 v173, v152, v155
	v_mov_b32_e32 v240, v141
	v_mov_b32_e32 v128, v139
	v_add_u32_e32 v172, v152, v154
	ds_read_b128 v[224:227], v171
	ds_read_b128 v[228:231], v172
	v_add_u32_e32 v174, v152, v156
	ds_read_b128 v[232:235], v173
	ds_read_b128 v[236:239], v174
	v_readfirstlane_b32 s53, v142
	v_lshl_add_u64 v[242:243], s[44:45], 0, v[128:129]
	v_mov_b32_e32 v241, v129
	v_lshl_add_u64 v[242:243], v[242:243], 0, s[20:21]
	s_mov_b32 m0, s53
	v_lshl_add_u64 v[240:241], s[44:45], 0, v[240:241]
	v_readfirstlane_b32 s53, v143
	global_load_lds_dwordx4 v[242:243], off
	v_lshl_add_u64 v[240:241], v[240:241], 0, s[20:21]
	s_mov_b32 m0, s53
	s_nop 0
	global_load_lds_dwordx4 v[240:241], off
	s_barrier
; #define LDA(dst, b, h) for (int m = 0; m < 4; ++m) for (int k = 0; k < 2; ++k) \
;     dst[m][k] = *reinterpret_cast<const bf16x8*>((char*)SA(b, h) + lds_byte(wr * 64 + m * 16 + fr, k * 32 + fq * 8))
; #define LDB(dst, b, h) for (int n = 0; n < 2; ++n) for (int k = 0; k < 2; ++k) \
;     dst[n][k] = *reinterpret_cast<const bf16x8*>((char*)SB(b, h) + lds_byte(wc * 32 + n * 16 + fr, k * 32 + fq * 8))
; #define MMA(ai, bj, At_, Bt_) do { __builtin_amdgcn_s_setprio(1); \
;     for (int m = 0; m < 4; ++m) for (int n = 0; n < 2; ++n) for (int k = 0; k < 2; ++k) \
;       acc[ai][bj][m][n] = MFMA16(Bt_[n][k], At_[m][k], acc[ai][bj][m][n]); \
;     __builtin_amdgcn_s_setprio(0); } while (0)
; #define WAIT_V(n) asm volatile("s_waitcnt vmcnt(" #n ")" ::: "memory")
; #define WAIT_L(n) asm volatile("s_waitcnt lgkmcnt(" #n ")" ::: "memory")
; #define BAR __builtin_amdgcn_s_barrier()
; #define SCHED __builtin_amdgcn_sched_barrier(0)
; template <int PART  , bool SYNC_FIRST = true>
; __device__ __forceinline__ void kloop_t(const u16* __restrict__ A, int lda, const u16* __restrict__ Bt, int ldb, int K, Acc& acc, const int wv) {
;     ...
;     BAR; WAIT_L(0); MMA(0, 1, At, B1); BAR;
;     LDA(At, 1, 1); STAGE(SA(1, 0), A, lda, 0, t + 3);
;     BAR; WAIT_L(0); MMA(1, 0, At, B0); BAR; SCHED;
;     STAGE(SB(1, 1), Bt, ldb, HALF, t + 3);
;     WAIT_V(6); BAR; MMA(1, 1, At, B1); BAR;
;   }
;   { LDB(B0, 0, 0); LDA(At, 0, 0); STAGE(SA(1, 1), A, lda, HALF, nt - 1);
	s_waitcnt lgkmcnt(0)
	v_mfma_f32_16x16x32_bf16 v[92:95], v[224:227], v[192:195], v[92:95]
	v_mfma_f32_16x16x32_bf16 v[88:91], v[232:235], v[192:195], v[88:91]
	v_mfma_f32_16x16x32_bf16 v[84:87], v[224:227], v[200:203], v[84:87]
	v_mfma_f32_16x16x32_bf16 v[80:83], v[232:235], v[200:203], v[80:83]
	v_mfma_f32_16x16x32_bf16 v[76:79], v[224:227], v[208:211], v[76:79]
	v_mfma_f32_16x16x32_bf16 v[72:75], v[232:235], v[208:211], v[72:75]
	v_mfma_f32_16x16x32_bf16 v[68:71], v[224:227], v[216:219], v[68:71]
	v_mfma_f32_16x16x32_bf16 v[64:67], v[232:235], v[216:219], v[64:67]
	v_mfma_f32_16x16x32_bf16 v[92:95], v[228:231], v[196:199], v[92:95]
	v_mfma_f32_16x16x32_bf16 v[88:91], v[236:239], v[196:199], v[88:91]
	v_mfma_f32_16x16x32_bf16 v[84:87], v[228:231], v[204:207], v[84:87]
	v_mfma_f32_16x16x32_bf16 v[80:83], v[236:239], v[204:207], v[80:83]
	v_mfma_f32_16x16x32_bf16 v[76:79], v[228:231], v[212:215], v[76:79]
	v_mfma_f32_16x16x32_bf16 v[72:75], v[236:239], v[212:215], v[72:75]
	v_mfma_f32_16x16x32_bf16 v[68:71], v[228:231], v[220:223], v[68:71]
	v_mfma_f32_16x16x32_bf16 v[64:67], v[236:239], v[220:223], v[64:67]
	v_mov_b32_e32 v240, v141
	v_mov_b32_e32 v128, v139
	s_barrier
	ds_read_b128 v[192:195], v130 offset:49152
	ds_read_b128 v[196:199], v131 offset:49152
	ds_read_b128 v[200:203], v132 offset:49152
	ds_read_b128 v[204:207], v133 offset:49152
	ds_read_b128 v[208:211], v134 offset:49152
	ds_read_b128 v[212:215], v135 offset:49152
	ds_read_b128 v[216:219], v137 offset:49152
	ds_read_b128 v[220:223], v138 offset:49152
	v_readfirstlane_b32 s53, v145
	v_lshl_add_u64 v[242:243], s[42:43], 0, v[128:129]
	v_mov_b32_e32 v241, v129
	v_lshl_add_u64 v[242:243], v[242:243], 0, s[20:21]
	s_mov_b32 m0, s53
	v_lshl_add_u64 v[240:241], s[42:43], 0, v[240:241]
	v_readfirstlane_b32 s42, v146
	global_load_lds_dwordx4 v[242:243], off
	v_lshl_add_u64 v[240:241], v[240:241], 0, s[20:21]
	s_mov_b32 m0, s42
	s_nop 0
	global_load_lds_dwordx4 v[240:241], off
	s_barrier
	s_waitcnt lgkmcnt(0)
	v_mfma_f32_16x16x32_bf16 v[60:63], v[176:179], v[192:195], v[60:63]
	v_mfma_f32_16x16x32_bf16 v[56:59], v[184:187], v[192:195], v[56:59]
	v_mfma_f32_16x16x32_bf16 v[52:55], v[176:179], v[200:203], v[52:55]
	v_mfma_f32_16x16x32_bf16 v[48:51], v[184:187], v[200:203], v[48:51]
	v_mfma_f32_16x16x32_bf16 v[44:47], v[176:179], v[208:211], v[44:47]
	v_mfma_f32_16x16x32_bf16 v[40:43], v[184:187], v[208:211], v[40:43]
	v_mfma_f32_16x16x32_bf16 v[36:39], v[176:179], v[216:219], v[36:39]
	v_mfma_f32_16x16x32_bf16 v[32:35], v[184:187], v[216:219], v[32:35]
	v_mfma_f32_16x16x32_bf16 v[60:63], v[180:183], v[196:199], v[60:63]
	v_mfma_f32_16x16x32_bf16 v[56:59], v[188:191], v[196:199], v[56:59]
	v_mfma_f32_16x16x32_bf16 v[52:55], v[180:183], v[204:207], v[52:55]
	v_mfma_f32_16x16x32_bf16 v[48:51], v[188:191], v[204:207], v[48:51]
	v_mfma_f32_16x16x32_bf16 v[44:47], v[180:183], v[212:215], v[44:47]
	v_mfma_f32_16x16x32_bf16 v[40:43], v[188:191], v[212:215], v[40:43]
	v_mfma_f32_16x16x32_bf16 v[36:39], v[180:183], v[220:223], v[36:39]
	v_mfma_f32_16x16x32_bf16 v[32:35], v[188:191], v[220:223], v[32:35]
	s_barrier
	v_mov_b32_e32 v176, v141
	v_mov_b32_e32 v128, v139
	v_readfirstlane_b32 s42, v147
	v_lshl_add_u64 v[178:179], s[44:45], 0, v[128:129]
	v_mov_b32_e32 v177, v129
	v_lshl_add_u64 v[178:179], v[178:179], 0, s[22:23]
	s_mov_b32 m0, s42
	v_lshl_add_u64 v[176:177], s[44:45], 0, v[176:177]
	v_readfirstlane_b32 s42, v148
	global_load_lds_dwordx4 v[178:179], off
	v_lshl_add_u64 v[176:177], v[176:177], 0, s[22:23]
	s_mov_b32 m0, s42
	s_nop 0
	global_load_lds_dwordx4 v[176:177], off
	s_waitcnt vmcnt(6)
	s_barrier
	v_mfma_f32_16x16x32_bf16 v[28:31], v[224:227], v[192:195], v[28:31]
	v_mfma_f32_16x16x32_bf16 v[24:27], v[232:235], v[192:195], v[24:27]
	v_mfma_f32_16x16x32_bf16 v[20:23], v[224:227], v[200:203], v[20:23]
	v_mfma_f32_16x16x32_bf16 v[16:19], v[232:235], v[200:203], v[16:19]
	v_mfma_f32_16x16x32_bf16 v[12:15], v[224:227], v[208:211], v[12:15]
	v_mfma_f32_16x16x32_bf16 v[8:11], v[232:235], v[208:211], v[8:11]
	v_mfma_f32_16x16x32_bf16 v[4:7], v[224:227], v[216:219], v[4:7]
	v_mfma_f32_16x16x32_bf16 v[0:3], v[232:235], v[216:219], v[0:3]
	v_mfma_f32_16x16x32_bf16 v[28:31], v[228:231], v[196:199], v[28:31]
	v_mfma_f32_16x16x32_bf16 v[24:27], v[236:239], v[196:199], v[24:27]
	v_mfma_f32_16x16x32_bf16 v[20:23], v[228:231], v[204:207], v[20:23]
	v_mfma_f32_16x16x32_bf16 v[16:19], v[236:239], v[204:207], v[16:19]
	v_mfma_f32_16x16x32_bf16 v[12:15], v[228:231], v[212:215], v[12:15]
	v_mfma_f32_16x16x32_bf16 v[8:11], v[236:239], v[212:215], v[8:11]
	v_mfma_f32_16x16x32_bf16 v[4:7], v[228:231], v[220:223], v[4:7]
	v_mfma_f32_16x16x32_bf16 v[0:3], v[236:239], v[220:223], v[0:3]
	s_add_i32 s39, s39, 2
	s_add_u32 s40, s40, 0x100
	s_addc_u32 s41, s41, 0
	s_cmp_lt_u32 s39, 12
	s_barrier
	s_cbranch_scc1 .LBB0_193
	s_add_u32 s4, s4, 0x40780
	v_readfirstlane_b32 s36, v161
	s_addc_u32 s5, s5, 0
	s_mov_b32 m0, s36
	v_readfirstlane_b32 s36, v162
	ds_read_b128 v[142:145], v157
	ds_read_b128 v[146:149], v158
	ds_read_b128 v[150:153], v159
	ds_read_b128 v[154:157], v160
	ds_read_b128 v[176:179], v130
	ds_read_b128 v[180:183], v131
	ds_read_b128 v[184:187], v132
	ds_read_b128 v[188:191], v133
	ds_read_b128 v[192:195], v134
	ds_read_b128 v[196:199], v135
	ds_read_b128 v[200:203], v137
	ds_read_b128 v[204:207], v138
	s_nop 0
	global_load_lds_dwordx4 v139, s[4:5]
	s_mov_b32 m0, s36
	s_nop 0
	global_load_lds_dwordx4 v141, s[4:5]
	s_barrier
; #define LDA(dst, b, h) for (int m = 0; m < 4; ++m) for (int k = 0; k < 2; ++k) \
;     dst[m][k] = *reinterpret_cast<const bf16x8*>((char*)SA(b, h) + lds_byte(wr * 64 + m * 16 + fr, k * 32 + fq * 8))
; #define LDB(dst, b, h) for (int n = 0; n < 2; ++n) for (int k = 0; k < 2; ++k) \
;     dst[n][k] = *reinterpret_cast<const bf16x8*>((char*)SB(b, h) + lds_byte(wc * 32 + n * 16 + fr, k * 32 + fq * 8))
; #define MMA(ai, bj, At_, Bt_) do { __builtin_amdgcn_s_setprio(1); \
;     for (int m = 0; m < 4; ++m) for (int n = 0; n < 2; ++n) for (int k = 0; k < 2; ++k) \
;       acc[ai][bj][m][n] = MFMA16(Bt_[n][k], At_[m][k], acc[ai][bj][m][n]); \
;     __builtin_amdgcn_s_setprio(0); } while (0)
; #define WAIT_V(n) asm volatile("s_waitcnt vmcnt(" #n ")" ::: "memory")
; #define WAIT_L(n) asm volatile("s_waitcnt lgkmcnt(" #n ")" ::: "memory")
; #define BAR __builtin_amdgcn_s_barrier()
; template <int PART  , bool SYNC_FIRST = true>
; __device__ __forceinline__ void kloop_t(const u16* __restrict__ A, int lda, const u16* __restrict__ Bt, int ldb, int K, Acc& acc, const int wv) {
;     ...
;     BAR; WAIT_L(0); MMA(0, 0, At, B0); BAR;
;     LDB(B1, 0, 1); BAR; WAIT_L(0); MMA(0, 1, At, B1); BAR;
;     LDA(At, 0, 1); WAIT_V(4); BAR; WAIT_L(0); MMA(1, 0, At, B0); MMA(1, 1, At, B1); BAR; }
;   { LDB(B0, 1, 0); LDA(At, 1, 0); WAIT_V(2); BAR; WAIT_L(0); MMA(0, 0, At, B0); BAR;
	s_waitcnt lgkmcnt(0)
	v_mfma_f32_16x16x32_bf16 v[124:127], v[142:145], v[176:179], v[124:127]
	v_mfma_f32_16x16x32_bf16 v[120:123], v[150:153], v[176:179], v[120:123]
	v_mfma_f32_16x16x32_bf16 v[116:119], v[142:145], v[184:187], v[116:119]
	v_mfma_f32_16x16x32_bf16 v[112:115], v[150:153], v[184:187], v[112:115]
	v_mfma_f32_16x16x32_bf16 v[100:103], v[142:145], v[200:203], v[100:103]
	v_mfma_f32_16x16x32_bf16 v[96:99], v[150:153], v[200:203], v[96:99]
	v_mfma_f32_16x16x32_bf16 v[124:127], v[146:149], v[180:183], v[124:127]
	v_mfma_f32_16x16x32_bf16 v[120:123], v[154:157], v[180:183], v[120:123]
	v_mfma_f32_16x16x32_bf16 v[116:119], v[146:149], v[188:191], v[116:119]
	v_mfma_f32_16x16x32_bf16 v[112:115], v[154:157], v[188:191], v[112:115]
	v_mfma_f32_16x16x32_bf16 v[108:111], v[142:145], v[192:195], v[108:111]
	v_mfma_f32_16x16x32_bf16 v[104:107], v[150:153], v[192:195], v[104:107]
	v_mfma_f32_16x16x32_bf16 v[100:103], v[146:149], v[204:207], v[100:103]
	v_mfma_f32_16x16x32_bf16 v[96:99], v[154:157], v[204:207], v[96:99]
	v_mfma_f32_16x16x32_bf16 v[158:161], v[146:149], v[196:199], v[108:111]
	v_mfma_f32_16x16x32_bf16 v[208:211], v[154:157], v[196:199], v[104:107]
	s_barrier
	s_nop 1
	ds_read_b128 v[104:107], v163
	ds_read_b128 v[108:111], v164
	ds_read_b128 v[162:165], v165
	ds_read_b128 v[212:215], v166
	s_barrier
	s_waitcnt lgkmcnt(0)
	v_mfma_f32_16x16x32_bf16 v[84:87], v[104:107], v[184:187], v[84:87]
	v_mfma_f32_16x16x32_bf16 v[80:83], v[162:165], v[184:187], v[80:83]
	v_mfma_f32_16x16x32_bf16 v[68:71], v[104:107], v[200:203], v[68:71]
	v_mfma_f32_16x16x32_bf16 v[64:67], v[162:165], v[200:203], v[64:67]
	v_mfma_f32_16x16x32_bf16 v[92:95], v[104:107], v[176:179], v[92:95]
	v_mfma_f32_16x16x32_bf16 v[88:91], v[162:165], v[176:179], v[88:91]
	v_mfma_f32_16x16x32_bf16 v[84:87], v[108:111], v[188:191], v[84:87]
	v_mfma_f32_16x16x32_bf16 v[80:83], v[212:215], v[188:191], v[80:83]
	v_mfma_f32_16x16x32_bf16 v[76:79], v[104:107], v[192:195], v[76:79]
	v_mfma_f32_16x16x32_bf16 v[72:75], v[162:165], v[192:195], v[72:75]
	v_mfma_f32_16x16x32_bf16 v[68:71], v[108:111], v[204:207], v[68:71]
	v_mfma_f32_16x16x32_bf16 v[64:67], v[212:215], v[204:207], v[64:67]
	v_mfma_f32_16x16x32_bf16 v[216:219], v[108:111], v[180:183], v[92:95]
	v_mfma_f32_16x16x32_bf16 v[176:179], v[212:215], v[180:183], v[88:91]
	v_mfma_f32_16x16x32_bf16 v[180:183], v[108:111], v[196:199], v[76:79]
	v_mfma_f32_16x16x32_bf16 v[184:187], v[212:215], v[196:199], v[72:75]
	s_barrier
	s_nop 0
	ds_read_b128 v[72:75], v130 offset:16384
	ds_read_b128 v[76:79], v131 offset:16384
	ds_read_b128 v[88:91], v132 offset:16384
	ds_read_b128 v[92:95], v133 offset:16384
	ds_read_b128 v[188:191], v134 offset:16384
	ds_read_b128 v[192:195], v135 offset:16384
	ds_read_b128 v[196:199], v137 offset:16384
	ds_read_b128 v[200:203], v138 offset:16384
	s_waitcnt vmcnt(4)
	s_barrier
	s_waitcnt lgkmcnt(0)
	v_mfma_f32_16x16x32_bf16 v[60:63], v[142:145], v[72:75], v[60:63]
	v_mfma_f32_16x16x32_bf16 v[56:59], v[150:153], v[72:75], v[56:59]
	v_mfma_f32_16x16x32_bf16 v[52:55], v[142:145], v[88:91], v[52:55]
	v_mfma_f32_16x16x32_bf16 v[48:51], v[150:153], v[88:91], v[48:51]
	v_mfma_f32_16x16x32_bf16 v[36:39], v[142:145], v[196:199], v[36:39]
	v_mfma_f32_16x16x32_bf16 v[32:35], v[150:153], v[196:199], v[32:35]
	v_mfma_f32_16x16x32_bf16 v[60:63], v[146:149], v[76:79], v[60:63]
	v_mfma_f32_16x16x32_bf16 v[56:59], v[154:157], v[76:79], v[56:59]
	v_mfma_f32_16x16x32_bf16 v[52:55], v[146:149], v[92:95], v[52:55]
	v_mfma_f32_16x16x32_bf16 v[48:51], v[154:157], v[92:95], v[48:51]
	v_mfma_f32_16x16x32_bf16 v[44:47], v[142:145], v[188:191], v[44:47]
	v_mfma_f32_16x16x32_bf16 v[40:43], v[150:153], v[188:191], v[40:43]
	v_mfma_f32_16x16x32_bf16 v[36:39], v[146:149], v[200:203], v[36:39]
	v_mfma_f32_16x16x32_bf16 v[32:35], v[154:157], v[200:203], v[32:35]
	v_mfma_f32_16x16x32_bf16 v[204:207], v[146:149], v[192:195], v[44:47]
	v_mfma_f32_16x16x32_bf16 v[220:223], v[154:157], v[192:195], v[40:43]
	v_mfma_f32_16x16x32_bf16 v[20:23], v[104:107], v[88:91], v[20:23]
	v_mfma_f32_16x16x32_bf16 v[16:19], v[162:165], v[88:91], v[16:19]
	v_mfma_f32_16x16x32_bf16 v[4:7], v[104:107], v[196:199], v[4:7]
	v_mfma_f32_16x16x32_bf16 v[0:3], v[162:165], v[196:199], v[0:3]
	v_mfma_f32_16x16x32_bf16 v[28:31], v[104:107], v[72:75], v[28:31]
	v_mfma_f32_16x16x32_bf16 v[24:27], v[162:165], v[72:75], v[24:27]
	v_mfma_f32_16x16x32_bf16 v[20:23], v[108:111], v[92:95], v[20:23]
	v_mfma_f32_16x16x32_bf16 v[16:19], v[212:215], v[92:95], v[16:19]
	v_mfma_f32_16x16x32_bf16 v[12:15], v[104:107], v[188:191], v[12:15]
	v_mfma_f32_16x16x32_bf16 v[8:11], v[162:165], v[188:191], v[8:11]
	v_mfma_f32_16x16x32_bf16 v[4:7], v[108:111], v[200:203], v[4:7]
	v_mfma_f32_16x16x32_bf16 v[0:3], v[212:215], v[200:203], v[0:3]
	v_mfma_f32_16x16x32_bf16 v[140:143], v[108:111], v[76:79], v[28:31]
	v_mfma_f32_16x16x32_bf16 v[144:147], v[212:215], v[76:79], v[24:27]
	v_mfma_f32_16x16x32_bf16 v[148:151], v[108:111], v[192:195], v[12:15]
	v_mfma_f32_16x16x32_bf16 v[152:155], v[212:215], v[192:195], v[8:11]
	s_barrier
; #define LDA(dst, b, h) for (int m = 0; m < 4; ++m) for (int k = 0; k < 2; ++k) \
;     dst[m][k] = *reinterpret_cast<const bf16x8*>((char*)SA(b, h) + lds_byte(wr * 64 + m * 16 + fr, k * 32 + fq * 8))
; #define LDB(dst, b, h) for (int n = 0; n < 2; ++n) for (int k = 0; k < 2; ++k) \
;     dst[n][k] = *reinterpret_cast<const bf16x8*>((char*)SB(b, h) + lds_byte(wc * 32 + n * 16 + fr, k * 32 + fq * 8))
; #define MMA(ai, bj, At_, Bt_) do { __builtin_amdgcn_s_setprio(1); \
;     for (int m = 0; m < 4; ++m) for (int n = 0; n < 2; ++n) for (int k = 0; k < 2; ++k) \
;       acc[ai][bj][m][n] = MFMA16(Bt_[n][k], At_[m][k], acc[ai][bj][m][n]); \
;     __builtin_amdgcn_s_setprio(0); } while (0)
; #define WAIT_V(n) asm volatile("s_waitcnt vmcnt(" #n ")" ::: "memory")
; #define WAIT_L(n) asm volatile("s_waitcnt lgkmcnt(" #n ")" ::: "memory")
; #define BAR __builtin_amdgcn_s_barrier()
; template <int PART  , bool SYNC_FIRST = true>
; __device__ __forceinline__ void kloop_t(const u16* __restrict__ A, int lda, const u16* __restrict__ Bt, int ldb, int K, Acc& acc, const int wv) {
;     ...
;   { LDB(B0, 1, 0); LDA(At, 1, 0); WAIT_V(2); BAR; WAIT_L(0); MMA(0, 0, At, B0); BAR;
;     LDB(B1, 1, 1); WAIT_V(0); BAR; WAIT_L(0); MMA(0, 1, At, B1); BAR;
;     LDA(At, 1, 1); BAR; WAIT_L(0); MMA(1, 0, At, B0); MMA(1, 1, At, B1); BAR; }
	s_nop 0
	ds_read_b128 v[8:11], v167
	ds_read_b128 v[12:15], v168
	ds_read_b128 v[162:165], v169
	ds_read_b128 v[166:169], v170
	ds_read_b128 v[24:27], v130 offset:32768
	ds_read_b128 v[28:31], v131 offset:32768
	ds_read_b128 v[40:43], v132 offset:32768
	ds_read_b128 v[44:47], v133 offset:32768
	ds_read_b128 v[188:191], v134 offset:32768
	ds_read_b128 v[192:195], v135 offset:32768
	ds_read_b128 v[196:199], v137 offset:32768
	ds_read_b128 v[200:203], v138 offset:32768
	s_waitcnt vmcnt(2)
	s_barrier
	s_waitcnt lgkmcnt(0)
	v_mfma_f32_16x16x32_bf16 v[72:75], v[8:11], v[24:27], v[124:127]
	v_mfma_f32_16x16x32_bf16 v[124:127], v[12:15], v[28:31], v[72:75]
	v_mfma_f32_16x16x32_bf16 v[72:75], v[162:165], v[24:27], v[120:123]
	v_mfma_f32_16x16x32_bf16 v[120:123], v[166:169], v[28:31], v[72:75]
	v_mfma_f32_16x16x32_bf16 v[72:75], v[8:11], v[40:43], v[116:119]
	v_mfma_f32_16x16x32_bf16 v[108:111], v[12:15], v[44:47], v[72:75]
	v_mfma_f32_16x16x32_bf16 v[72:75], v[162:165], v[40:43], v[112:115]
	v_mfma_f32_16x16x32_bf16 v[104:107], v[166:169], v[44:47], v[72:75]
	v_mfma_f32_16x16x32_bf16 v[72:75], v[8:11], v[188:191], v[158:161]
	v_mfma_f32_16x16x32_bf16 v[92:95], v[12:15], v[192:195], v[72:75]
	v_mfma_f32_16x16x32_bf16 v[72:75], v[162:165], v[188:191], v[208:211]
	v_mfma_f32_16x16x32_bf16 v[88:91], v[166:169], v[192:195], v[72:75]
	v_mfma_f32_16x16x32_bf16 v[72:75], v[8:11], v[196:199], v[100:103]
	v_mfma_f32_16x16x32_bf16 v[76:79], v[12:15], v[200:203], v[72:75]
	v_mfma_f32_16x16x32_bf16 v[72:75], v[162:165], v[196:199], v[96:99]
	v_mfma_f32_16x16x32_bf16 v[72:75], v[166:169], v[200:203], v[72:75]
	s_barrier
	ds_read_b128 v[156:159], v171
	ds_read_b128 v[208:211], v172
	ds_read_b128 v[170:173], v173
	ds_read_b128 v[212:215], v174
	s_waitcnt vmcnt(0)
	s_barrier
	s_waitcnt lgkmcnt(0)
	v_mfma_f32_16x16x32_bf16 v[96:99], v[156:159], v[24:27], v[216:219]
	v_mfma_f32_16x16x32_bf16 v[24:27], v[170:173], v[24:27], v[176:179]
	v_mfma_f32_16x16x32_bf16 v[112:115], v[212:215], v[28:31], v[24:27]
	v_mfma_f32_16x16x32_bf16 v[24:27], v[156:159], v[40:43], v[84:87]
	v_mfma_f32_16x16x32_bf16 v[100:103], v[208:211], v[44:47], v[24:27]
	v_mfma_f32_16x16x32_bf16 v[24:27], v[170:173], v[40:43], v[80:83]
	v_mfma_f32_16x16x32_bf16 v[116:119], v[208:211], v[28:31], v[96:99]
	v_mfma_f32_16x16x32_bf16 v[96:99], v[212:215], v[44:47], v[24:27]
	v_mfma_f32_16x16x32_bf16 v[24:27], v[156:159], v[188:191], v[180:183]
	v_mfma_f32_16x16x32_bf16 v[84:87], v[208:211], v[192:195], v[24:27]
	v_mfma_f32_16x16x32_bf16 v[24:27], v[170:173], v[188:191], v[184:187]
	v_mfma_f32_16x16x32_bf16 v[80:83], v[212:215], v[192:195], v[24:27]
	v_mfma_f32_16x16x32_bf16 v[24:27], v[156:159], v[196:199], v[68:71]
	v_mfma_f32_16x16x32_bf16 v[68:71], v[208:211], v[200:203], v[24:27]
	v_mfma_f32_16x16x32_bf16 v[24:27], v[170:173], v[196:199], v[64:67]
	v_mfma_f32_16x16x32_bf16 v[64:67], v[212:215], v[200:203], v[24:27]
	s_barrier
	ds_read_b128 v[174:177], v130 offset:49152
	ds_read_b128 v[178:181], v131 offset:49152
	ds_read_b128 v[182:185], v132 offset:49152
	ds_read_b128 v[130:133], v133 offset:49152
	ds_read_b128 v[186:189], v134 offset:49152
	ds_read_b128 v[190:193], v135 offset:49152
	ds_read_b128 v[194:197], v137 offset:49152
	ds_read_b128 v[198:201], v138 offset:49152
	s_barrier
	s_waitcnt lgkmcnt(0)
	v_mfma_f32_16x16x32_bf16 v[24:27], v[8:11], v[174:177], v[60:63]
	v_mfma_f32_16x16x32_bf16 v[60:63], v[12:15], v[178:181], v[24:27]
	v_mfma_f32_16x16x32_bf16 v[24:27], v[162:165], v[174:177], v[56:59]
	v_mfma_f32_16x16x32_bf16 v[56:59], v[166:169], v[178:181], v[24:27]
	v_mfma_f32_16x16x32_bf16 v[24:27], v[8:11], v[182:185], v[52:55]
	v_mfma_f32_16x16x32_bf16 v[44:47], v[12:15], v[130:133], v[24:27]
	v_mfma_f32_16x16x32_bf16 v[24:27], v[162:165], v[182:185], v[48:51]
	v_mfma_f32_16x16x32_bf16 v[40:43], v[166:169], v[130:133], v[24:27]
	v_mfma_f32_16x16x32_bf16 v[24:27], v[8:11], v[186:189], v[204:207]
	v_mfma_f32_16x16x32_bf16 v[8:11], v[8:11], v[194:197], v[36:39]
	v_mfma_f32_16x16x32_bf16 v[28:31], v[12:15], v[190:193], v[24:27]
	v_mfma_f32_16x16x32_bf16 v[24:27], v[162:165], v[186:189], v[220:223]
	v_mfma_f32_16x16x32_bf16 v[12:15], v[12:15], v[198:201], v[8:11]
	v_mfma_f32_16x16x32_bf16 v[8:11], v[162:165], v[194:197], v[32:35]
	v_mfma_f32_16x16x32_bf16 v[24:27], v[166:169], v[190:193], v[24:27]
	v_mfma_f32_16x16x32_bf16 v[8:11], v[166:169], v[198:201], v[8:11]
	v_mfma_f32_16x16x32_bf16 v[32:35], v[156:159], v[174:177], v[140:143]
	v_mfma_f32_16x16x32_bf16 v[52:55], v[208:211], v[178:181], v[32:35]
	v_mfma_f32_16x16x32_bf16 v[32:35], v[170:173], v[174:177], v[144:147]
	v_mfma_f32_16x16x32_bf16 v[16:19], v[170:173], v[182:185], v[16:19]
	v_mfma_f32_16x16x32_bf16 v[48:51], v[212:215], v[178:181], v[32:35]
	v_mfma_f32_16x16x32_bf16 v[20:23], v[156:159], v[182:185], v[20:23]
	v_mfma_f32_16x16x32_bf16 v[32:35], v[212:215], v[130:133], v[16:19]
	v_mfma_f32_16x16x32_bf16 v[16:19], v[156:159], v[186:189], v[148:151]
	v_mfma_f32_16x16x32_bf16 v[36:39], v[208:211], v[130:133], v[20:23]
	v_mfma_f32_16x16x32_bf16 v[20:23], v[208:211], v[190:193], v[16:19]
	v_mfma_f32_16x16x32_bf16 v[16:19], v[170:173], v[186:189], v[152:155]
	v_mfma_f32_16x16x32_bf16 v[4:7], v[156:159], v[194:197], v[4:7]
	v_mfma_f32_16x16x32_bf16 v[0:3], v[170:173], v[194:197], v[0:3]
	v_mfma_f32_16x16x32_bf16 v[16:19], v[212:215], v[190:193], v[16:19]
	v_mfma_f32_16x16x32_bf16 v[4:7], v[208:211], v[198:201], v[4:7]
	v_mfma_f32_16x16x32_bf16 v[0:3], v[212:215], v[198:201], v[0:3]
	s_andn2_b64 vcc, exec, s[0:1]
	s_barrier
	s_cbranch_vccnz .LBB0_196
	s_barrier

; #define LDA(dst, b, h) for (int m = 0; m < 4; ++m) for (int k = 0; k < 2; ++k) \
;     dst[m][k] = *reinterpret_cast<const bf16x8*>((char*)SA(b, h) + lds_byte(wr * 64 + m * 16 + fr, k * 32 + fq * 8))
; #define LDB(dst, b, h) for (int n = 0; n < 2; ++n) for (int k = 0; k < 2; ++k) \
;     dst[n][k] = *reinterpret_cast<const bf16x8*>((char*)SB(b, h) + lds_byte(wc * 32 + n * 16 + fr, k * 32 + fq * 8))
; #define MMA(ai, bj, At_, Bt_) do { __builtin_amdgcn_s_setprio(1); \
;     for (int m = 0; m < 4; ++m) for (int n = 0; n < 2; ++n) for (int k = 0; k < 2; ++k) \
;       acc[ai][bj][m][n] = MFMA16(Bt_[n][k], At_[m][k], acc[ai][bj][m][n]); \
;     __builtin_amdgcn_s_setprio(0); } while (0)
; #define WAIT_L(n) asm volatile("s_waitcnt lgkmcnt(" #n ")" ::: "memory")
; #define BAR __builtin_amdgcn_s_barrier()
; #define SCHED __builtin_amdgcn_sched_barrier(0)
; template <int PART  , bool SYNC_FIRST = true>
; __device__ __forceinline__ void kloop_t(const u16* __restrict__ A, int lda, const u16* __restrict__ Bt, int ldb, int K, Acc& acc, const int wv) {
;     ...
;     LDB(B0, 0, 0); SCHED; LDA(At, 0, 0); STAGE(SA(1, 1), A, lda, HALF, t + 1);
;     WAIT_L(8); BAR; WAIT_L(0); MMA(0, 0, At, B0); BAR; SCHED;
;     LDB(B1, 0, 1); STAGE(SB(0, 0), Bt, ldb, 0, t + 2);
;     BAR; WAIT_L(0); MMA(0, 1, At, B1); BAR;
;     LDA(At, 0, 1); STAGE(SA(0, 0), A, lda, 0, t + 2);
.LBB0_318:
	v_add_u32_e32 v164, v156, v160
	v_add_u32_e32 v166, v156, v162
	v_add_u32_e32 v165, v156, v161
	ds_read_b128 v[174:177], v164
	ds_read_b128 v[178:181], v165
	v_add_u32_e32 v167, v156, v163
	ds_read_b128 v[182:185], v166
	ds_read_b128 v[186:189], v167
	s_add_u32 s44, s6, s4
	v_mov_b32_e32 v170, v131
	v_mov_b32_e32 v128, v130
	s_addc_u32 s45, s7, s5
	ds_read_b128 v[190:193], v132
	ds_read_b128 v[194:197], v133
	ds_read_b128 v[198:201], v134
	ds_read_b128 v[202:205], v135
	ds_read_b128 v[206:209], v136
	ds_read_b128 v[210:213], v137
	ds_read_b128 v[214:217], v138
	ds_read_b128 v[218:221], v139
	v_mov_b32_e32 v171, v129
	v_lshl_add_u64 v[168:169], s[44:45], 0, v[128:129]
	v_lshl_add_u64 v[172:173], v[168:169], 0, s[24:25]
	v_add_u32_e32 v168, 0xc000, v142
	v_add_u32_e32 v169, 0xe000, v142
	v_readfirstlane_b32 s52, v168
	s_mov_b32 m0, s52
	v_lshl_add_u64 v[170:171], s[44:45], 0, v[170:171]
	v_readfirstlane_b32 s52, v169
	global_load_lds_dwordx4 v[172:173], off
	v_lshl_add_u64 v[170:171], v[170:171], 0, s[24:25]
	s_mov_b32 m0, s52
	s_nop 0
	global_load_lds_dwordx4 v[170:171], off
	s_waitcnt lgkmcnt(8)
	s_barrier
	s_waitcnt lgkmcnt(0)
	v_mfma_f32_16x16x32_bf16 v[124:127], v[174:177], v[190:193], v[124:127]
	v_mfma_f32_16x16x32_bf16 v[120:123], v[182:185], v[190:193], v[120:123]
	v_mfma_f32_16x16x32_bf16 v[116:119], v[174:177], v[198:201], v[116:119]
	v_mfma_f32_16x16x32_bf16 v[112:115], v[182:185], v[198:201], v[112:115]
	v_mfma_f32_16x16x32_bf16 v[108:111], v[174:177], v[206:209], v[108:111]
	v_mfma_f32_16x16x32_bf16 v[104:107], v[182:185], v[206:209], v[104:107]
	v_mfma_f32_16x16x32_bf16 v[100:103], v[174:177], v[214:217], v[100:103]
	v_mfma_f32_16x16x32_bf16 v[96:99], v[182:185], v[214:217], v[96:99]
	v_mfma_f32_16x16x32_bf16 v[124:127], v[178:181], v[194:197], v[124:127]
	v_mfma_f32_16x16x32_bf16 v[120:123], v[186:189], v[194:197], v[120:123]
	v_mfma_f32_16x16x32_bf16 v[116:119], v[178:181], v[202:205], v[116:119]
	v_mfma_f32_16x16x32_bf16 v[112:115], v[186:189], v[202:205], v[112:115]
	v_mfma_f32_16x16x32_bf16 v[108:111], v[178:181], v[210:213], v[108:111]
	v_mfma_f32_16x16x32_bf16 v[104:107], v[186:189], v[210:213], v[104:107]
	v_mfma_f32_16x16x32_bf16 v[100:103], v[178:181], v[218:221], v[100:103]
	v_mfma_f32_16x16x32_bf16 v[96:99], v[186:189], v[218:221], v[96:99]
	s_barrier
	s_add_u32 s52, s6, s43
	v_add_u32_e32 v170, v157, v160
	v_add_u32_e32 v172, v157, v162
	v_mov_b32_e32 v238, v131
	v_mov_b32_e32 v128, v130
	s_addc_u32 s53, s7, 0
	v_add_u32_e32 v171, v157, v161
	ds_read_b128 v[222:225], v170
	ds_read_b128 v[226:229], v171
	v_add_u32_e32 v173, v157, v163
	ds_read_b128 v[230:233], v172
	ds_read_b128 v[234:237], v173
	v_readfirstlane_b32 s91, v140
	v_lshl_add_u64 v[240:241], s[52:53], 0, v[128:129]
	v_mov_b32_e32 v239, v129
	v_lshl_add_u64 v[240:241], v[240:241], 0, s[26:27]
	s_mov_b32 m0, s91
	v_lshl_add_u64 v[238:239], s[52:53], 0, v[238:239]
	v_readfirstlane_b32 s91, v141
	global_load_lds_dwordx4 v[240:241], off
	v_lshl_add_u64 v[238:239], v[238:239], 0, s[26:27]
	s_mov_b32 m0, s91
	s_nop 0
	global_load_lds_dwordx4 v[238:239], off
	s_barrier
	s_waitcnt lgkmcnt(0)
	v_mfma_f32_16x16x32_bf16 v[92:95], v[222:225], v[190:193], v[92:95]
	v_mfma_f32_16x16x32_bf16 v[88:91], v[230:233], v[190:193], v[88:91]
	v_mfma_f32_16x16x32_bf16 v[84:87], v[222:225], v[198:201], v[84:87]
	v_mfma_f32_16x16x32_bf16 v[80:83], v[230:233], v[198:201], v[80:83]
	v_mfma_f32_16x16x32_bf16 v[76:79], v[222:225], v[206:209], v[76:79]
	v_mfma_f32_16x16x32_bf16 v[72:75], v[230:233], v[206:209], v[72:75]
	v_mfma_f32_16x16x32_bf16 v[68:71], v[222:225], v[214:217], v[68:71]
	v_mfma_f32_16x16x32_bf16 v[64:67], v[230:233], v[214:217], v[64:67]
	v_mfma_f32_16x16x32_bf16 v[92:95], v[226:229], v[194:197], v[92:95]
	v_mfma_f32_16x16x32_bf16 v[88:91], v[234:237], v[194:197], v[88:91]
	v_mfma_f32_16x16x32_bf16 v[84:87], v[226:229], v[202:205], v[84:87]
	v_mfma_f32_16x16x32_bf16 v[80:83], v[234:237], v[202:205], v[80:83]
	v_mfma_f32_16x16x32_bf16 v[76:79], v[226:229], v[210:213], v[76:79]
	v_mfma_f32_16x16x32_bf16 v[72:75], v[234:237], v[210:213], v[72:75]
	v_mfma_f32_16x16x32_bf16 v[68:71], v[226:229], v[218:221], v[68:71]
	v_mfma_f32_16x16x32_bf16 v[64:67], v[234:237], v[218:221], v[64:67]
	v_mov_b32_e32 v238, v131
	v_mov_b32_e32 v128, v130
	s_barrier
	ds_read_b128 v[190:193], v132 offset:16384
	ds_read_b128 v[194:197], v133 offset:16384
	ds_read_b128 v[198:201], v134 offset:16384
	ds_read_b128 v[202:205], v135 offset:16384
	ds_read_b128 v[206:209], v136 offset:16384
	ds_read_b128 v[210:213], v137 offset:16384
	ds_read_b128 v[214:217], v138 offset:16384
	ds_read_b128 v[218:221], v139 offset:16384
	v_readfirstlane_b32 s91, v142
	v_lshl_add_u64 v[240:241], s[44:45], 0, v[128:129]
	v_mov_b32_e32 v239, v129
	v_lshl_add_u64 v[240:241], v[240:241], 0, s[28:29]
	s_mov_b32 m0, s91
	v_lshl_add_u64 v[238:239], s[44:45], 0, v[238:239]
	v_readfirstlane_b32 s91, v143
	global_load_lds_dwordx4 v[240:241], off
	v_lshl_add_u64 v[238:239], v[238:239], 0, s[28:29]
	s_mov_b32 m0, s91
	s_nop 0
	global_load_lds_dwordx4 v[238:239], off
	s_barrier
; #define LDA(dst, b, h) for (int m = 0; m < 4; ++m) for (int k = 0; k < 2; ++k) \
;     dst[m][k] = *reinterpret_cast<const bf16x8*>((char*)SA(b, h) + lds_byte(wr * 64 + m * 16 + fr, k * 32 + fq * 8))
; #define LDB(dst, b, h) for (int n = 0; n < 2; ++n) for (int k = 0; k < 2; ++k) \
;     dst[n][k] = *reinterpret_cast<const bf16x8*>((char*)SB(b, h) + lds_byte(wc * 32 + n * 16 + fr, k * 32 + fq * 8))
; #define MMA(ai, bj, At_, Bt_) do { __builtin_amdgcn_s_setprio(1); \
;     for (int m = 0; m < 4; ++m) for (int n = 0; n < 2; ++n) for (int k = 0; k < 2; ++k) \
;       acc[ai][bj][m][n] = MFMA16(Bt_[n][k], At_[m][k], acc[ai][bj][m][n]); \
;     __builtin_amdgcn_s_setprio(0); } while (0)
; #define WAIT_V(n) asm volatile("s_waitcnt vmcnt(" #n ")" ::: "memory")
; #define WAIT_L(n) asm volatile("s_waitcnt lgkmcnt(" #n ")" ::: "memory")
; #define BAR __builtin_amdgcn_s_barrier()
; #define SCHED __builtin_amdgcn_sched_barrier(0)
; template <int PART  , bool SYNC_FIRST = true>
; __device__ __forceinline__ void kloop_t(const u16* __restrict__ A, int lda, const u16* __restrict__ Bt, int ldb, int K, Acc& acc, const int wv) {
;     ...
;     BAR; WAIT_L(0); MMA(1, 0, At, B0); BAR; SCHED;
;     STAGE(SB(0, 1), Bt, ldb, HALF, t + 2);
;     WAIT_V(6); BAR; MMA(1, 1, At, B1); BAR;
;     LDB(B0, 1, 0); SCHED; LDA(At, 1, 0); STAGE(SA(0, 1), A, lda, HALF, t + 2);
;     WAIT_L(8); BAR; WAIT_L(0); MMA(0, 0, At, B0); BAR; SCHED;
;     LDB(B1, 1, 1); STAGE(SB(1, 0), Bt, ldb, 0, t + 3);
;     BAR; WAIT_L(0); MMA(0, 1, At, B1); BAR;
	s_waitcnt lgkmcnt(0)
	v_mfma_f32_16x16x32_bf16 v[60:63], v[174:177], v[190:193], v[60:63]
	v_mfma_f32_16x16x32_bf16 v[56:59], v[182:185], v[190:193], v[56:59]
	v_mfma_f32_16x16x32_bf16 v[52:55], v[174:177], v[198:201], v[52:55]
	v_mfma_f32_16x16x32_bf16 v[48:51], v[182:185], v[198:201], v[48:51]
	v_mfma_f32_16x16x32_bf16 v[44:47], v[174:177], v[206:209], v[44:47]
	v_mfma_f32_16x16x32_bf16 v[40:43], v[182:185], v[206:209], v[40:43]
	v_mfma_f32_16x16x32_bf16 v[36:39], v[174:177], v[214:217], v[36:39]
	v_mfma_f32_16x16x32_bf16 v[32:35], v[182:185], v[214:217], v[32:35]
	v_mfma_f32_16x16x32_bf16 v[60:63], v[178:181], v[194:197], v[60:63]
	v_mfma_f32_16x16x32_bf16 v[56:59], v[186:189], v[194:197], v[56:59]
	v_mfma_f32_16x16x32_bf16 v[52:55], v[178:181], v[202:205], v[52:55]
	v_mfma_f32_16x16x32_bf16 v[48:51], v[186:189], v[202:205], v[48:51]
	v_mfma_f32_16x16x32_bf16 v[44:47], v[178:181], v[210:213], v[44:47]
	v_mfma_f32_16x16x32_bf16 v[40:43], v[186:189], v[210:213], v[40:43]
	v_mfma_f32_16x16x32_bf16 v[36:39], v[178:181], v[218:221], v[36:39]
	v_mfma_f32_16x16x32_bf16 v[32:35], v[186:189], v[218:221], v[32:35]
	s_barrier
	v_mov_b32_e32 v174, v131
	v_mov_b32_e32 v128, v130
	v_readfirstlane_b32 s91, v144
	v_lshl_add_u64 v[176:177], s[52:53], 0, v[128:129]
	v_mov_b32_e32 v175, v129
	v_lshl_add_u64 v[176:177], v[176:177], 0, s[30:31]
	s_mov_b32 m0, s91
	v_lshl_add_u64 v[174:175], s[52:53], 0, v[174:175]
	v_readfirstlane_b32 s91, v145
	global_load_lds_dwordx4 v[176:177], off
	v_lshl_add_u64 v[174:175], v[174:175], 0, s[30:31]
	s_mov_b32 m0, s91
	s_nop 0
	global_load_lds_dwordx4 v[174:175], off
	s_waitcnt vmcnt(6)
	s_barrier
	v_mfma_f32_16x16x32_bf16 v[28:31], v[222:225], v[190:193], v[28:31]
	v_mfma_f32_16x16x32_bf16 v[24:27], v[230:233], v[190:193], v[24:27]
	v_mfma_f32_16x16x32_bf16 v[20:23], v[222:225], v[198:201], v[20:23]
	v_mfma_f32_16x16x32_bf16 v[16:19], v[230:233], v[198:201], v[16:19]
	v_mfma_f32_16x16x32_bf16 v[12:15], v[222:225], v[206:209], v[12:15]
	v_mfma_f32_16x16x32_bf16 v[8:11], v[230:233], v[206:209], v[8:11]
	v_mfma_f32_16x16x32_bf16 v[4:7], v[222:225], v[214:217], v[4:7]
	v_mfma_f32_16x16x32_bf16 v[0:3], v[230:233], v[214:217], v[0:3]
	v_mfma_f32_16x16x32_bf16 v[28:31], v[226:229], v[194:197], v[28:31]
	v_mfma_f32_16x16x32_bf16 v[24:27], v[234:237], v[194:197], v[24:27]
	v_mfma_f32_16x16x32_bf16 v[20:23], v[226:229], v[202:205], v[20:23]
	v_mfma_f32_16x16x32_bf16 v[16:19], v[234:237], v[202:205], v[16:19]
	v_mfma_f32_16x16x32_bf16 v[12:15], v[226:229], v[210:213], v[12:15]
	v_mfma_f32_16x16x32_bf16 v[8:11], v[234:237], v[210:213], v[8:11]
	v_mfma_f32_16x16x32_bf16 v[4:7], v[226:229], v[218:221], v[4:7]
	v_mfma_f32_16x16x32_bf16 v[0:3], v[234:237], v[218:221], v[0:3]
	v_add_u32_e32 v174, v158, v160
	v_add_u32_e32 v176, v158, v162
	s_barrier
	v_add_u32_e32 v175, v158, v161
	ds_read_b128 v[182:185], v174
	ds_read_b128 v[186:189], v175
	v_add_u32_e32 v177, v158, v163
	ds_read_b128 v[190:193], v176
	ds_read_b128 v[194:197], v177
	v_mov_b32_e32 v178, v131
	v_mov_b32_e32 v128, v130
	ds_read_b128 v[198:201], v132 offset:32768
	ds_read_b128 v[202:205], v133 offset:32768
	ds_read_b128 v[206:209], v134 offset:32768
	ds_read_b128 v[210:213], v135 offset:32768
	ds_read_b128 v[214:217], v136 offset:32768
	ds_read_b128 v[218:221], v137 offset:32768
	ds_read_b128 v[222:225], v138 offset:32768
	ds_read_b128 v[226:229], v139 offset:32768
	v_readfirstlane_b32 s91, v148
	v_lshl_add_u64 v[180:181], s[44:45], 0, v[128:129]
	v_mov_b32_e32 v179, v129
	v_lshl_add_u64 v[180:181], v[180:181], 0, s[34:35]
	s_mov_b32 m0, s91
	v_lshl_add_u64 v[178:179], s[44:45], 0, v[178:179]
	v_readfirstlane_b32 s91, v149
	global_load_lds_dwordx4 v[180:181], off
	v_lshl_add_u64 v[178:179], v[178:179], 0, s[34:35]
	s_mov_b32 m0, s91
	s_nop 0
	global_load_lds_dwordx4 v[178:179], off
	s_waitcnt lgkmcnt(8)
	s_barrier
	s_waitcnt lgkmcnt(0)
	v_mfma_f32_16x16x32_bf16 v[124:127], v[182:185], v[198:201], v[124:127]
	v_mfma_f32_16x16x32_bf16 v[120:123], v[190:193], v[198:201], v[120:123]
	v_mfma_f32_16x16x32_bf16 v[116:119], v[182:185], v[206:209], v[116:119]
	v_mfma_f32_16x16x32_bf16 v[112:115], v[190:193], v[206:209], v[112:115]
	v_mfma_f32_16x16x32_bf16 v[108:111], v[182:185], v[214:217], v[108:111]
	v_mfma_f32_16x16x32_bf16 v[104:107], v[190:193], v[214:217], v[104:107]
	v_mfma_f32_16x16x32_bf16 v[100:103], v[182:185], v[222:225], v[100:103]
	v_mfma_f32_16x16x32_bf16 v[96:99], v[190:193], v[222:225], v[96:99]
	v_mfma_f32_16x16x32_bf16 v[124:127], v[186:189], v[202:205], v[124:127]
	v_mfma_f32_16x16x32_bf16 v[120:123], v[194:197], v[202:205], v[120:123]
	v_mfma_f32_16x16x32_bf16 v[116:119], v[186:189], v[210:213], v[116:119]
	v_mfma_f32_16x16x32_bf16 v[112:115], v[194:197], v[210:213], v[112:115]
	v_mfma_f32_16x16x32_bf16 v[108:111], v[186:189], v[218:221], v[108:111]
	v_mfma_f32_16x16x32_bf16 v[104:107], v[194:197], v[218:221], v[104:107]
	v_mfma_f32_16x16x32_bf16 v[100:103], v[186:189], v[226:229], v[100:103]
	v_mfma_f32_16x16x32_bf16 v[96:99], v[194:197], v[226:229], v[96:99]
	s_barrier
	v_add_u32_e32 v178, v159, v160
	v_add_u32_e32 v180, v159, v162
	v_mov_b32_e32 v246, v131
	v_mov_b32_e32 v128, v130
	v_add_u32_e32 v179, v159, v161
	ds_read_b128 v[230:233], v178
	ds_read_b128 v[234:237], v179
	v_add_u32_e32 v181, v159, v163
	ds_read_b128 v[238:241], v180
	ds_read_b128 v[242:245], v181
	v_readfirstlane_b32 s91, v150
	v_lshl_add_u64 v[248:249], s[52:53], 0, v[128:129]
	v_mov_b32_e32 v247, v129
	v_lshl_add_u64 v[248:249], v[248:249], 0, s[36:37]
	s_mov_b32 m0, s91
	v_lshl_add_u64 v[246:247], s[52:53], 0, v[246:247]
	v_readfirstlane_b32 s91, v151
	global_load_lds_dwordx4 v[248:249], off
	v_lshl_add_u64 v[246:247], v[246:247], 0, s[36:37]
	s_mov_b32 m0, s91
	s_nop 0
	global_load_lds_dwordx4 v[246:247], off
	s_barrier
; #define LDA(dst, b, h) for (int m = 0; m < 4; ++m) for (int k = 0; k < 2; ++k) \
;     dst[m][k] = *reinterpret_cast<const bf16x8*>((char*)SA(b, h) + lds_byte(wr * 64 + m * 16 + fr, k * 32 + fq * 8))
; #define LDB(dst, b, h) for (int n = 0; n < 2; ++n) for (int k = 0; k < 2; ++k) \
;     dst[n][k] = *reinterpret_cast<const bf16x8*>((char*)SB(b, h) + lds_byte(wc * 32 + n * 16 + fr, k * 32 + fq * 8))
; #define MMA(ai, bj, At_, Bt_) do { __builtin_amdgcn_s_setprio(1); \
;     for (int m = 0; m < 4; ++m) for (int n = 0; n < 2; ++n) for (int k = 0; k < 2; ++k) \
;       acc[ai][bj][m][n] = MFMA16(Bt_[n][k], At_[m][k], acc[ai][bj][m][n]); \
;     __builtin_amdgcn_s_setprio(0); } while (0)
; #define WAIT_V(n) asm volatile("s_waitcnt vmcnt(" #n ")" ::: "memory")
; #define WAIT_L(n) asm volatile("s_waitcnt lgkmcnt(" #n ")" ::: "memory")
; #define BAR __builtin_amdgcn_s_barrier()
; #define SCHED __builtin_amdgcn_sched_barrier(0)
; template <int PART  , bool SYNC_FIRST = true>
; __device__ __forceinline__ void kloop_t(const u16* __restrict__ A, int lda, const u16* __restrict__ Bt, int ldb, int K, Acc& acc, const int wv) {
;     ...
;     BAR; WAIT_L(0); MMA(0, 1, At, B1); BAR;
;     LDA(At, 1, 1); STAGE(SA(1, 0), A, lda, 0, t + 3);
;     BAR; WAIT_L(0); MMA(1, 0, At, B0); BAR; SCHED;
;     STAGE(SB(1, 1), Bt, ldb, HALF, t + 3);
;     WAIT_V(6); BAR; MMA(1, 1, At, B1); BAR;
;   }
;   { LDB(B0, 0, 0); LDA(At, 0, 0); STAGE(SA(1, 1), A, lda, HALF, nt - 1);
	s_waitcnt lgkmcnt(0)
	v_mfma_f32_16x16x32_bf16 v[92:95], v[230:233], v[198:201], v[92:95]
	v_mfma_f32_16x16x32_bf16 v[88:91], v[238:241], v[198:201], v[88:91]
	v_mfma_f32_16x16x32_bf16 v[84:87], v[230:233], v[206:209], v[84:87]
	v_mfma_f32_16x16x32_bf16 v[80:83], v[238:241], v[206:209], v[80:83]
	v_mfma_f32_16x16x32_bf16 v[76:79], v[230:233], v[214:217], v[76:79]
	v_mfma_f32_16x16x32_bf16 v[72:75], v[238:241], v[214:217], v[72:75]
	v_mfma_f32_16x16x32_bf16 v[68:71], v[230:233], v[222:225], v[68:71]
	v_mfma_f32_16x16x32_bf16 v[64:67], v[238:241], v[222:225], v[64:67]
	v_mfma_f32_16x16x32_bf16 v[92:95], v[234:237], v[202:205], v[92:95]
	v_mfma_f32_16x16x32_bf16 v[88:91], v[242:245], v[202:205], v[88:91]
	v_mfma_f32_16x16x32_bf16 v[84:87], v[234:237], v[210:213], v[84:87]
	v_mfma_f32_16x16x32_bf16 v[80:83], v[242:245], v[210:213], v[80:83]
	v_mfma_f32_16x16x32_bf16 v[76:79], v[234:237], v[218:221], v[76:79]
	v_mfma_f32_16x16x32_bf16 v[72:75], v[242:245], v[218:221], v[72:75]
	v_mfma_f32_16x16x32_bf16 v[68:71], v[234:237], v[226:229], v[68:71]
	v_mfma_f32_16x16x32_bf16 v[64:67], v[242:245], v[226:229], v[64:67]
	v_mov_b32_e32 v246, v131
	v_mov_b32_e32 v128, v130
	s_barrier
	ds_read_b128 v[198:201], v132 offset:49152
	ds_read_b128 v[202:205], v133 offset:49152
	ds_read_b128 v[206:209], v134 offset:49152
	ds_read_b128 v[210:213], v135 offset:49152
	ds_read_b128 v[214:217], v136 offset:49152
	ds_read_b128 v[218:221], v137 offset:49152
	ds_read_b128 v[222:225], v138 offset:49152
	ds_read_b128 v[226:229], v139 offset:49152
	v_readfirstlane_b32 s91, v152
	v_lshl_add_u64 v[248:249], s[44:45], 0, v[128:129]
	v_mov_b32_e32 v247, v129
	v_lshl_add_u64 v[248:249], v[248:249], 0, s[38:39]
	s_mov_b32 m0, s91
	v_lshl_add_u64 v[246:247], s[44:45], 0, v[246:247]
	v_readfirstlane_b32 s44, v153
	global_load_lds_dwordx4 v[248:249], off
	v_lshl_add_u64 v[246:247], v[246:247], 0, s[38:39]
	s_mov_b32 m0, s44
	s_nop 0
	global_load_lds_dwordx4 v[246:247], off
	s_barrier
	s_waitcnt lgkmcnt(0)
	v_mfma_f32_16x16x32_bf16 v[60:63], v[182:185], v[198:201], v[60:63]
	v_mfma_f32_16x16x32_bf16 v[56:59], v[190:193], v[198:201], v[56:59]
	v_mfma_f32_16x16x32_bf16 v[52:55], v[182:185], v[206:209], v[52:55]
	v_mfma_f32_16x16x32_bf16 v[48:51], v[190:193], v[206:209], v[48:51]
	v_mfma_f32_16x16x32_bf16 v[44:47], v[182:185], v[214:217], v[44:47]
	v_mfma_f32_16x16x32_bf16 v[40:43], v[190:193], v[214:217], v[40:43]
	v_mfma_f32_16x16x32_bf16 v[36:39], v[182:185], v[222:225], v[36:39]
	v_mfma_f32_16x16x32_bf16 v[32:35], v[190:193], v[222:225], v[32:35]
	v_mfma_f32_16x16x32_bf16 v[60:63], v[186:189], v[202:205], v[60:63]
	v_mfma_f32_16x16x32_bf16 v[56:59], v[194:197], v[202:205], v[56:59]
	v_mfma_f32_16x16x32_bf16 v[52:55], v[186:189], v[210:213], v[52:55]
	v_mfma_f32_16x16x32_bf16 v[48:51], v[194:197], v[210:213], v[48:51]
	v_mfma_f32_16x16x32_bf16 v[44:47], v[186:189], v[218:221], v[44:47]
	v_mfma_f32_16x16x32_bf16 v[40:43], v[194:197], v[218:221], v[40:43]
	v_mfma_f32_16x16x32_bf16 v[36:39], v[186:189], v[226:229], v[36:39]
	v_mfma_f32_16x16x32_bf16 v[32:35], v[194:197], v[226:229], v[32:35]
	s_barrier
	v_mov_b32_e32 v182, v131
	v_mov_b32_e32 v128, v130
	v_readfirstlane_b32 s44, v154
	v_lshl_add_u64 v[184:185], s[52:53], 0, v[128:129]
	v_mov_b32_e32 v183, v129
	v_lshl_add_u64 v[184:185], v[184:185], 0, s[40:41]
	s_mov_b32 m0, s44
	v_lshl_add_u64 v[182:183], s[52:53], 0, v[182:183]
	v_readfirstlane_b32 s44, v155
	global_load_lds_dwordx4 v[184:185], off
	v_lshl_add_u64 v[182:183], v[182:183], 0, s[40:41]
	s_mov_b32 m0, s44
	s_nop 0
	global_load_lds_dwordx4 v[182:183], off
	s_waitcnt vmcnt(6)
	s_barrier
	v_mfma_f32_16x16x32_bf16 v[28:31], v[230:233], v[198:201], v[28:31]
	v_mfma_f32_16x16x32_bf16 v[24:27], v[238:241], v[198:201], v[24:27]
	v_mfma_f32_16x16x32_bf16 v[20:23], v[230:233], v[206:209], v[20:23]
	v_mfma_f32_16x16x32_bf16 v[16:19], v[238:241], v[206:209], v[16:19]
	v_mfma_f32_16x16x32_bf16 v[12:15], v[230:233], v[214:217], v[12:15]
	v_mfma_f32_16x16x32_bf16 v[8:11], v[238:241], v[214:217], v[8:11]
	v_mfma_f32_16x16x32_bf16 v[4:7], v[230:233], v[222:225], v[4:7]
	v_mfma_f32_16x16x32_bf16 v[0:3], v[238:241], v[222:225], v[0:3]
	v_mfma_f32_16x16x32_bf16 v[28:31], v[234:237], v[202:205], v[28:31]
	v_mfma_f32_16x16x32_bf16 v[24:27], v[242:245], v[202:205], v[24:27]
	v_mfma_f32_16x16x32_bf16 v[20:23], v[234:237], v[210:213], v[20:23]
	v_mfma_f32_16x16x32_bf16 v[16:19], v[242:245], v[210:213], v[16:19]
	v_mfma_f32_16x16x32_bf16 v[12:15], v[234:237], v[218:221], v[12:15]
	v_mfma_f32_16x16x32_bf16 v[8:11], v[242:245], v[218:221], v[8:11]
	v_mfma_f32_16x16x32_bf16 v[4:7], v[234:237], v[226:229], v[4:7]
	v_mfma_f32_16x16x32_bf16 v[0:3], v[242:245], v[226:229], v[0:3]
	s_add_i32 s90, s90, 2
	s_add_u32 s6, s6, 0x100
	s_addc_u32 s7, s7, 0
	s_cmp_lt_u32 s90, 12
	s_barrier
	s_cbranch_scc1 .LBB0_318
	s_add_u32 s0, s0, 0x40780
	v_readfirstlane_b32 s4, v168
	s_addc_u32 s1, s1, 0
	s_mov_b32 m0, s4
	v_readfirstlane_b32 s4, v169
	ds_read_b128 v[140:143], v164
	ds_read_b128 v[148:151], v165
	ds_read_b128 v[152:155], v166
	ds_read_b128 v[156:159], v167
	ds_read_b128 v[160:163], v132
	ds_read_b128 v[164:167], v133
	ds_read_b128 v[182:185], v134
	ds_read_b128 v[186:189], v135
	ds_read_b128 v[190:193], v136
	ds_read_b128 v[194:197], v137
	ds_read_b128 v[198:201], v138
	ds_read_b128 v[202:205], v139
	s_nop 0
	global_load_lds_dwordx4 v130, s[0:1]
	s_mov_b32 m0, s4
	s_nop 0
	global_load_lds_dwordx4 v131, s[0:1]
	s_barrier
; #define LDA(dst, b, h) for (int m = 0; m < 4; ++m) for (int k = 0; k < 2; ++k) \
;     dst[m][k] = *reinterpret_cast<const bf16x8*>((char*)SA(b, h) + lds_byte(wr * 64 + m * 16 + fr, k * 32 + fq * 8))
; #define LDB(dst, b, h) for (int n = 0; n < 2; ++n) for (int k = 0; k < 2; ++k) \
;     dst[n][k] = *reinterpret_cast<const bf16x8*>((char*)SB(b, h) + lds_byte(wc * 32 + n * 16 + fr, k * 32 + fq * 8))
; #define MMA(ai, bj, At_, Bt_) do { __builtin_amdgcn_s_setprio(1); \
;     for (int m = 0; m < 4; ++m) for (int n = 0; n < 2; ++n) for (int k = 0; k < 2; ++k) \
;       acc[ai][bj][m][n] = MFMA16(Bt_[n][k], At_[m][k], acc[ai][bj][m][n]); \
;     __builtin_amdgcn_s_setprio(0); } while (0)
; #define WAIT_V(n) asm volatile("s_waitcnt vmcnt(" #n ")" ::: "memory")
; #define WAIT_L(n) asm volatile("s_waitcnt lgkmcnt(" #n ")" ::: "memory")
; #define BAR __builtin_amdgcn_s_barrier()
; template <int PART  , bool SYNC_FIRST = true>
; __device__ __forceinline__ void kloop_t(const u16* __restrict__ A, int lda, const u16* __restrict__ Bt, int ldb, int K, Acc& acc, const int wv) {
;     ...
;     BAR; WAIT_L(0); MMA(0, 0, At, B0); BAR;
;     LDB(B1, 0, 1); BAR; WAIT_L(0); MMA(0, 1, At, B1); BAR;
;     LDA(At, 0, 1); WAIT_V(4); BAR; WAIT_L(0); MMA(1, 0, At, B0); MMA(1, 1, At, B1); BAR; }
;   { LDB(B0, 1, 0); LDA(At, 1, 0); WAIT_V(2); BAR; WAIT_L(0); MMA(0, 0, At, B0); BAR;
	s_waitcnt lgkmcnt(0)
	v_mfma_f32_16x16x32_bf16 v[124:127], v[140:143], v[160:163], v[124:127]
	v_mfma_f32_16x16x32_bf16 v[120:123], v[152:155], v[160:163], v[120:123]
	v_mfma_f32_16x16x32_bf16 v[116:119], v[140:143], v[182:185], v[116:119]
	v_mfma_f32_16x16x32_bf16 v[112:115], v[152:155], v[182:185], v[112:115]
	v_mfma_f32_16x16x32_bf16 v[100:103], v[140:143], v[198:201], v[100:103]
	v_mfma_f32_16x16x32_bf16 v[96:99], v[152:155], v[198:201], v[96:99]
	v_mfma_f32_16x16x32_bf16 v[124:127], v[148:151], v[164:167], v[124:127]
	v_mfma_f32_16x16x32_bf16 v[120:123], v[156:159], v[164:167], v[120:123]
	v_mfma_f32_16x16x32_bf16 v[116:119], v[148:151], v[186:189], v[116:119]
	v_mfma_f32_16x16x32_bf16 v[112:115], v[156:159], v[186:189], v[112:115]
	v_mfma_f32_16x16x32_bf16 v[108:111], v[140:143], v[190:193], v[108:111]
	v_mfma_f32_16x16x32_bf16 v[104:107], v[152:155], v[190:193], v[104:107]
	v_mfma_f32_16x16x32_bf16 v[100:103], v[148:151], v[202:205], v[100:103]
	v_mfma_f32_16x16x32_bf16 v[96:99], v[156:159], v[202:205], v[96:99]
	v_mfma_f32_16x16x32_bf16 v[206:209], v[148:151], v[194:197], v[108:111]
	v_mfma_f32_16x16x32_bf16 v[210:213], v[156:159], v[194:197], v[104:107]
	s_barrier
	s_nop 1
	ds_read_b128 v[104:107], v170
	ds_read_b128 v[108:111], v171
	ds_read_b128 v[168:171], v172
	ds_read_b128 v[214:217], v173
	s_barrier
	s_waitcnt lgkmcnt(0)
	v_mfma_f32_16x16x32_bf16 v[84:87], v[104:107], v[182:185], v[84:87]
	v_mfma_f32_16x16x32_bf16 v[80:83], v[168:171], v[182:185], v[80:83]
	v_mfma_f32_16x16x32_bf16 v[68:71], v[104:107], v[198:201], v[68:71]
	v_mfma_f32_16x16x32_bf16 v[64:67], v[168:171], v[198:201], v[64:67]
	v_mfma_f32_16x16x32_bf16 v[92:95], v[104:107], v[160:163], v[92:95]
	v_mfma_f32_16x16x32_bf16 v[88:91], v[168:171], v[160:163], v[88:91]
	v_mfma_f32_16x16x32_bf16 v[84:87], v[108:111], v[186:189], v[84:87]
	v_mfma_f32_16x16x32_bf16 v[80:83], v[214:217], v[186:189], v[80:83]
	v_mfma_f32_16x16x32_bf16 v[76:79], v[104:107], v[190:193], v[76:79]
	v_mfma_f32_16x16x32_bf16 v[72:75], v[168:171], v[190:193], v[72:75]
	v_mfma_f32_16x16x32_bf16 v[68:71], v[108:111], v[202:205], v[68:71]
	v_mfma_f32_16x16x32_bf16 v[64:67], v[214:217], v[202:205], v[64:67]
	v_mfma_f32_16x16x32_bf16 v[218:221], v[108:111], v[164:167], v[92:95]
	v_mfma_f32_16x16x32_bf16 v[160:163], v[214:217], v[164:167], v[88:91]
	v_mfma_f32_16x16x32_bf16 v[164:167], v[108:111], v[194:197], v[76:79]
	v_mfma_f32_16x16x32_bf16 v[182:185], v[214:217], v[194:197], v[72:75]
	s_barrier
	s_nop 0
	ds_read_b128 v[72:75], v132 offset:16384
	ds_read_b128 v[76:79], v133 offset:16384
	ds_read_b128 v[88:91], v134 offset:16384
	ds_read_b128 v[92:95], v135 offset:16384
	ds_read_b128 v[186:189], v136 offset:16384
	ds_read_b128 v[190:193], v137 offset:16384
	ds_read_b128 v[194:197], v138 offset:16384
	ds_read_b128 v[198:201], v139 offset:16384
	s_waitcnt vmcnt(4)
	s_barrier
	s_waitcnt lgkmcnt(0)
	v_mfma_f32_16x16x32_bf16 v[60:63], v[140:143], v[72:75], v[60:63]
	v_mfma_f32_16x16x32_bf16 v[56:59], v[152:155], v[72:75], v[56:59]
	v_mfma_f32_16x16x32_bf16 v[52:55], v[140:143], v[88:91], v[52:55]
	v_mfma_f32_16x16x32_bf16 v[48:51], v[152:155], v[88:91], v[48:51]
	v_mfma_f32_16x16x32_bf16 v[36:39], v[140:143], v[194:197], v[36:39]
	v_mfma_f32_16x16x32_bf16 v[32:35], v[152:155], v[194:197], v[32:35]
	v_mfma_f32_16x16x32_bf16 v[60:63], v[148:151], v[76:79], v[60:63]
	v_mfma_f32_16x16x32_bf16 v[56:59], v[156:159], v[76:79], v[56:59]
	v_mfma_f32_16x16x32_bf16 v[52:55], v[148:151], v[92:95], v[52:55]
	v_mfma_f32_16x16x32_bf16 v[48:51], v[156:159], v[92:95], v[48:51]
	v_mfma_f32_16x16x32_bf16 v[44:47], v[140:143], v[186:189], v[44:47]
	v_mfma_f32_16x16x32_bf16 v[40:43], v[152:155], v[186:189], v[40:43]
	v_mfma_f32_16x16x32_bf16 v[36:39], v[148:151], v[198:201], v[36:39]
	v_mfma_f32_16x16x32_bf16 v[32:35], v[156:159], v[198:201], v[32:35]
	v_mfma_f32_16x16x32_bf16 v[202:205], v[148:151], v[190:193], v[44:47]
	v_mfma_f32_16x16x32_bf16 v[222:225], v[156:159], v[190:193], v[40:43]
	v_mfma_f32_16x16x32_bf16 v[20:23], v[104:107], v[88:91], v[20:23]
	v_mfma_f32_16x16x32_bf16 v[16:19], v[168:171], v[88:91], v[16:19]
	v_mfma_f32_16x16x32_bf16 v[4:7], v[104:107], v[194:197], v[4:7]
	v_mfma_f32_16x16x32_bf16 v[0:3], v[168:171], v[194:197], v[0:3]
	v_mfma_f32_16x16x32_bf16 v[28:31], v[104:107], v[72:75], v[28:31]
	v_mfma_f32_16x16x32_bf16 v[24:27], v[168:171], v[72:75], v[24:27]
	v_mfma_f32_16x16x32_bf16 v[20:23], v[108:111], v[92:95], v[20:23]
	v_mfma_f32_16x16x32_bf16 v[16:19], v[214:217], v[92:95], v[16:19]
	v_mfma_f32_16x16x32_bf16 v[12:15], v[104:107], v[186:189], v[12:15]
	v_mfma_f32_16x16x32_bf16 v[8:11], v[168:171], v[186:189], v[8:11]
	v_mfma_f32_16x16x32_bf16 v[4:7], v[108:111], v[198:201], v[4:7]
	v_mfma_f32_16x16x32_bf16 v[0:3], v[214:217], v[198:201], v[0:3]
	v_mfma_f32_16x16x32_bf16 v[140:143], v[108:111], v[76:79], v[28:31]
	v_mfma_f32_16x16x32_bf16 v[148:151], v[214:217], v[76:79], v[24:27]
	v_mfma_f32_16x16x32_bf16 v[152:155], v[108:111], v[190:193], v[12:15]
	v_mfma_f32_16x16x32_bf16 v[156:159], v[214:217], v[190:193], v[8:11]
	s_barrier
; #define LDA(dst, b, h) for (int m = 0; m < 4; ++m) for (int k = 0; k < 2; ++k) \
;     dst[m][k] = *reinterpret_cast<const bf16x8*>((char*)SA(b, h) + lds_byte(wr * 64 + m * 16 + fr, k * 32 + fq * 8))
; #define LDB(dst, b, h) for (int n = 0; n < 2; ++n) for (int k = 0; k < 2; ++k) \
;     dst[n][k] = *reinterpret_cast<const bf16x8*>((char*)SB(b, h) + lds_byte(wc * 32 + n * 16 + fr, k * 32 + fq * 8))
; #define MMA(ai, bj, At_, Bt_) do { __builtin_amdgcn_s_setprio(1); \
;     for (int m = 0; m < 4; ++m) for (int n = 0; n < 2; ++n) for (int k = 0; k < 2; ++k) \
;       acc[ai][bj][m][n] = MFMA16(Bt_[n][k], At_[m][k], acc[ai][bj][m][n]); \
;     __builtin_amdgcn_s_setprio(0); } while (0)
; #define WAIT_V(n) asm volatile("s_waitcnt vmcnt(" #n ")" ::: "memory")
; #define WAIT_L(n) asm volatile("s_waitcnt lgkmcnt(" #n ")" ::: "memory")
; #define BAR __builtin_amdgcn_s_barrier()
; template <int PART  , bool SYNC_FIRST = true>
; __device__ __forceinline__ void kloop_t(const u16* __restrict__ A, int lda, const u16* __restrict__ Bt, int ldb, int K, Acc& acc, const int wv) {
;     ...
;   { LDB(B0, 1, 0); LDA(At, 1, 0); WAIT_V(2); BAR; WAIT_L(0); MMA(0, 0, At, B0); BAR;
;     LDB(B1, 1, 1); WAIT_V(0); BAR; WAIT_L(0); MMA(0, 1, At, B1); BAR;
;     LDA(At, 1, 1); BAR; WAIT_L(0); MMA(1, 0, At, B0); MMA(1, 1, At, B1); BAR; }
	s_nop 0
	ds_read_b128 v[8:11], v174
	ds_read_b128 v[12:15], v175
	ds_read_b128 v[168:171], v176
	ds_read_b128 v[172:175], v177
	ds_read_b128 v[24:27], v132 offset:32768
	ds_read_b128 v[28:31], v133 offset:32768
	ds_read_b128 v[40:43], v134 offset:32768
	ds_read_b128 v[44:47], v135 offset:32768
	ds_read_b128 v[186:189], v136 offset:32768
	ds_read_b128 v[190:193], v137 offset:32768
	ds_read_b128 v[194:197], v138 offset:32768
	ds_read_b128 v[198:201], v139 offset:32768
	s_waitcnt vmcnt(2)
	s_barrier
	s_waitcnt lgkmcnt(0)
	v_mfma_f32_16x16x32_bf16 v[72:75], v[8:11], v[24:27], v[124:127]
	v_mfma_f32_16x16x32_bf16 v[124:127], v[12:15], v[28:31], v[72:75]
	v_mfma_f32_16x16x32_bf16 v[72:75], v[168:171], v[24:27], v[120:123]
	v_mfma_f32_16x16x32_bf16 v[120:123], v[172:175], v[28:31], v[72:75]
	v_mfma_f32_16x16x32_bf16 v[72:75], v[8:11], v[40:43], v[116:119]
	v_mfma_f32_16x16x32_bf16 v[108:111], v[12:15], v[44:47], v[72:75]
	v_mfma_f32_16x16x32_bf16 v[72:75], v[168:171], v[40:43], v[112:115]
	v_mfma_f32_16x16x32_bf16 v[104:107], v[172:175], v[44:47], v[72:75]
	v_mfma_f32_16x16x32_bf16 v[72:75], v[8:11], v[186:189], v[206:209]
	v_mfma_f32_16x16x32_bf16 v[92:95], v[12:15], v[190:193], v[72:75]
	v_mfma_f32_16x16x32_bf16 v[72:75], v[168:171], v[186:189], v[210:213]
	v_mfma_f32_16x16x32_bf16 v[88:91], v[172:175], v[190:193], v[72:75]
	v_mfma_f32_16x16x32_bf16 v[72:75], v[8:11], v[194:197], v[100:103]
	v_mfma_f32_16x16x32_bf16 v[76:79], v[12:15], v[198:201], v[72:75]
	v_mfma_f32_16x16x32_bf16 v[72:75], v[168:171], v[194:197], v[96:99]
	v_mfma_f32_16x16x32_bf16 v[72:75], v[172:175], v[198:201], v[72:75]
	s_barrier
	ds_read_b128 v[206:209], v178
	ds_read_b128 v[176:179], v179
	ds_read_b128 v[210:213], v180
	ds_read_b128 v[214:217], v181
	s_waitcnt vmcnt(0)
	s_barrier
	s_waitcnt lgkmcnt(0)
	v_mfma_f32_16x16x32_bf16 v[96:99], v[206:209], v[24:27], v[218:221]
	v_mfma_f32_16x16x32_bf16 v[24:27], v[210:213], v[24:27], v[160:163]
	v_mfma_f32_16x16x32_bf16 v[112:115], v[214:217], v[28:31], v[24:27]
	v_mfma_f32_16x16x32_bf16 v[24:27], v[206:209], v[40:43], v[84:87]
	v_mfma_f32_16x16x32_bf16 v[100:103], v[176:179], v[44:47], v[24:27]
	v_mfma_f32_16x16x32_bf16 v[24:27], v[210:213], v[40:43], v[80:83]
	v_mfma_f32_16x16x32_bf16 v[116:119], v[176:179], v[28:31], v[96:99]
	v_mfma_f32_16x16x32_bf16 v[96:99], v[214:217], v[44:47], v[24:27]
	v_mfma_f32_16x16x32_bf16 v[24:27], v[206:209], v[186:189], v[164:167]
	v_mfma_f32_16x16x32_bf16 v[84:87], v[176:179], v[190:193], v[24:27]
	v_mfma_f32_16x16x32_bf16 v[24:27], v[210:213], v[186:189], v[182:185]
	v_mfma_f32_16x16x32_bf16 v[80:83], v[214:217], v[190:193], v[24:27]
	v_mfma_f32_16x16x32_bf16 v[24:27], v[206:209], v[194:197], v[68:71]
	v_mfma_f32_16x16x32_bf16 v[68:71], v[176:179], v[198:201], v[24:27]
	v_mfma_f32_16x16x32_bf16 v[24:27], v[210:213], v[194:197], v[64:67]
	v_mfma_f32_16x16x32_bf16 v[64:67], v[214:217], v[198:201], v[24:27]
	s_barrier
	ds_read_b128 v[160:163], v132 offset:49152
	ds_read_b128 v[130:133], v133 offset:49152
	ds_read_b128 v[164:167], v134 offset:49152
	ds_read_b128 v[180:183], v135 offset:49152
	ds_read_b128 v[184:187], v136 offset:49152
	ds_read_b128 v[134:137], v137 offset:49152
	ds_read_b128 v[188:191], v138 offset:49152
	ds_read_b128 v[192:195], v139 offset:49152
	s_barrier
	s_waitcnt lgkmcnt(0)
	v_mfma_f32_16x16x32_bf16 v[24:27], v[8:11], v[160:163], v[60:63]
	v_mfma_f32_16x16x32_bf16 v[60:63], v[12:15], v[130:133], v[24:27]
	v_mfma_f32_16x16x32_bf16 v[24:27], v[168:171], v[160:163], v[56:59]
	v_mfma_f32_16x16x32_bf16 v[56:59], v[172:175], v[130:133], v[24:27]
	v_mfma_f32_16x16x32_bf16 v[24:27], v[8:11], v[164:167], v[52:55]
	v_mfma_f32_16x16x32_bf16 v[44:47], v[12:15], v[180:183], v[24:27]
	v_mfma_f32_16x16x32_bf16 v[24:27], v[168:171], v[164:167], v[48:51]
	v_mfma_f32_16x16x32_bf16 v[40:43], v[172:175], v[180:183], v[24:27]
	v_mfma_f32_16x16x32_bf16 v[24:27], v[8:11], v[184:187], v[202:205]
	v_mfma_f32_16x16x32_bf16 v[8:11], v[8:11], v[188:191], v[36:39]
	v_mfma_f32_16x16x32_bf16 v[28:31], v[12:15], v[134:137], v[24:27]
	v_mfma_f32_16x16x32_bf16 v[24:27], v[168:171], v[184:187], v[222:225]
	v_mfma_f32_16x16x32_bf16 v[12:15], v[12:15], v[192:195], v[8:11]
	v_mfma_f32_16x16x32_bf16 v[8:11], v[168:171], v[188:191], v[32:35]
	v_mfma_f32_16x16x32_bf16 v[24:27], v[172:175], v[134:137], v[24:27]
	v_mfma_f32_16x16x32_bf16 v[8:11], v[172:175], v[192:195], v[8:11]
	v_mfma_f32_16x16x32_bf16 v[32:35], v[206:209], v[160:163], v[140:143]
	v_mfma_f32_16x16x32_bf16 v[52:55], v[176:179], v[130:133], v[32:35]
	v_mfma_f32_16x16x32_bf16 v[32:35], v[210:213], v[160:163], v[148:151]
	v_mfma_f32_16x16x32_bf16 v[16:19], v[210:213], v[164:167], v[16:19]
	v_mfma_f32_16x16x32_bf16 v[48:51], v[214:217], v[130:133], v[32:35]
	v_mfma_f32_16x16x32_bf16 v[20:23], v[206:209], v[164:167], v[20:23]
	v_mfma_f32_16x16x32_bf16 v[32:35], v[214:217], v[180:183], v[16:19]
	v_mfma_f32_16x16x32_bf16 v[16:19], v[206:209], v[184:187], v[152:155]
	v_mfma_f32_16x16x32_bf16 v[36:39], v[176:179], v[180:183], v[20:23]
	v_mfma_f32_16x16x32_bf16 v[20:23], v[176:179], v[134:137], v[16:19]
	v_mfma_f32_16x16x32_bf16 v[16:19], v[210:213], v[184:187], v[156:159]
	v_mfma_f32_16x16x32_bf16 v[4:7], v[206:209], v[188:191], v[4:7]
	v_mfma_f32_16x16x32_bf16 v[0:3], v[210:213], v[188:191], v[0:3]
	v_mfma_f32_16x16x32_bf16 v[16:19], v[214:217], v[134:137], v[16:19]
	v_mfma_f32_16x16x32_bf16 v[4:7], v[176:179], v[192:195], v[4:7]
	v_mfma_f32_16x16x32_bf16 v[0:3], v[214:217], v[192:195], v[0:3]
	s_andn2_b64 vcc, exec, s[12:13]
	s_barrier
	s_cbranch_vccnz .LBB0_321
	s_barrier

; __device__ __forceinline__ int lane_fresh() { int l; asm volatile("v_mbcnt_lo_u32_b32 %0, -1, 0\n\tv_mbcnt_hi_u32_b32 %0, -1, %0" : "=v"(l)); return l; }
; #define WAIT_V(n) asm volatile("s_waitcnt vmcnt(" #n ")" ::: "memory")
; #define WAIT_L(n) asm volatile("s_waitcnt lgkmcnt(" #n ")" ::: "memory")
; template <int PART  , bool SYNC_FIRST = true>
; __device__ __forceinline__ void kloop_t(const u16* __restrict__ A, int lda, const u16* __restrict__ Bt, int ldb, int K, Acc& acc, const int wv) {
;     ...
;   const int wid = wv, lane = lane_fresh(), ktid = wv * 64 + lane, wr = wid >> 2, wc = wid & 3, fr = lane & 15, fq = lane >> 4;
;   bf16x8 At[4][2], B0[2][2], B1[2][2];
;   const int nt = K / BK;
;   unsigned oA0, oA1, oB0, oB1;
;   { int r_, c_; stage_rc(ktid * 16, r_, c_); oA0 = (unsigned)(r_ * lda + c_) * 2u; oB0 = (unsigned)(r_ * ldb + c_) * 2u;
;     stage_rc(ktid * 16 + 8192, r_, c_); oA1 = (unsigned)(r_ * lda + c_) * 2u; oB1 = (unsigned)(r_ * ldb + c_) * 2u; }
;   if (PART != 2) {
;     if (SYNC_FIRST) { WAIT_V(0); WAIT_L(0); __syncthreads(); }
; __device__ __forceinline__ void phaseD(const Params& p, const int wv, const int rep) {
;     ...
;     __syncthreads();
;     {
;       const int tid = wv * 64 + lane_fresh();
;       const int r = tid >> 1, gg = tid & 1;
;       const float* ps = YPS + (size_t)(brow + r) * 32 + gg * 16;
;       f32x4 a = *(const f32x4*)ps + *(const f32x4*)(ps + 4) + *(const f32x4*)(ps + 8) + *(const f32x4*)(ps + 12);
;       rs_l[r * 2 + gg] = rsqrtf((a[0] + a[1] + a[2] + a[3]) * (1.f / 512.f) + EPS);
;     }
.LBB0_690:
	s_lshl_b32 s0, s89, 8
	s_and_b32 s90, s0, 0x3f00
	v_readlane_b32 s0, v250, 0
	s_barrier
	v_mbcnt_lo_u32_b32 v0, -1, 0
	v_mbcnt_hi_u32_b32 v0, -1, v0
	v_readlane_b32 s1, v250, 1
	v_add_u32_e32 v18, s0, v0
	v_ashrrev_i32_e32 v2, 1, v18
	v_add_u32_e32 v2, s90, v2
	v_ashrrev_i32_e32 v3, 31, v2
	v_readlane_b32 s0, v251, 4
	v_lshlrev_b64 v[2:3], 7, v[2:3]
	v_readlane_b32 s1, v251, 5
	v_lshlrev_b32_e32 v0, 6, v0
	v_and_b32_e32 v0, 64, v0
	v_lshl_add_u64 v[2:3], s[0:1], 0, v[2:3]
	v_lshl_add_u64 v[14:15], v[2:3], 0, v[0:1]
	global_load_dwordx4 v[200:203], v[14:15], off
	global_load_dwordx4 v[204:207], v[14:15], off offset:16
	global_load_dwordx4 v[208:211], v[14:15], off offset:32
	s_nop 0
	global_load_dwordx4 v[212:215], v[14:15], off offset:48
	s_mov_b32 s5, 0x800000
	v_lshl_add_u32 v216, v18, 2, 16
	v_add_u32_e32 v216, 0x20000, v216
	s_lshl_b32 s0, s89, 2
	s_and_b32 s0, s0, 0x300
	s_lshl_b32 s1, s90, 10
	s_add_u32 s28, s66, s1
	s_addc_u32 s29, s67, 0
	s_lshl_b32 s4, s0, 10
	s_add_u32 s30, s70, s4
	s_addc_u32 s31, s71, 0
	s_add_u32 s6, s30, 0x20000
	s_addc_u32 s7, s31, 0
	s_mov_b32 s33, s19
	v_mbcnt_lo_u32_b32 v0, -1, 0
	v_mbcnt_hi_u32_b32 v0, -1, v0
	s_waitcnt lgkmcnt(0)
	v_lshl_add_u32 v0, v0, 4, s76
	v_ashrrev_i32_e32 v2, 31, v0
	v_add_u32_e32 v3, 0x2000, v0
	v_add_u32_e32 v4, s94, v0
	v_lshrrev_b32_e32 v2, 22, v2
	v_ashrrev_i32_e32 v6, 31, v3
	v_readfirstlane_b32 s5, v4
	v_add_u32_e32 v4, 0x2000, v4
	v_add_u32_e32 v2, v0, v2
	v_lshrrev_b32_e32 v6, 22, v6
	v_readfirstlane_b32 s9, v4
	v_ashrrev_i32_e32 v2, 10, v2
	v_add_u32_e32 v4, v3, v6
	v_mul_i32_i24_e32 v6, 0x400, v2
	v_ashrrev_i32_e32 v4, 10, v4
	v_sub_u32_e32 v6, v0, v6
	v_mul_i32_i24_e32 v8, 0x400, v4
	v_lshlrev_b32_e32 v9, 3, v4
	v_lshrrev_b32_e32 v10, 4, v6
	v_sub_u32_e32 v3, v3, v8
	v_and_b32_e32 v8, 0x3ffff0, v9
	v_bitop3_b32 v6, v10, v6, 32 bitop3:0x6c
	v_lshrrev_b32_e32 v9, 4, v3
	v_ashrrev_i32_e32 v10, 31, v6
	v_bitop3_b32 v3, v9, v3, 32 bitop3:0x6c
	v_lshrrev_b32_e32 v9, 26, v10
	v_ashrrev_i32_e32 v10, 31, v3
	v_add_u32_e32 v5, 16, v0
	v_add_u32_e32 v9, v6, v9
	v_lshrrev_b32_e32 v10, 26, v10
	v_add_u32_e32 v7, 0x2000, v5
	v_lshrrev_b32_e32 v11, 6, v9
	v_and_b32_e32 v9, 0xc0, v9
	v_add_u32_e32 v10, v3, v10
	v_readfirstlane_b32 s18, v7
	v_lshlrev_b32_e32 v7, 3, v2
	v_lshlrev_b32_e32 v2, 5, v2
	v_sub_u32_e32 v6, v6, v9
	v_lshrrev_b32_e32 v9, 6, v10
	v_and_b32_e32 v10, 0xffc0, v10
	v_and_b32_e32 v2, 32, v2
	v_ashrrev_i16_sdwa v6, v187, sext(v6) dst_sel:DWORD dst_unused:UNUSED_PAD src0_sel:DWORD src1_sel:BYTE_0
	v_sub_u32_e32 v3, v3, v10
	v_add_u32_sdwa v2, v2, sext(v6) dst_sel:DWORD dst_unused:UNUSED_PAD src0_sel:DWORD src1_sel:WORD_0
	v_lshrrev_b16_e32 v6, 7, v3
	v_and_b32_e32 v6, 1, v6
	v_lshlrev_b32_e32 v4, 5, v4
	v_add_u16_e32 v3, v3, v6
	v_and_b32_e32 v7, 0x3ffff0, v7
	v_and_b32_e32 v4, 32, v4
	v_ashrrev_i16_sdwa v3, v187, sext(v3) dst_sel:DWORD dst_unused:UNUSED_PAD src0_sel:DWORD src1_sel:BYTE_0
	v_add_lshl_u32 v7, v11, v7, 10
	v_add_lshl_u32 v8, v9, v8, 10
	v_add_u32_sdwa v3, v4, sext(v3) dst_sel:DWORD dst_unused:UNUSED_PAD src0_sel:DWORD src1_sel:WORD_0
	v_lshl_add_u32 v2, v2, 1, v7
	v_lshl_add_u32 v3, v3, 1, v8
	v_mov_b32_e32 v6, v2
	v_mov_b32_e32 v4, v3
	s_mov_b32 m0, s5
	s_barrier
; #define ACC_ZERO(acc) do { _Pragma("unroll") for (int ai = 0; ai < 2; ++ai) _Pragma("unroll") for (int bj = 0; bj < 2; ++bj) \
;   _Pragma("unroll") for (int m = 0; m < 4; ++m) _Pragma("unroll") for (int n = 0; n < 2; ++n) acc[ai][bj][m][n] = (f32x4){0.f, 0.f, 0.f, 0.f}; } while (0)
; template <int PART  , bool SYNC_FIRST = true>
; __device__ __forceinline__ void kloop_t(const u16* __restrict__ A, int lda, const u16* __restrict__ Bt, int ldb, int K, Acc& acc, const int wv) {
;     ...
;     STAGE(SB(0, 0), Bt, ldb, 0, 0); STAGE(SA(0, 0), A, lda, 0, 0);
;     STAGE(SB(0, 1), Bt, ldb, HALF, 0); STAGE(SA(0, 1), A, lda, HALF, 0);
; __device__ __forceinline__ void phaseD(const Params& p, const int wv, const int rep) {
;     ...
;       f32x4 a = *(const f32x4*)ps + *(const f32x4*)(ps + 4) + *(const f32x4*)(ps + 8) + *(const f32x4*)(ps + 12);
;       rs_l[r * 2 + gg] = rsqrtf((a[0] + a[1] + a[2] + a[3]) * (1.f / 512.f) + EPS);
;     }
;     auto opnd = [&](int br, const u16*& Ap, const u16*& Bp, int& ld) {
;       if (br == 0) { Ap = GM + (size_t)brow * 512; Bp = WGM + (size_t)bcol * 512; ld = 512; }
;       else if (br == 1) { Ap = Y + (size_t)brow * 1024; Bp = WSSD + (size_t)bcol * 1024; ld = 1024; }
;       else if (br == 2) { Ap = Y + (size_t)brow * 1024 + 512; Bp = WSSD + (size_t)bcol * 1024 + 512; ld = 1024; }
;       else { Ap = XA + (size_t)brow * 512; Bp = WXA + (size_t)bcol * 512; ld = 512; }
;     };
;     Acc acc; ACC_ZERO(acc);
;     { const u16 *Ap, *Bp; int ld; opnd(0, Ap, Bp, ld); kloop_t<1, true>(Ap, ld, Bp, ld, 512, acc, wv); }
	v_readfirstlane_b32 s8, v5
	v_mov_b32_e32 v7, v2
	global_load_lds_dwordx4 v6, s[30:31]
	s_mov_b32 m0, s9
	v_mov_b32_e32 v8, v3
	global_load_lds_dwordx4 v4, s[30:31]
	s_mov_b32 m0, s8
	v_add_u32_e32 v0, s95, v0
	v_mov_b32_e32 v9, v2
	global_load_lds_dwordx4 v7, s[28:29]
	s_mov_b32 m0, s18
	v_readfirstlane_b32 s5, v0
	v_add_u32_e32 v0, 0x2000, v0
	v_mov_b32_e32 v10, v3
	global_load_lds_dwordx4 v8, s[28:29]
	s_mov_b32 m0, s5
	v_readfirstlane_b32 s5, v0
	v_add_u32_e32 v0, 0x4000, v5
	global_load_lds_dwordx4 v9, s[6:7]
	s_mov_b32 m0, s5
	v_readfirstlane_b32 s5, v0
	global_load_lds_dwordx4 v10, s[6:7]
	s_add_u32 s6, s28, 0x20000
	v_add_u32_e32 v0, 0x6000, v5
	s_addc_u32 s7, s29, 0
	s_mov_b32 m0, s5
	v_readfirstlane_b32 s5, v0
	v_mov_b32_e32 v0, v1
	global_load_lds_dwordx4 v2, s[6:7]
	s_mov_b32 m0, s5
	s_lshl_b32 s5, s90, 11
	global_load_lds_dwordx4 v3, s[6:7]
	s_waitcnt vmcnt(10)
	v_pk_add_f32 v[200:201], v[200:201], v[204:205]
	v_pk_add_f32 v[202:203], v[202:203], v[206:207]
	s_waitcnt vmcnt(9)
	v_pk_add_f32 v[200:201], v[200:201], v[208:209]
	v_pk_add_f32 v[202:203], v[202:203], v[210:211]
	s_waitcnt vmcnt(8)
	v_pk_add_f32 v[200:201], v[200:201], v[212:213]
	v_pk_add_f32 v[202:203], v[202:203], v[214:215]
	v_add_f32_e32 v200, v200, v201
	v_add_f32_e32 v200, v202, v200
	v_add_f32_e32 v200, v203, v200
	v_fmamk_f32 v200, v200, 0x3b000000, v186
	v_mul_f32_e32 v201, 0x4b800000, v200
	v_cmp_gt_f32_e32 vcc, 0x800000, v200
	s_nop 1
	v_cndmask_b32_e32 v200, v200, v201, vcc
	v_rsq_f32_e32 v200, v200
	s_nop 0
	v_mul_f32_e32 v201, 0x45800000, v200
	v_cndmask_b32_e32 v200, v200, v201, vcc
	ds_write_b32 v216, v200
	s_add_u32 s34, s48, s5
	s_addc_u32 s35, s49, 0
	s_add_u32 s36, s34, 0x400
	s_addc_u32 s37, s35, 0
	s_lshl_b32 s5, s0, 11
	s_add_u32 s38, s72, s5
	s_addc_u32 s39, s73, 0
	s_add_u32 s40, s38, 0x400
	s_addc_u32 s41, s39, 0
	s_add_u32 s42, s68, s1
	s_addc_u32 s43, s69, 0
	s_add_u32 s44, s74, s4
	s_addc_u32 s45, s75, 0
	s_add_i32 s91, s90, s87
	s_lshl_b32 s0, s0, 1
	v_readlane_b32 s1, v250, 29
	s_add_u32 s52, s1, s0
	v_readlane_b32 s1, v250, 31
	v_mov_b32_e32 v2, v1
	v_mov_b32_e32 v3, v1
	s_addc_u32 s53, s1, 0
	v_readlane_b32 s1, v250, 33
	v_mov_b64_e32 v[20:21], v[2:3]
	v_mov_b64_e32 v[24:25], v[2:3]
	v_mov_b64_e32 v[52:53], v[2:3]
	v_mov_b64_e32 v[56:57], v[2:3]
	v_mov_b64_e32 v[68:69], v[2:3]
	v_mov_b64_e32 v[76:77], v[2:3]
	v_mov_b64_e32 v[12:13], v[2:3]
	v_mov_b64_e32 v[16:17], v[2:3]
	v_mov_b64_e32 v[28:29], v[2:3]
	v_mov_b64_e32 v[36:37], v[2:3]
	v_mov_b64_e32 v[60:61], v[2:3]
	v_mov_b64_e32 v[64:65], v[2:3]
	v_mov_b64_e32 v[88:89], v[2:3]
	v_mov_b64_e32 v[96:97], v[2:3]
	v_mov_b64_e32 v[100:101], v[2:3]
	v_mov_b64_e32 v[104:105], v[2:3]
	v_mov_b64_e32 v[128:129], v[2:3]
	v_mov_b64_e32 v[120:121], v[2:3]
	v_mov_b64_e32 v[92:93], v[2:3]
	v_mov_b64_e32 v[84:85], v[2:3]
	v_mov_b64_e32 v[48:49], v[2:3]
	v_mov_b64_e32 v[44:45], v[2:3]
	v_mov_b64_e32 v[112:113], v[2:3]
	v_mov_b64_e32 v[124:125], v[2:3]
	v_mov_b64_e32 v[116:117], v[2:3]
	v_mov_b64_e32 v[108:109], v[2:3]
	v_mov_b64_e32 v[80:81], v[2:3]
	v_mov_b64_e32 v[72:73], v[2:3]
	v_mov_b64_e32 v[40:41], v[2:3]
	v_mov_b64_e32 v[32:33], v[2:3]
	v_mov_b64_e32 v[8:9], v[2:3]
	s_add_u32 s54, s1, s0
	v_readlane_b32 s0, v250, 35
	v_mov_b64_e32 v[18:19], v[0:1]
	v_mov_b64_e32 v[22:23], v[0:1]
	v_mov_b64_e32 v[50:51], v[0:1]
	v_mov_b64_e32 v[54:55], v[0:1]
	v_mov_b64_e32 v[66:67], v[0:1]
	v_mov_b64_e32 v[74:75], v[0:1]
	v_mov_b64_e32 v[10:11], v[0:1]
	v_mov_b64_e32 v[14:15], v[0:1]
	v_mov_b64_e32 v[26:27], v[0:1]
	v_mov_b64_e32 v[34:35], v[0:1]
	v_mov_b64_e32 v[58:59], v[0:1]
	v_mov_b64_e32 v[62:63], v[0:1]
	v_mov_b64_e32 v[86:87], v[0:1]
	v_mov_b64_e32 v[94:95], v[0:1]
	v_mov_b64_e32 v[98:99], v[0:1]
	v_mov_b64_e32 v[102:103], v[0:1]
	v_mov_b64_e32 v[126:127], v[0:1]
	v_mov_b64_e32 v[118:119], v[0:1]
	v_mov_b64_e32 v[90:91], v[0:1]
	v_mov_b64_e32 v[82:83], v[0:1]
	v_mov_b64_e32 v[46:47], v[0:1]
	v_mov_b64_e32 v[42:43], v[0:1]
	v_mov_b64_e32 v[110:111], v[0:1]
	v_mov_b64_e32 v[122:123], v[0:1]
	v_mov_b64_e32 v[114:115], v[0:1]
	v_mov_b64_e32 v[106:107], v[0:1]
	v_mov_b64_e32 v[78:79], v[0:1]
	v_mov_b64_e32 v[70:71], v[0:1]
	v_mov_b64_e32 v[38:39], v[0:1]
	v_mov_b64_e32 v[30:31], v[0:1]
	v_mov_b64_e32 v[6:7], v[0:1]
	v_mov_b64_e32 v[4:5], v[2:3]
	s_addc_u32 s55, s0, 0
	v_mov_b64_e32 v[2:3], v[0:1]
	s_branch .LBB0_692

; #define LDA(dst, b, h) for (int m = 0; m < 4; ++m) for (int k = 0; k < 2; ++k) \
;     dst[m][k] = *reinterpret_cast<const bf16x8*>((char*)SA(b, h) + lds_byte(wr * 64 + m * 16 + fr, k * 32 + fq * 8))
; #define LDB(dst, b, h) for (int n = 0; n < 2; ++n) for (int k = 0; k < 2; ++k) \
;     dst[n][k] = *reinterpret_cast<const bf16x8*>((char*)SB(b, h) + lds_byte(wc * 32 + n * 16 + fr, k * 32 + fq * 8))
; #define MMA(ai, bj, At_, Bt_) do { __builtin_amdgcn_s_setprio(1); \
;     for (int m = 0; m < 4; ++m) for (int n = 0; n < 2; ++n) for (int k = 0; k < 2; ++k) \
;       acc[ai][bj][m][n] = MFMA16(Bt_[n][k], At_[m][k], acc[ai][bj][m][n]); \
;     __builtin_amdgcn_s_setprio(0); } while (0)
; #define WAIT_L(n) asm volatile("s_waitcnt lgkmcnt(" #n ")" ::: "memory")
; #define BAR __builtin_amdgcn_s_barrier()
; #define SCHED __builtin_amdgcn_sched_barrier(0)
; template <int PART  , bool SYNC_FIRST = true>
; __device__ __forceinline__ void kloop_t(const u16* __restrict__ A, int lda, const u16* __restrict__ Bt, int ldb, int K, Acc& acc, const int wv) {
;     ...
;     LDB(B0, 0, 0); SCHED; LDA(At, 0, 0); STAGE(SA(1, 1), A, lda, HALF, t + 1);
;     WAIT_L(8); BAR; WAIT_L(0); MMA(0, 0, At, B0); BAR; SCHED;
;     LDB(B1, 0, 1); STAGE(SB(0, 0), Bt, ldb, 0, t + 2);
;     BAR; WAIT_L(0); MMA(0, 1, At, B1); BAR;
;     LDA(At, 0, 1); STAGE(SA(0, 0), A, lda, 0, t + 2);
.LBB0_704:
	v_add_u32_e32 v156, v148, v152
	v_add_u32_e32 v158, v148, v154
	v_add_u32_e32 v157, v148, v153
	ds_read_b128 v[166:169], v156
	ds_read_b128 v[170:173], v157
	v_add_u32_e32 v159, v148, v155
	ds_read_b128 v[174:177], v158
	ds_read_b128 v[178:181], v159
	s_add_u32 s58, s18, s56
	v_mov_b32_e32 v0, v130
	v_mov_b32_e32 v162, v132
	s_addc_u32 s59, vcc_lo, s57
	ds_read_b128 v[182:185], v134
	ds_read_b128 v[188:191], v135
	ds_read_b128 v[192:195], v136
	ds_read_b128 v[196:199], v137
	ds_read_b128 v[200:203], v138
	ds_read_b128 v[204:207], v139
	ds_read_b128 v[208:211], v140
	ds_read_b128 v[212:215], v141
	v_mov_b32_e32 v163, v1
	v_lshl_add_u64 v[160:161], s[58:59], 0, v[0:1]
	v_lshl_add_u64 v[164:165], v[160:161], 0, s[20:21]
	v_add_u32_e32 v160, 0xc000, v143
	v_add_u32_e32 v161, 0xe000, v143
	v_readfirstlane_b32 s60, v160
	s_mov_b32 m0, s60
	v_lshl_add_u64 v[162:163], s[58:59], 0, v[162:163]
	v_readfirstlane_b32 s60, v161
	global_load_lds_dwordx4 v[164:165], off
	v_lshl_add_u64 v[162:163], v[162:163], 0, s[20:21]
	s_mov_b32 m0, s60
	s_nop 0
	global_load_lds_dwordx4 v[162:163], off
	s_waitcnt lgkmcnt(8)
	s_barrier
	s_waitcnt lgkmcnt(0)
	v_mfma_f32_16x16x32_bf16 v[30:33], v[166:169], v[182:185], v[30:33]
	v_mfma_f32_16x16x32_bf16 v[38:41], v[174:177], v[182:185], v[38:41]
	v_mfma_f32_16x16x32_bf16 v[70:73], v[166:169], v[192:195], v[70:73]
	v_mfma_f32_16x16x32_bf16 v[78:81], v[174:177], v[192:195], v[78:81]
	v_mfma_f32_16x16x32_bf16 v[106:109], v[166:169], v[200:203], v[106:109]
	v_mfma_f32_16x16x32_bf16 v[114:117], v[174:177], v[200:203], v[114:117]
	v_mfma_f32_16x16x32_bf16 v[122:125], v[166:169], v[208:211], v[122:125]
	v_mfma_f32_16x16x32_bf16 v[110:113], v[174:177], v[208:211], v[110:113]
	v_mfma_f32_16x16x32_bf16 v[30:33], v[170:173], v[188:191], v[30:33]
	v_mfma_f32_16x16x32_bf16 v[38:41], v[178:181], v[188:191], v[38:41]
	v_mfma_f32_16x16x32_bf16 v[70:73], v[170:173], v[196:199], v[70:73]
	v_mfma_f32_16x16x32_bf16 v[78:81], v[178:181], v[196:199], v[78:81]
	v_mfma_f32_16x16x32_bf16 v[106:109], v[170:173], v[204:207], v[106:109]
	v_mfma_f32_16x16x32_bf16 v[114:117], v[178:181], v[204:207], v[114:117]
	v_mfma_f32_16x16x32_bf16 v[122:125], v[170:173], v[212:215], v[122:125]
	v_mfma_f32_16x16x32_bf16 v[110:113], v[178:181], v[212:215], v[110:113]
	s_barrier
	v_add_u32_e32 v162, v149, v152
	v_add_u32_e32 v164, v149, v154
	v_mov_b32_e32 v0, v130
	v_mov_b32_e32 v232, v132
	s_add_u32 s60, s4, s56
	v_add_u32_e32 v163, v149, v153
	ds_read_b128 v[216:219], v162
	ds_read_b128 v[220:223], v163
	v_add_u32_e32 v165, v149, v155
	ds_read_b128 v[224:227], v164
	ds_read_b128 v[228:231], v165
	s_addc_u32 s61, s5, s57
	v_lshl_add_u64 v[234:235], s[60:61], 0, v[0:1]
	v_add_u32_e32 v0, s94, v131
	v_mov_b32_e32 v233, v1
	v_readfirstlane_b32 s62, v0
	v_add_u32_e32 v0, 0x2000, v0
	v_lshl_add_u64 v[234:235], v[234:235], 0, s[22:23]
	s_mov_b32 m0, s62
	v_lshl_add_u64 v[232:233], s[60:61], 0, v[232:233]
	v_readfirstlane_b32 s62, v0
	global_load_lds_dwordx4 v[234:235], off
	v_lshl_add_u64 v[232:233], v[232:233], 0, s[22:23]
	s_mov_b32 m0, s62
	s_nop 0
	global_load_lds_dwordx4 v[232:233], off
	s_barrier
	s_waitcnt lgkmcnt(0)
	v_mfma_f32_16x16x32_bf16 v[42:45], v[216:219], v[182:185], v[42:45]
	v_mfma_f32_16x16x32_bf16 v[46:49], v[224:227], v[182:185], v[46:49]
	v_mfma_f32_16x16x32_bf16 v[82:85], v[216:219], v[192:195], v[82:85]
	v_mfma_f32_16x16x32_bf16 v[90:93], v[224:227], v[192:195], v[90:93]
	v_mfma_f32_16x16x32_bf16 v[118:121], v[216:219], v[200:203], v[118:121]
	v_mfma_f32_16x16x32_bf16 v[126:129], v[224:227], v[200:203], v[126:129]
	v_mfma_f32_16x16x32_bf16 v[102:105], v[216:219], v[208:211], v[102:105]
	v_mfma_f32_16x16x32_bf16 v[98:101], v[224:227], v[208:211], v[98:101]
	v_mfma_f32_16x16x32_bf16 v[42:45], v[220:223], v[188:191], v[42:45]
	v_mfma_f32_16x16x32_bf16 v[46:49], v[228:231], v[188:191], v[46:49]
	v_mfma_f32_16x16x32_bf16 v[82:85], v[220:223], v[196:199], v[82:85]
	v_mfma_f32_16x16x32_bf16 v[90:93], v[228:231], v[196:199], v[90:93]
	v_mfma_f32_16x16x32_bf16 v[118:121], v[220:223], v[204:207], v[118:121]
	v_mfma_f32_16x16x32_bf16 v[126:129], v[228:231], v[204:207], v[126:129]
	v_mfma_f32_16x16x32_bf16 v[102:105], v[220:223], v[212:215], v[102:105]
	v_mfma_f32_16x16x32_bf16 v[98:101], v[228:231], v[212:215], v[98:101]
	v_mov_b32_e32 v0, v130
	v_mov_b32_e32 v232, v132
	s_add_u32 s62, s0, s56
	s_barrier
	ds_read_b128 v[182:185], v134 offset:16384
	ds_read_b128 v[188:191], v135 offset:16384
	ds_read_b128 v[192:195], v136 offset:16384
	ds_read_b128 v[196:199], v137 offset:16384
	ds_read_b128 v[200:203], v138 offset:16384
	ds_read_b128 v[204:207], v139 offset:16384
	ds_read_b128 v[208:211], v140 offset:16384
	ds_read_b128 v[212:215], v141 offset:16384
	s_addc_u32 s63, s1, s57
	v_lshl_add_u64 v[234:235], s[62:63], 0, v[0:1]
	v_readfirstlane_b32 s64, v143
	v_mov_b32_e32 v233, v1
	v_add_u32_e32 v0, 0x2000, v143
	v_lshl_add_u64 v[234:235], v[234:235], 0, s[22:23]
	s_mov_b32 m0, s64
	v_lshl_add_u64 v[232:233], s[62:63], 0, v[232:233]
	v_readfirstlane_b32 s64, v0
	global_load_lds_dwordx4 v[234:235], off
	v_lshl_add_u64 v[232:233], v[232:233], 0, s[22:23]
	s_mov_b32 m0, s64
	s_nop 0
	global_load_lds_dwordx4 v[232:233], off
	s_barrier
; #define LDA(dst, b, h) for (int m = 0; m < 4; ++m) for (int k = 0; k < 2; ++k) \
;     dst[m][k] = *reinterpret_cast<const bf16x8*>((char*)SA(b, h) + lds_byte(wr * 64 + m * 16 + fr, k * 32 + fq * 8))
; #define LDB(dst, b, h) for (int n = 0; n < 2; ++n) for (int k = 0; k < 2; ++k) \
;     dst[n][k] = *reinterpret_cast<const bf16x8*>((char*)SB(b, h) + lds_byte(wc * 32 + n * 16 + fr, k * 32 + fq * 8))
; #define MMA(ai, bj, At_, Bt_) do { __builtin_amdgcn_s_setprio(1); \
;     for (int m = 0; m < 4; ++m) for (int n = 0; n < 2; ++n) for (int k = 0; k < 2; ++k) \
;       acc[ai][bj][m][n] = MFMA16(Bt_[n][k], At_[m][k], acc[ai][bj][m][n]); \
;     __builtin_amdgcn_s_setprio(0); } while (0)
; #define WAIT_V(n) asm volatile("s_waitcnt vmcnt(" #n ")" ::: "memory")
; #define WAIT_L(n) asm volatile("s_waitcnt lgkmcnt(" #n ")" ::: "memory")
; #define BAR __builtin_amdgcn_s_barrier()
; #define SCHED __builtin_amdgcn_sched_barrier(0)
; template <int PART  , bool SYNC_FIRST = true>
; __device__ __forceinline__ void kloop_t(const u16* __restrict__ A, int lda, const u16* __restrict__ Bt, int ldb, int K, Acc& acc, const int wv) {
;     ...
;     BAR; WAIT_L(0); MMA(1, 0, At, B0); BAR; SCHED;
;     STAGE(SB(0, 1), Bt, ldb, HALF, t + 2);
;     WAIT_V(6); BAR; MMA(1, 1, At, B1); BAR;
;     LDB(B0, 1, 0); SCHED; LDA(At, 1, 0); STAGE(SA(0, 1), A, lda, HALF, t + 2);
;     WAIT_L(8); BAR; WAIT_L(0); MMA(0, 0, At, B0); BAR; SCHED;
;     LDB(B1, 1, 1); STAGE(SB(1, 0), Bt, ldb, 0, t + 3);
;     BAR; WAIT_L(0); MMA(0, 1, At, B1); BAR;
	s_waitcnt lgkmcnt(0)
	v_mfma_f32_16x16x32_bf16 v[94:97], v[166:169], v[182:185], v[94:97]
	v_mfma_f32_16x16x32_bf16 v[86:89], v[174:177], v[182:185], v[86:89]
	v_mfma_f32_16x16x32_bf16 v[62:65], v[166:169], v[192:195], v[62:65]
	v_mfma_f32_16x16x32_bf16 v[58:61], v[174:177], v[192:195], v[58:61]
	v_mfma_f32_16x16x32_bf16 v[34:37], v[166:169], v[200:203], v[34:37]
	v_mfma_f32_16x16x32_bf16 v[26:29], v[174:177], v[200:203], v[26:29]
	v_mfma_f32_16x16x32_bf16 v[14:17], v[166:169], v[208:211], v[14:17]
	v_mfma_f32_16x16x32_bf16 v[10:13], v[174:177], v[208:211], v[10:13]
	v_mfma_f32_16x16x32_bf16 v[94:97], v[170:173], v[188:191], v[94:97]
	v_mfma_f32_16x16x32_bf16 v[86:89], v[178:181], v[188:191], v[86:89]
	v_mfma_f32_16x16x32_bf16 v[62:65], v[170:173], v[196:199], v[62:65]
	v_mfma_f32_16x16x32_bf16 v[58:61], v[178:181], v[196:199], v[58:61]
	v_mfma_f32_16x16x32_bf16 v[34:37], v[170:173], v[204:207], v[34:37]
	v_mfma_f32_16x16x32_bf16 v[26:29], v[178:181], v[204:207], v[26:29]
	v_mfma_f32_16x16x32_bf16 v[14:17], v[170:173], v[212:215], v[14:17]
	v_mfma_f32_16x16x32_bf16 v[10:13], v[178:181], v[212:215], v[10:13]
	s_barrier
	v_mov_b32_e32 v0, v130
	v_mov_b32_e32 v166, v132
	s_add_u32 s64, s8, s56
	s_addc_u32 s65, s9, s57
	v_lshl_add_u64 v[168:169], s[64:65], 0, v[0:1]
	v_add_u32_e32 v0, s95, v131
	v_mov_b32_e32 v167, v1
	v_readfirstlane_b32 s12, v0
	v_add_u32_e32 v0, 0x2000, v0
	v_lshl_add_u64 v[168:169], v[168:169], 0, s[22:23]
	s_mov_b32 m0, s12
	v_lshl_add_u64 v[166:167], s[64:65], 0, v[166:167]
	v_readfirstlane_b32 s12, v0
	global_load_lds_dwordx4 v[168:169], off
	v_lshl_add_u64 v[166:167], v[166:167], 0, s[22:23]
	s_mov_b32 m0, s12
	s_nop 0
	global_load_lds_dwordx4 v[166:167], off
	s_waitcnt vmcnt(6)
	s_barrier
	v_mfma_f32_16x16x32_bf16 v[74:77], v[216:219], v[182:185], v[74:77]
	v_mfma_f32_16x16x32_bf16 v[66:69], v[224:227], v[182:185], v[66:69]
	v_mfma_f32_16x16x32_bf16 v[54:57], v[216:219], v[192:195], v[54:57]
	v_mfma_f32_16x16x32_bf16 v[50:53], v[224:227], v[192:195], v[50:53]
	v_mfma_f32_16x16x32_bf16 v[22:25], v[216:219], v[200:203], v[22:25]
	v_mfma_f32_16x16x32_bf16 v[18:21], v[224:227], v[200:203], v[18:21]
	v_mfma_f32_16x16x32_bf16 v[6:9], v[216:219], v[208:211], v[6:9]
	v_mfma_f32_16x16x32_bf16 v[2:5], v[224:227], v[208:211], v[2:5]
	v_mfma_f32_16x16x32_bf16 v[74:77], v[220:223], v[188:191], v[74:77]
	v_mfma_f32_16x16x32_bf16 v[66:69], v[228:231], v[188:191], v[66:69]
	v_mfma_f32_16x16x32_bf16 v[54:57], v[220:223], v[196:199], v[54:57]
	v_mfma_f32_16x16x32_bf16 v[50:53], v[228:231], v[196:199], v[50:53]
	v_mfma_f32_16x16x32_bf16 v[22:25], v[220:223], v[204:207], v[22:25]
	v_mfma_f32_16x16x32_bf16 v[18:21], v[228:231], v[204:207], v[18:21]
	v_mfma_f32_16x16x32_bf16 v[6:9], v[220:223], v[212:215], v[6:9]
	v_mfma_f32_16x16x32_bf16 v[2:5], v[228:231], v[212:215], v[2:5]
	v_add_u32_e32 v166, v150, v152
	v_add_u32_e32 v168, v150, v154
	s_barrier
	v_add_u32_e32 v167, v150, v153
	ds_read_b128 v[174:177], v166
	ds_read_b128 v[178:181], v167
	v_add_u32_e32 v169, v150, v155
	ds_read_b128 v[182:185], v168
	ds_read_b128 v[188:191], v169
	v_mov_b32_e32 v0, v130
	v_mov_b32_e32 v170, v132
	ds_read_b128 v[192:195], v134 offset:32768
	ds_read_b128 v[196:199], v135 offset:32768
	ds_read_b128 v[200:203], v136 offset:32768
	ds_read_b128 v[204:207], v137 offset:32768
	ds_read_b128 v[208:211], v138 offset:32768
	ds_read_b128 v[212:215], v139 offset:32768
	ds_read_b128 v[216:219], v140 offset:32768
	ds_read_b128 v[220:223], v141 offset:32768
	v_mov_b32_e32 v171, v1
	v_lshl_add_u64 v[172:173], s[58:59], 0, v[0:1]
	v_add_u32_e32 v0, 0x4000, v143
	v_lshl_add_u64 v[172:173], v[172:173], 0, s[22:23]
	v_readfirstlane_b32 s12, v0
	v_add_u32_e32 v0, 0x6000, v143
	s_mov_b32 m0, s12
	v_lshl_add_u64 v[170:171], s[58:59], 0, v[170:171]
	v_readfirstlane_b32 s12, v0
	global_load_lds_dwordx4 v[172:173], off
	v_lshl_add_u64 v[170:171], v[170:171], 0, s[22:23]
	s_mov_b32 m0, s12
	s_nop 0
	global_load_lds_dwordx4 v[170:171], off
	s_waitcnt lgkmcnt(8)
	s_barrier
	s_waitcnt lgkmcnt(0)
	v_mfma_f32_16x16x32_bf16 v[30:33], v[174:177], v[192:195], v[30:33]
	v_mfma_f32_16x16x32_bf16 v[38:41], v[182:185], v[192:195], v[38:41]
	v_mfma_f32_16x16x32_bf16 v[70:73], v[174:177], v[200:203], v[70:73]
	v_mfma_f32_16x16x32_bf16 v[78:81], v[182:185], v[200:203], v[78:81]
	v_mfma_f32_16x16x32_bf16 v[106:109], v[174:177], v[208:211], v[106:109]
	v_mfma_f32_16x16x32_bf16 v[114:117], v[182:185], v[208:211], v[114:117]
	v_mfma_f32_16x16x32_bf16 v[122:125], v[174:177], v[216:219], v[122:125]
	v_mfma_f32_16x16x32_bf16 v[110:113], v[182:185], v[216:219], v[110:113]
	v_mfma_f32_16x16x32_bf16 v[30:33], v[178:181], v[196:199], v[30:33]
	v_mfma_f32_16x16x32_bf16 v[38:41], v[188:191], v[196:199], v[38:41]
	v_mfma_f32_16x16x32_bf16 v[70:73], v[178:181], v[204:207], v[70:73]
	v_mfma_f32_16x16x32_bf16 v[78:81], v[188:191], v[204:207], v[78:81]
	v_mfma_f32_16x16x32_bf16 v[106:109], v[178:181], v[212:215], v[106:109]
	v_mfma_f32_16x16x32_bf16 v[114:117], v[188:191], v[212:215], v[114:117]
	v_mfma_f32_16x16x32_bf16 v[122:125], v[178:181], v[220:223], v[122:125]
	v_mfma_f32_16x16x32_bf16 v[110:113], v[188:191], v[220:223], v[110:113]
	s_barrier
	v_add_u32_e32 v170, v151, v152
	v_add_u32_e32 v172, v151, v154
	v_mov_b32_e32 v0, v130
	v_mov_b32_e32 v240, v132
	v_add_u32_e32 v171, v151, v153
	ds_read_b128 v[224:227], v170
	ds_read_b128 v[228:231], v171
	v_add_u32_e32 v173, v151, v155
	ds_read_b128 v[232:235], v172
	ds_read_b128 v[236:239], v173
	v_readfirstlane_b32 s12, v133
	v_lshl_add_u64 v[242:243], s[60:61], 0, v[0:1]
	v_mov_b32_e32 v241, v1
	v_lshl_add_u64 v[242:243], v[242:243], 0, s[24:25]
	s_mov_b32 m0, s12
	v_lshl_add_u64 v[240:241], s[60:61], 0, v[240:241]
	v_readfirstlane_b32 s12, v142
	global_load_lds_dwordx4 v[242:243], off
	v_lshl_add_u64 v[240:241], v[240:241], 0, s[24:25]
	s_mov_b32 m0, s12
	s_nop 0
	global_load_lds_dwordx4 v[240:241], off
	s_barrier
; #define LDA(dst, b, h) for (int m = 0; m < 4; ++m) for (int k = 0; k < 2; ++k) \
;     dst[m][k] = *reinterpret_cast<const bf16x8*>((char*)SA(b, h) + lds_byte(wr * 64 + m * 16 + fr, k * 32 + fq * 8))
; #define LDB(dst, b, h) for (int n = 0; n < 2; ++n) for (int k = 0; k < 2; ++k) \
;     dst[n][k] = *reinterpret_cast<const bf16x8*>((char*)SB(b, h) + lds_byte(wc * 32 + n * 16 + fr, k * 32 + fq * 8))
; #define MMA(ai, bj, At_, Bt_) do { __builtin_amdgcn_s_setprio(1); \
;     for (int m = 0; m < 4; ++m) for (int n = 0; n < 2; ++n) for (int k = 0; k < 2; ++k) \
;       acc[ai][bj][m][n] = MFMA16(Bt_[n][k], At_[m][k], acc[ai][bj][m][n]); \
;     __builtin_amdgcn_s_setprio(0); } while (0)
; #define WAIT_V(n) asm volatile("s_waitcnt vmcnt(" #n ")" ::: "memory")
; #define WAIT_L(n) asm volatile("s_waitcnt lgkmcnt(" #n ")" ::: "memory")
; #define BAR __builtin_amdgcn_s_barrier()
; #define SCHED __builtin_amdgcn_sched_barrier(0)
; template <int PART  , bool SYNC_FIRST = true>
; __device__ __forceinline__ void kloop_t(const u16* __restrict__ A, int lda, const u16* __restrict__ Bt, int ldb, int K, Acc& acc, const int wv) {
;     ...
;     BAR; WAIT_L(0); MMA(0, 1, At, B1); BAR;
;     LDA(At, 1, 1); STAGE(SA(1, 0), A, lda, 0, t + 3);
;     BAR; WAIT_L(0); MMA(1, 0, At, B0); BAR; SCHED;
;     STAGE(SB(1, 1), Bt, ldb, HALF, t + 3);
;     WAIT_V(6); BAR; MMA(1, 1, At, B1); BAR;
;   }
;   { LDB(B0, 0, 0); LDA(At, 0, 0); STAGE(SA(1, 1), A, lda, HALF, nt - 1);
	s_waitcnt lgkmcnt(0)
	v_mfma_f32_16x16x32_bf16 v[42:45], v[224:227], v[192:195], v[42:45]
	v_mfma_f32_16x16x32_bf16 v[46:49], v[232:235], v[192:195], v[46:49]
	v_mfma_f32_16x16x32_bf16 v[82:85], v[224:227], v[200:203], v[82:85]
	v_mfma_f32_16x16x32_bf16 v[90:93], v[232:235], v[200:203], v[90:93]
	v_mfma_f32_16x16x32_bf16 v[118:121], v[224:227], v[208:211], v[118:121]
	v_mfma_f32_16x16x32_bf16 v[126:129], v[232:235], v[208:211], v[126:129]
	v_mfma_f32_16x16x32_bf16 v[102:105], v[224:227], v[216:219], v[102:105]
	v_mfma_f32_16x16x32_bf16 v[98:101], v[232:235], v[216:219], v[98:101]
	v_mfma_f32_16x16x32_bf16 v[42:45], v[228:231], v[196:199], v[42:45]
	v_mfma_f32_16x16x32_bf16 v[46:49], v[236:239], v[196:199], v[46:49]
	v_mfma_f32_16x16x32_bf16 v[82:85], v[228:231], v[204:207], v[82:85]
	v_mfma_f32_16x16x32_bf16 v[90:93], v[236:239], v[204:207], v[90:93]
	v_mfma_f32_16x16x32_bf16 v[118:121], v[228:231], v[212:215], v[118:121]
	v_mfma_f32_16x16x32_bf16 v[126:129], v[236:239], v[212:215], v[126:129]
	v_mfma_f32_16x16x32_bf16 v[102:105], v[228:231], v[220:223], v[102:105]
	v_mfma_f32_16x16x32_bf16 v[98:101], v[236:239], v[220:223], v[98:101]
	v_mov_b32_e32 v0, v130
	v_mov_b32_e32 v240, v132
	s_barrier
	ds_read_b128 v[192:195], v134 offset:49152
	ds_read_b128 v[196:199], v135 offset:49152
	ds_read_b128 v[200:203], v136 offset:49152
	ds_read_b128 v[204:207], v137 offset:49152
	ds_read_b128 v[208:211], v138 offset:49152
	ds_read_b128 v[212:215], v139 offset:49152
	ds_read_b128 v[216:219], v140 offset:49152
	ds_read_b128 v[220:223], v141 offset:49152
	v_readfirstlane_b32 s12, v144
	v_lshl_add_u64 v[242:243], s[62:63], 0, v[0:1]
	v_mov_b32_e32 v241, v1
	v_lshl_add_u64 v[242:243], v[242:243], 0, s[24:25]
	s_mov_b32 m0, s12
	v_lshl_add_u64 v[240:241], s[62:63], 0, v[240:241]
	v_readfirstlane_b32 s12, v145
	global_load_lds_dwordx4 v[242:243], off
	v_lshl_add_u64 v[240:241], v[240:241], 0, s[24:25]
	s_mov_b32 m0, s12
	s_nop 0
	global_load_lds_dwordx4 v[240:241], off
	s_barrier
	s_waitcnt lgkmcnt(0)
	v_mfma_f32_16x16x32_bf16 v[94:97], v[174:177], v[192:195], v[94:97]
	v_mfma_f32_16x16x32_bf16 v[86:89], v[182:185], v[192:195], v[86:89]
	v_mfma_f32_16x16x32_bf16 v[62:65], v[174:177], v[200:203], v[62:65]
	v_mfma_f32_16x16x32_bf16 v[58:61], v[182:185], v[200:203], v[58:61]
	v_mfma_f32_16x16x32_bf16 v[34:37], v[174:177], v[208:211], v[34:37]
	v_mfma_f32_16x16x32_bf16 v[26:29], v[182:185], v[208:211], v[26:29]
	v_mfma_f32_16x16x32_bf16 v[14:17], v[174:177], v[216:219], v[14:17]
	v_mfma_f32_16x16x32_bf16 v[10:13], v[182:185], v[216:219], v[10:13]
	v_mfma_f32_16x16x32_bf16 v[94:97], v[178:181], v[196:199], v[94:97]
	v_mfma_f32_16x16x32_bf16 v[86:89], v[188:191], v[196:199], v[86:89]
	v_mfma_f32_16x16x32_bf16 v[62:65], v[178:181], v[204:207], v[62:65]
	v_mfma_f32_16x16x32_bf16 v[58:61], v[188:191], v[204:207], v[58:61]
	v_mfma_f32_16x16x32_bf16 v[34:37], v[178:181], v[212:215], v[34:37]
	v_mfma_f32_16x16x32_bf16 v[26:29], v[188:191], v[212:215], v[26:29]
	v_mfma_f32_16x16x32_bf16 v[14:17], v[178:181], v[220:223], v[14:17]
	v_mfma_f32_16x16x32_bf16 v[10:13], v[188:191], v[220:223], v[10:13]
	s_barrier
	v_mov_b32_e32 v0, v130
	v_mov_b32_e32 v174, v132
	v_readfirstlane_b32 s12, v146
	v_lshl_add_u64 v[176:177], s[64:65], 0, v[0:1]
	v_mov_b32_e32 v175, v1
	v_lshl_add_u64 v[176:177], v[176:177], 0, s[24:25]
	s_mov_b32 m0, s12
	v_lshl_add_u64 v[174:175], s[64:65], 0, v[174:175]
	v_readfirstlane_b32 s12, v147
	global_load_lds_dwordx4 v[176:177], off
	v_lshl_add_u64 v[174:175], v[174:175], 0, s[24:25]
	s_mov_b32 m0, s12
	s_nop 0
	global_load_lds_dwordx4 v[174:175], off
	s_waitcnt vmcnt(6)
	s_barrier
	v_mfma_f32_16x16x32_bf16 v[74:77], v[224:227], v[192:195], v[74:77]
	v_mfma_f32_16x16x32_bf16 v[66:69], v[232:235], v[192:195], v[66:69]
	v_mfma_f32_16x16x32_bf16 v[54:57], v[224:227], v[200:203], v[54:57]
	v_mfma_f32_16x16x32_bf16 v[50:53], v[232:235], v[200:203], v[50:53]
	v_mfma_f32_16x16x32_bf16 v[22:25], v[224:227], v[208:211], v[22:25]
	v_mfma_f32_16x16x32_bf16 v[18:21], v[232:235], v[208:211], v[18:21]
	v_mfma_f32_16x16x32_bf16 v[6:9], v[224:227], v[216:219], v[6:9]
	v_mfma_f32_16x16x32_bf16 v[2:5], v[232:235], v[216:219], v[2:5]
	v_mfma_f32_16x16x32_bf16 v[74:77], v[228:231], v[196:199], v[74:77]
	v_mfma_f32_16x16x32_bf16 v[66:69], v[236:239], v[196:199], v[66:69]
	v_mfma_f32_16x16x32_bf16 v[54:57], v[228:231], v[204:207], v[54:57]
	v_mfma_f32_16x16x32_bf16 v[50:53], v[236:239], v[204:207], v[50:53]
	v_mfma_f32_16x16x32_bf16 v[22:25], v[228:231], v[212:215], v[22:25]
	v_mfma_f32_16x16x32_bf16 v[18:21], v[236:239], v[212:215], v[18:21]
	v_mfma_f32_16x16x32_bf16 v[6:9], v[228:231], v[220:223], v[6:9]
	v_mfma_f32_16x16x32_bf16 v[2:5], v[236:239], v[220:223], v[2:5]
	s_add_i32 vcc_hi, vcc_hi, 2
	s_add_u32 s56, s56, 0x100
	s_addc_u32 s57, s57, 0
	s_cmp_lt_u32 vcc_hi, 4
	s_barrier
	s_cbranch_scc1 .LBB0_704
	s_add_u32 s0, s0, s6
	ds_read_b128 v[142:145], v156
	ds_read_b128 v[146:149], v157
	ds_read_b128 v[150:153], v158
	ds_read_b128 v[154:157], v159
	ds_read_b128 v[174:177], v134
	ds_read_b128 v[178:181], v135
	ds_read_b128 v[182:185], v136
	ds_read_b128 v[188:191], v137
	ds_read_b128 v[192:195], v138
	ds_read_b128 v[196:199], v139
	ds_read_b128 v[200:203], v140
	ds_read_b128 v[204:207], v141
	s_addc_u32 s1, s1, s7
	v_mov_b32_e32 v131, v1
	v_lshl_add_u64 v[130:131], s[0:1], 0, v[130:131]
	v_readfirstlane_b32 s4, v160
	v_lshl_add_u64 v[130:131], v[130:131], 0, s[26:27]
	s_mov_b32 m0, s4
	v_mov_b32_e32 v133, v1
	global_load_lds_dwordx4 v[130:131], off
	v_lshl_add_u64 v[130:131], s[0:1], 0, v[132:133]
	v_readfirstlane_b32 s0, v161
	v_lshl_add_u64 v[130:131], v[130:131], 0, s[26:27]
	s_mov_b32 m0, s0
	s_nop 0
	global_load_lds_dwordx4 v[130:131], off
	s_barrier
; #define LDA(dst, b, h) for (int m = 0; m < 4; ++m) for (int k = 0; k < 2; ++k) \
;     dst[m][k] = *reinterpret_cast<const bf16x8*>((char*)SA(b, h) + lds_byte(wr * 64 + m * 16 + fr, k * 32 + fq * 8))
; #define LDB(dst, b, h) for (int n = 0; n < 2; ++n) for (int k = 0; k < 2; ++k) \
;     dst[n][k] = *reinterpret_cast<const bf16x8*>((char*)SB(b, h) + lds_byte(wc * 32 + n * 16 + fr, k * 32 + fq * 8))
; #define MMA(ai, bj, At_, Bt_) do { __builtin_amdgcn_s_setprio(1); \
;     for (int m = 0; m < 4; ++m) for (int n = 0; n < 2; ++n) for (int k = 0; k < 2; ++k) \
;       acc[ai][bj][m][n] = MFMA16(Bt_[n][k], At_[m][k], acc[ai][bj][m][n]); \
;     __builtin_amdgcn_s_setprio(0); } while (0)
; #define WAIT_V(n) asm volatile("s_waitcnt vmcnt(" #n ")" ::: "memory")
; #define WAIT_L(n) asm volatile("s_waitcnt lgkmcnt(" #n ")" ::: "memory")
; #define BAR __builtin_amdgcn_s_barrier()
; template <int PART  , bool SYNC_FIRST = true>
; __device__ __forceinline__ void kloop_t(const u16* __restrict__ A, int lda, const u16* __restrict__ Bt, int ldb, int K, Acc& acc, const int wv) {
;     ...
;     BAR; WAIT_L(0); MMA(0, 0, At, B0); BAR;
;     LDB(B1, 0, 1); BAR; WAIT_L(0); MMA(0, 1, At, B1); BAR;
;     LDA(At, 0, 1); WAIT_V(4); BAR; WAIT_L(0); MMA(1, 0, At, B0); MMA(1, 1, At, B1); BAR; }
;   { LDB(B0, 1, 0); LDA(At, 1, 0); WAIT_V(2); BAR; WAIT_L(0); MMA(0, 0, At, B0); BAR;
;     LDB(B1, 1, 1); WAIT_V(0); BAR; WAIT_L(0); MMA(0, 1, At, B1); BAR;
	s_waitcnt lgkmcnt(0)
	v_mfma_f32_16x16x32_bf16 v[30:33], v[142:145], v[174:177], v[30:33]
	v_mfma_f32_16x16x32_bf16 v[38:41], v[150:153], v[174:177], v[38:41]
	v_mfma_f32_16x16x32_bf16 v[70:73], v[142:145], v[182:185], v[70:73]
	v_mfma_f32_16x16x32_bf16 v[78:81], v[150:153], v[182:185], v[78:81]
	v_mfma_f32_16x16x32_bf16 v[106:109], v[142:145], v[192:195], v[106:109]
	v_mfma_f32_16x16x32_bf16 v[114:117], v[150:153], v[192:195], v[114:117]
	v_mfma_f32_16x16x32_bf16 v[122:125], v[142:145], v[200:203], v[122:125]
	v_mfma_f32_16x16x32_bf16 v[110:113], v[150:153], v[200:203], v[110:113]
	v_mfma_f32_16x16x32_bf16 v[30:33], v[146:149], v[178:181], v[30:33]
	v_mfma_f32_16x16x32_bf16 v[38:41], v[154:157], v[178:181], v[38:41]
	v_mfma_f32_16x16x32_bf16 v[70:73], v[146:149], v[188:191], v[70:73]
	v_mfma_f32_16x16x32_bf16 v[78:81], v[154:157], v[188:191], v[78:81]
	v_mfma_f32_16x16x32_bf16 v[106:109], v[146:149], v[196:199], v[106:109]
	v_mfma_f32_16x16x32_bf16 v[114:117], v[154:157], v[196:199], v[114:117]
	v_mfma_f32_16x16x32_bf16 v[122:125], v[146:149], v[204:207], v[122:125]
	v_mfma_f32_16x16x32_bf16 v[110:113], v[154:157], v[204:207], v[110:113]
	s_barrier
	ds_read_b128 v[130:133], v162
	ds_read_b128 v[158:161], v163
	ds_read_b128 v[208:211], v164
	ds_read_b128 v[162:165], v165
	s_barrier
	s_waitcnt lgkmcnt(0)
	v_mfma_f32_16x16x32_bf16 v[42:45], v[130:133], v[174:177], v[42:45]
	v_mfma_f32_16x16x32_bf16 v[46:49], v[208:211], v[174:177], v[46:49]
	v_mfma_f32_16x16x32_bf16 v[82:85], v[130:133], v[182:185], v[82:85]
	v_mfma_f32_16x16x32_bf16 v[90:93], v[208:211], v[182:185], v[90:93]
	v_mfma_f32_16x16x32_bf16 v[118:121], v[130:133], v[192:195], v[118:121]
	v_mfma_f32_16x16x32_bf16 v[126:129], v[208:211], v[192:195], v[126:129]
	v_mfma_f32_16x16x32_bf16 v[102:105], v[130:133], v[200:203], v[102:105]
	v_mfma_f32_16x16x32_bf16 v[98:101], v[208:211], v[200:203], v[98:101]
	v_mfma_f32_16x16x32_bf16 v[42:45], v[158:161], v[178:181], v[42:45]
	v_mfma_f32_16x16x32_bf16 v[46:49], v[162:165], v[178:181], v[46:49]
	v_mfma_f32_16x16x32_bf16 v[82:85], v[158:161], v[188:191], v[82:85]
	v_mfma_f32_16x16x32_bf16 v[90:93], v[162:165], v[188:191], v[90:93]
	v_mfma_f32_16x16x32_bf16 v[118:121], v[158:161], v[196:199], v[118:121]
	v_mfma_f32_16x16x32_bf16 v[126:129], v[162:165], v[196:199], v[126:129]
	v_mfma_f32_16x16x32_bf16 v[102:105], v[158:161], v[204:207], v[102:105]
	v_mfma_f32_16x16x32_bf16 v[98:101], v[162:165], v[204:207], v[98:101]
	s_barrier
	ds_read_b128 v[174:177], v134 offset:16384
	ds_read_b128 v[178:181], v135 offset:16384
	ds_read_b128 v[182:185], v136 offset:16384
	ds_read_b128 v[188:191], v137 offset:16384
	ds_read_b128 v[192:195], v138 offset:16384
	ds_read_b128 v[196:199], v139 offset:16384
	ds_read_b128 v[200:203], v140 offset:16384
	ds_read_b128 v[204:207], v141 offset:16384
	s_waitcnt vmcnt(4)
	s_barrier
	s_waitcnt lgkmcnt(0)
	v_mfma_f32_16x16x32_bf16 v[94:97], v[142:145], v[174:177], v[94:97]
	v_mfma_f32_16x16x32_bf16 v[86:89], v[150:153], v[174:177], v[86:89]
	v_mfma_f32_16x16x32_bf16 v[62:65], v[142:145], v[182:185], v[62:65]
	v_mfma_f32_16x16x32_bf16 v[58:61], v[150:153], v[182:185], v[58:61]
	v_mfma_f32_16x16x32_bf16 v[34:37], v[142:145], v[192:195], v[34:37]
	v_mfma_f32_16x16x32_bf16 v[26:29], v[150:153], v[192:195], v[26:29]
	v_mfma_f32_16x16x32_bf16 v[14:17], v[142:145], v[200:203], v[14:17]
	v_mfma_f32_16x16x32_bf16 v[10:13], v[150:153], v[200:203], v[10:13]
	v_mfma_f32_16x16x32_bf16 v[94:97], v[146:149], v[178:181], v[94:97]
	v_mfma_f32_16x16x32_bf16 v[86:89], v[154:157], v[178:181], v[86:89]
	v_mfma_f32_16x16x32_bf16 v[62:65], v[146:149], v[188:191], v[62:65]
	v_mfma_f32_16x16x32_bf16 v[58:61], v[154:157], v[188:191], v[58:61]
	v_mfma_f32_16x16x32_bf16 v[34:37], v[146:149], v[196:199], v[34:37]
	v_mfma_f32_16x16x32_bf16 v[26:29], v[154:157], v[196:199], v[26:29]
	v_mfma_f32_16x16x32_bf16 v[14:17], v[146:149], v[204:207], v[14:17]
	v_mfma_f32_16x16x32_bf16 v[10:13], v[154:157], v[204:207], v[10:13]
	v_mfma_f32_16x16x32_bf16 v[74:77], v[130:133], v[174:177], v[74:77]
	v_mfma_f32_16x16x32_bf16 v[66:69], v[208:211], v[174:177], v[66:69]
	v_mfma_f32_16x16x32_bf16 v[54:57], v[130:133], v[182:185], v[54:57]
	v_mfma_f32_16x16x32_bf16 v[50:53], v[208:211], v[182:185], v[50:53]
	v_mfma_f32_16x16x32_bf16 v[22:25], v[130:133], v[192:195], v[22:25]
	v_mfma_f32_16x16x32_bf16 v[18:21], v[208:211], v[192:195], v[18:21]
	v_mfma_f32_16x16x32_bf16 v[6:9], v[130:133], v[200:203], v[6:9]
	v_mfma_f32_16x16x32_bf16 v[2:5], v[208:211], v[200:203], v[2:5]
	v_mfma_f32_16x16x32_bf16 v[74:77], v[158:161], v[178:181], v[74:77]
	v_mfma_f32_16x16x32_bf16 v[66:69], v[162:165], v[178:181], v[66:69]
	v_mfma_f32_16x16x32_bf16 v[54:57], v[158:161], v[188:191], v[54:57]
	v_mfma_f32_16x16x32_bf16 v[50:53], v[162:165], v[188:191], v[50:53]
	v_mfma_f32_16x16x32_bf16 v[22:25], v[158:161], v[196:199], v[22:25]
	v_mfma_f32_16x16x32_bf16 v[18:21], v[162:165], v[196:199], v[18:21]
	v_mfma_f32_16x16x32_bf16 v[6:9], v[158:161], v[204:207], v[6:9]
	v_mfma_f32_16x16x32_bf16 v[2:5], v[162:165], v[204:207], v[2:5]
	s_barrier
	ds_read_b128 v[130:133], v166
	ds_read_b128 v[142:145], v167
	ds_read_b128 v[146:149], v168
	ds_read_b128 v[150:153], v169
	ds_read_b128 v[154:157], v134 offset:32768
	ds_read_b128 v[158:161], v135 offset:32768
	ds_read_b128 v[162:165], v136 offset:32768
	ds_read_b128 v[166:169], v137 offset:32768
	ds_read_b128 v[174:177], v138 offset:32768
	ds_read_b128 v[178:181], v139 offset:32768
	ds_read_b128 v[182:185], v140 offset:32768
	ds_read_b128 v[188:191], v141 offset:32768
	s_waitcnt vmcnt(2)
	s_barrier
; #define LDA(dst, b, h) for (int m = 0; m < 4; ++m) for (int k = 0; k < 2; ++k) \
;     dst[m][k] = *reinterpret_cast<const bf16x8*>((char*)SA(b, h) + lds_byte(wr * 64 + m * 16 + fr, k * 32 + fq * 8))
; #define LDB(dst, b, h) for (int n = 0; n < 2; ++n) for (int k = 0; k < 2; ++k) \
;     dst[n][k] = *reinterpret_cast<const bf16x8*>((char*)SB(b, h) + lds_byte(wc * 32 + n * 16 + fr, k * 32 + fq * 8))
; #define MMA(ai, bj, At_, Bt_) do { __builtin_amdgcn_s_setprio(1); \
;     for (int m = 0; m < 4; ++m) for (int n = 0; n < 2; ++n) for (int k = 0; k < 2; ++k) \
;       acc[ai][bj][m][n] = MFMA16(Bt_[n][k], At_[m][k], acc[ai][bj][m][n]); \
;     __builtin_amdgcn_s_setprio(0); } while (0)
; #define WAIT_V(n) asm volatile("s_waitcnt vmcnt(" #n ")" ::: "memory")
; #define WAIT_L(n) asm volatile("s_waitcnt lgkmcnt(" #n ")" ::: "memory")
; #define BAR __builtin_amdgcn_s_barrier()
; template <int PART  , bool SYNC_FIRST = true>
; __device__ __forceinline__ void kloop_t(const u16* __restrict__ A, int lda, const u16* __restrict__ Bt, int ldb, int K, Acc& acc, const int wv) {
;     ...
;     LDB(B1, 1, 1); WAIT_V(0); BAR; WAIT_L(0); MMA(0, 1, At, B1); BAR;
;     LDA(At, 1, 1); BAR; WAIT_L(0); MMA(1, 0, At, B0); MMA(1, 1, At, B1); BAR; }
	s_waitcnt lgkmcnt(0)
	v_mfma_f32_16x16x32_bf16 v[30:33], v[130:133], v[154:157], v[30:33]
	v_mfma_f32_16x16x32_bf16 v[38:41], v[146:149], v[154:157], v[38:41]
	v_mfma_f32_16x16x32_bf16 v[70:73], v[130:133], v[162:165], v[70:73]
	v_mfma_f32_16x16x32_bf16 v[78:81], v[146:149], v[162:165], v[78:81]
	v_mfma_f32_16x16x32_bf16 v[106:109], v[130:133], v[174:177], v[106:109]
	v_mfma_f32_16x16x32_bf16 v[114:117], v[146:149], v[174:177], v[114:117]
	v_mfma_f32_16x16x32_bf16 v[122:125], v[130:133], v[182:185], v[122:125]
	v_mfma_f32_16x16x32_bf16 v[110:113], v[146:149], v[182:185], v[110:113]
	v_mfma_f32_16x16x32_bf16 v[30:33], v[142:145], v[158:161], v[30:33]
	v_mfma_f32_16x16x32_bf16 v[38:41], v[150:153], v[158:161], v[38:41]
	v_mfma_f32_16x16x32_bf16 v[70:73], v[142:145], v[166:169], v[70:73]
	v_mfma_f32_16x16x32_bf16 v[78:81], v[150:153], v[166:169], v[78:81]
	v_mfma_f32_16x16x32_bf16 v[106:109], v[142:145], v[178:181], v[106:109]
	v_mfma_f32_16x16x32_bf16 v[114:117], v[150:153], v[178:181], v[114:117]
	v_mfma_f32_16x16x32_bf16 v[122:125], v[142:145], v[188:191], v[122:125]
	v_mfma_f32_16x16x32_bf16 v[110:113], v[150:153], v[188:191], v[110:113]
	s_barrier
	ds_read_b128 v[192:195], v170
	ds_read_b128 v[196:199], v171
	ds_read_b128 v[200:203], v172
	ds_read_b128 v[170:173], v173
	s_waitcnt vmcnt(0)
	s_barrier
	s_waitcnt lgkmcnt(0)
	v_mfma_f32_16x16x32_bf16 v[42:45], v[192:195], v[154:157], v[42:45]
	v_mfma_f32_16x16x32_bf16 v[46:49], v[200:203], v[154:157], v[46:49]
	v_mfma_f32_16x16x32_bf16 v[82:85], v[192:195], v[162:165], v[82:85]
	v_mfma_f32_16x16x32_bf16 v[90:93], v[200:203], v[162:165], v[90:93]
	v_mfma_f32_16x16x32_bf16 v[118:121], v[192:195], v[174:177], v[118:121]
	v_mfma_f32_16x16x32_bf16 v[126:129], v[200:203], v[174:177], v[126:129]
	v_mfma_f32_16x16x32_bf16 v[102:105], v[192:195], v[182:185], v[102:105]
	v_mfma_f32_16x16x32_bf16 v[98:101], v[200:203], v[182:185], v[98:101]
	v_mfma_f32_16x16x32_bf16 v[42:45], v[196:199], v[158:161], v[42:45]
	v_mfma_f32_16x16x32_bf16 v[46:49], v[170:173], v[158:161], v[46:49]
	v_mfma_f32_16x16x32_bf16 v[82:85], v[196:199], v[166:169], v[82:85]
	v_mfma_f32_16x16x32_bf16 v[90:93], v[170:173], v[166:169], v[90:93]
	v_mfma_f32_16x16x32_bf16 v[118:121], v[196:199], v[178:181], v[118:121]
	v_mfma_f32_16x16x32_bf16 v[126:129], v[170:173], v[178:181], v[126:129]
	v_mfma_f32_16x16x32_bf16 v[102:105], v[196:199], v[188:191], v[102:105]
	v_mfma_f32_16x16x32_bf16 v[98:101], v[170:173], v[188:191], v[98:101]
	s_barrier
	ds_read_b128 v[154:157], v134 offset:49152
	ds_read_b128 v[158:161], v135 offset:49152
	ds_read_b128 v[162:165], v136 offset:49152
	ds_read_b128 v[134:137], v137 offset:49152
	ds_read_b128 v[166:169], v138 offset:49152
	ds_read_b128 v[174:177], v139 offset:49152
	ds_read_b128 v[178:181], v140 offset:49152
	ds_read_b128 v[138:141], v141 offset:49152
	s_barrier
	s_waitcnt lgkmcnt(0)
	v_mfma_f32_16x16x32_bf16 v[94:97], v[130:133], v[154:157], v[94:97]
	v_mfma_f32_16x16x32_bf16 v[86:89], v[146:149], v[154:157], v[86:89]
	v_mfma_f32_16x16x32_bf16 v[62:65], v[130:133], v[162:165], v[62:65]
	v_mfma_f32_16x16x32_bf16 v[58:61], v[146:149], v[162:165], v[58:61]
	v_mfma_f32_16x16x32_bf16 v[34:37], v[130:133], v[166:169], v[34:37]
	v_mfma_f32_16x16x32_bf16 v[26:29], v[146:149], v[166:169], v[26:29]
	v_mfma_f32_16x16x32_bf16 v[14:17], v[130:133], v[178:181], v[14:17]
	v_mfma_f32_16x16x32_bf16 v[10:13], v[146:149], v[178:181], v[10:13]
	v_mfma_f32_16x16x32_bf16 v[94:97], v[142:145], v[158:161], v[94:97]
	v_mfma_f32_16x16x32_bf16 v[86:89], v[150:153], v[158:161], v[86:89]
	v_mfma_f32_16x16x32_bf16 v[62:65], v[142:145], v[134:137], v[62:65]
	v_mfma_f32_16x16x32_bf16 v[58:61], v[150:153], v[134:137], v[58:61]
	v_mfma_f32_16x16x32_bf16 v[34:37], v[142:145], v[174:177], v[34:37]
	v_mfma_f32_16x16x32_bf16 v[26:29], v[150:153], v[174:177], v[26:29]
	v_mfma_f32_16x16x32_bf16 v[14:17], v[142:145], v[138:141], v[14:17]
	v_mfma_f32_16x16x32_bf16 v[10:13], v[150:153], v[138:141], v[10:13]
	v_mfma_f32_16x16x32_bf16 v[74:77], v[192:195], v[154:157], v[74:77]
	v_mfma_f32_16x16x32_bf16 v[66:69], v[200:203], v[154:157], v[66:69]
	v_mfma_f32_16x16x32_bf16 v[54:57], v[192:195], v[162:165], v[54:57]
	v_mfma_f32_16x16x32_bf16 v[50:53], v[200:203], v[162:165], v[50:53]
	v_mfma_f32_16x16x32_bf16 v[22:25], v[192:195], v[166:169], v[22:25]
	v_mfma_f32_16x16x32_bf16 v[18:21], v[200:203], v[166:169], v[18:21]
	v_mfma_f32_16x16x32_bf16 v[6:9], v[192:195], v[178:181], v[6:9]
	v_mfma_f32_16x16x32_bf16 v[2:5], v[200:203], v[178:181], v[2:5]
	v_mfma_f32_16x16x32_bf16 v[74:77], v[196:199], v[158:161], v[74:77]
	v_mfma_f32_16x16x32_bf16 v[66:69], v[170:173], v[158:161], v[66:69]
	v_mfma_f32_16x16x32_bf16 v[54:57], v[196:199], v[134:137], v[54:57]
	v_mfma_f32_16x16x32_bf16 v[50:53], v[170:173], v[134:137], v[50:53]
	v_mfma_f32_16x16x32_bf16 v[22:25], v[196:199], v[174:177], v[22:25]
	v_mfma_f32_16x16x32_bf16 v[18:21], v[170:173], v[174:177], v[18:21]
	v_mfma_f32_16x16x32_bf16 v[6:9], v[196:199], v[138:141], v[6:9]
	v_mfma_f32_16x16x32_bf16 v[2:5], v[170:173], v[138:141], v[2:5]
	s_andn2_b64 vcc, exec, s[16:17]
	s_barrier
	s_cbranch_vccnz .LBB0_707
	s_barrier

; #define LDA(dst, b, h) for (int m = 0; m < 4; ++m) for (int k = 0; k < 2; ++k) \
;     dst[m][k] = *reinterpret_cast<const bf16x8*>((char*)SA(b, h) + lds_byte(wr * 64 + m * 16 + fr, k * 32 + fq * 8))
; #define LDB(dst, b, h) for (int n = 0; n < 2; ++n) for (int k = 0; k < 2; ++k) \
;     dst[n][k] = *reinterpret_cast<const bf16x8*>((char*)SB(b, h) + lds_byte(wc * 32 + n * 16 + fr, k * 32 + fq * 8))
; #define MMA(ai, bj, At_, Bt_) do { __builtin_amdgcn_s_setprio(1); \
;     for (int m = 0; m < 4; ++m) for (int n = 0; n < 2; ++n) for (int k = 0; k < 2; ++k) \
;       acc[ai][bj][m][n] = MFMA16(Bt_[n][k], At_[m][k], acc[ai][bj][m][n]); \
;     __builtin_amdgcn_s_setprio(0); } while (0)
; #define WAIT_L(n) asm volatile("s_waitcnt lgkmcnt(" #n ")" ::: "memory")
; #define BAR __builtin_amdgcn_s_barrier()
; #define SCHED __builtin_amdgcn_sched_barrier(0)
; template <int PART  , bool SYNC_FIRST = true>
; __device__ __forceinline__ void kloop_t(const u16* __restrict__ A, int lda, const u16* __restrict__ Bt, int ldb, int K, Acc& acc, const int wv) {
;     ...
;     LDB(B0, 0, 0); SCHED; LDA(At, 0, 0); STAGE(SA(1, 1), A, lda, HALF, t + 1);
;     WAIT_L(8); BAR; WAIT_L(0); MMA(0, 0, At, B0); BAR; SCHED;
;     LDB(B1, 0, 1); STAGE(SB(0, 0), Bt, ldb, 0, t + 2);
;     BAR; WAIT_L(0); MMA(0, 1, At, B1); BAR;
;     LDA(At, 0, 1); STAGE(SA(0, 0), A, lda, 0, t + 2);
.LBB0_980:
	v_add_u32_e32 v163, v155, v159
	v_add_u32_e32 v165, v155, v161
	v_add_u32_e32 v164, v155, v160
	ds_read_b128 v[174:177], v163
	ds_read_b128 v[178:181], v164
	v_add_u32_e32 v166, v155, v162
	ds_read_b128 v[182:185], v165
	ds_read_b128 v[186:189], v166
	s_add_u32 s36, s34, s72
	v_mov_b32_e32 v128, v130
	v_mov_b32_e32 v168, v131
	s_addc_u32 s37, s35, 0
	v_add_u32_e32 v167, 0xc000, v143
	ds_read_b128 v[190:193], v132
	ds_read_b128 v[194:197], v133
	ds_read_b128 v[198:201], v135
	ds_read_b128 v[202:205], v136
	ds_read_b128 v[206:209], v137
	ds_read_b128 v[210:213], v138
	ds_read_b128 v[214:217], v139
	ds_read_b128 v[218:221], v140
	v_readfirstlane_b32 s38, v167
	v_lshl_add_u64 v[170:171], s[36:37], 0, v[128:129]
	v_mov_b32_e32 v169, v129
	v_lshl_add_u64 v[170:171], v[170:171], 0, s[14:15]
	s_mov_b32 m0, s38
	v_lshl_add_u64 v[168:169], s[36:37], 0, v[168:169]
	global_load_lds_dwordx4 v[170:171], off
	v_lshl_add_u64 v[170:171], v[168:169], 0, s[14:15]
	v_add_u32_e32 v168, 0xe000, v143
	s_nop 0
	v_readfirstlane_b32 s38, v168
	s_mov_b32 m0, s38
	s_nop 0
	global_load_lds_dwordx4 v[170:171], off
	s_waitcnt lgkmcnt(8)
	s_barrier
	s_waitcnt lgkmcnt(0)
	v_mfma_f32_16x16x32_bf16 v[124:127], v[174:177], v[190:193], v[124:127]
	v_mfma_f32_16x16x32_bf16 v[120:123], v[182:185], v[190:193], v[120:123]
	v_mfma_f32_16x16x32_bf16 v[116:119], v[174:177], v[198:201], v[116:119]
	v_mfma_f32_16x16x32_bf16 v[112:115], v[182:185], v[198:201], v[112:115]
	v_mfma_f32_16x16x32_bf16 v[108:111], v[174:177], v[206:209], v[108:111]
	v_mfma_f32_16x16x32_bf16 v[104:107], v[182:185], v[206:209], v[104:107]
	v_mfma_f32_16x16x32_bf16 v[100:103], v[174:177], v[214:217], v[100:103]
	v_mfma_f32_16x16x32_bf16 v[96:99], v[182:185], v[214:217], v[96:99]
	v_mfma_f32_16x16x32_bf16 v[124:127], v[178:181], v[194:197], v[124:127]
	v_mfma_f32_16x16x32_bf16 v[120:123], v[186:189], v[194:197], v[120:123]
	v_mfma_f32_16x16x32_bf16 v[116:119], v[178:181], v[202:205], v[116:119]
	v_mfma_f32_16x16x32_bf16 v[112:115], v[186:189], v[202:205], v[112:115]
	v_mfma_f32_16x16x32_bf16 v[108:111], v[178:181], v[210:213], v[108:111]
	v_mfma_f32_16x16x32_bf16 v[104:107], v[186:189], v[210:213], v[104:107]
	v_mfma_f32_16x16x32_bf16 v[100:103], v[178:181], v[218:221], v[100:103]
	v_mfma_f32_16x16x32_bf16 v[96:99], v[186:189], v[218:221], v[96:99]
	s_barrier
	s_add_u32 s38, s34, s73
	v_add_u32_e32 v169, v156, v159
	v_add_u32_e32 v171, v156, v161
	v_mov_b32_e32 v128, v130
	v_mov_b32_e32 v238, v131
	s_addc_u32 s39, s35, 0
	v_add_u32_e32 v170, v156, v160
	ds_read_b128 v[222:225], v169
	ds_read_b128 v[226:229], v170
	v_add_u32_e32 v172, v156, v162
	ds_read_b128 v[230:233], v171
	ds_read_b128 v[234:237], v172
	v_readfirstlane_b32 s75, v141
	v_lshl_add_u64 v[240:241], s[38:39], 0, v[128:129]
	v_mov_b32_e32 v239, v129
	v_lshl_add_u64 v[240:241], v[240:241], 0, s[16:17]
	s_mov_b32 m0, s75
	v_lshl_add_u64 v[238:239], s[38:39], 0, v[238:239]
	v_readfirstlane_b32 s75, v142
	global_load_lds_dwordx4 v[240:241], off
	v_lshl_add_u64 v[238:239], v[238:239], 0, s[16:17]
	s_mov_b32 m0, s75
	s_nop 0
	global_load_lds_dwordx4 v[238:239], off
	s_barrier
	s_waitcnt lgkmcnt(0)
	v_mfma_f32_16x16x32_bf16 v[92:95], v[222:225], v[190:193], v[92:95]
	v_mfma_f32_16x16x32_bf16 v[88:91], v[230:233], v[190:193], v[88:91]
	v_mfma_f32_16x16x32_bf16 v[84:87], v[222:225], v[198:201], v[84:87]
	v_mfma_f32_16x16x32_bf16 v[80:83], v[230:233], v[198:201], v[80:83]
	v_mfma_f32_16x16x32_bf16 v[76:79], v[222:225], v[206:209], v[76:79]
	v_mfma_f32_16x16x32_bf16 v[72:75], v[230:233], v[206:209], v[72:75]
	v_mfma_f32_16x16x32_bf16 v[68:71], v[222:225], v[214:217], v[68:71]
	v_mfma_f32_16x16x32_bf16 v[64:67], v[230:233], v[214:217], v[64:67]
	v_mfma_f32_16x16x32_bf16 v[92:95], v[226:229], v[194:197], v[92:95]
	v_mfma_f32_16x16x32_bf16 v[88:91], v[234:237], v[194:197], v[88:91]
	v_mfma_f32_16x16x32_bf16 v[84:87], v[226:229], v[202:205], v[84:87]
	v_mfma_f32_16x16x32_bf16 v[80:83], v[234:237], v[202:205], v[80:83]
	v_mfma_f32_16x16x32_bf16 v[76:79], v[226:229], v[210:213], v[76:79]
	v_mfma_f32_16x16x32_bf16 v[72:75], v[234:237], v[210:213], v[72:75]
	v_mfma_f32_16x16x32_bf16 v[68:71], v[226:229], v[218:221], v[68:71]
	v_mfma_f32_16x16x32_bf16 v[64:67], v[234:237], v[218:221], v[64:67]
	v_mov_b32_e32 v128, v130
	v_mov_b32_e32 v238, v131
	s_barrier
	ds_read_b128 v[190:193], v132 offset:16384
	ds_read_b128 v[194:197], v133 offset:16384
	ds_read_b128 v[198:201], v135 offset:16384
	ds_read_b128 v[202:205], v136 offset:16384
	ds_read_b128 v[206:209], v137 offset:16384
	ds_read_b128 v[210:213], v138 offset:16384
	ds_read_b128 v[214:217], v139 offset:16384
	ds_read_b128 v[218:221], v140 offset:16384
	v_readfirstlane_b32 s75, v143
	v_lshl_add_u64 v[240:241], s[36:37], 0, v[128:129]
	v_mov_b32_e32 v239, v129
	v_lshl_add_u64 v[240:241], v[240:241], 0, s[18:19]
	s_mov_b32 m0, s75
	v_lshl_add_u64 v[238:239], s[36:37], 0, v[238:239]
	v_readfirstlane_b32 s75, v144
	global_load_lds_dwordx4 v[240:241], off
	v_lshl_add_u64 v[238:239], v[238:239], 0, s[18:19]
	s_mov_b32 m0, s75
	s_nop 0
	global_load_lds_dwordx4 v[238:239], off
	s_barrier
; #define LDA(dst, b, h) for (int m = 0; m < 4; ++m) for (int k = 0; k < 2; ++k) \
;     dst[m][k] = *reinterpret_cast<const bf16x8*>((char*)SA(b, h) + lds_byte(wr * 64 + m * 16 + fr, k * 32 + fq * 8))
; #define LDB(dst, b, h) for (int n = 0; n < 2; ++n) for (int k = 0; k < 2; ++k) \
;     dst[n][k] = *reinterpret_cast<const bf16x8*>((char*)SB(b, h) + lds_byte(wc * 32 + n * 16 + fr, k * 32 + fq * 8))
; #define MMA(ai, bj, At_, Bt_) do { __builtin_amdgcn_s_setprio(1); \
;     for (int m = 0; m < 4; ++m) for (int n = 0; n < 2; ++n) for (int k = 0; k < 2; ++k) \
;       acc[ai][bj][m][n] = MFMA16(Bt_[n][k], At_[m][k], acc[ai][bj][m][n]); \
;     __builtin_amdgcn_s_setprio(0); } while (0)
; #define WAIT_V(n) asm volatile("s_waitcnt vmcnt(" #n ")" ::: "memory")
; #define WAIT_L(n) asm volatile("s_waitcnt lgkmcnt(" #n ")" ::: "memory")
; #define BAR __builtin_amdgcn_s_barrier()
; #define SCHED __builtin_amdgcn_sched_barrier(0)
; template <int PART  , bool SYNC_FIRST = true>
; __device__ __forceinline__ void kloop_t(const u16* __restrict__ A, int lda, const u16* __restrict__ Bt, int ldb, int K, Acc& acc, const int wv) {
;     ...
;     BAR; WAIT_L(0); MMA(1, 0, At, B0); BAR; SCHED;
;     STAGE(SB(0, 1), Bt, ldb, HALF, t + 2);
;     WAIT_V(6); BAR; MMA(1, 1, At, B1); BAR;
;     LDB(B0, 1, 0); SCHED; LDA(At, 1, 0); STAGE(SA(0, 1), A, lda, HALF, t + 2);
;     WAIT_L(8); BAR; WAIT_L(0); MMA(0, 0, At, B0); BAR; SCHED;
;     LDB(B1, 1, 1); STAGE(SB(1, 0), Bt, ldb, 0, t + 3);
	s_waitcnt lgkmcnt(0)
	v_mfma_f32_16x16x32_bf16 v[60:63], v[174:177], v[190:193], v[60:63]
	v_mfma_f32_16x16x32_bf16 v[56:59], v[182:185], v[190:193], v[56:59]
	v_mfma_f32_16x16x32_bf16 v[52:55], v[174:177], v[198:201], v[52:55]
	v_mfma_f32_16x16x32_bf16 v[48:51], v[182:185], v[198:201], v[48:51]
	v_mfma_f32_16x16x32_bf16 v[44:47], v[174:177], v[206:209], v[44:47]
	v_mfma_f32_16x16x32_bf16 v[40:43], v[182:185], v[206:209], v[40:43]
	v_mfma_f32_16x16x32_bf16 v[36:39], v[174:177], v[214:217], v[36:39]
	v_mfma_f32_16x16x32_bf16 v[32:35], v[182:185], v[214:217], v[32:35]
	v_mfma_f32_16x16x32_bf16 v[60:63], v[178:181], v[194:197], v[60:63]
	v_mfma_f32_16x16x32_bf16 v[56:59], v[186:189], v[194:197], v[56:59]
	v_mfma_f32_16x16x32_bf16 v[52:55], v[178:181], v[202:205], v[52:55]
	v_mfma_f32_16x16x32_bf16 v[48:51], v[186:189], v[202:205], v[48:51]
	v_mfma_f32_16x16x32_bf16 v[44:47], v[178:181], v[210:213], v[44:47]
	v_mfma_f32_16x16x32_bf16 v[40:43], v[186:189], v[210:213], v[40:43]
	v_mfma_f32_16x16x32_bf16 v[36:39], v[178:181], v[218:221], v[36:39]
	v_mfma_f32_16x16x32_bf16 v[32:35], v[186:189], v[218:221], v[32:35]
	s_barrier
	v_mov_b32_e32 v128, v130
	v_mov_b32_e32 v174, v131
	v_readfirstlane_b32 s75, v145
	v_lshl_add_u64 v[176:177], s[38:39], 0, v[128:129]
	v_mov_b32_e32 v175, v129
	v_lshl_add_u64 v[176:177], v[176:177], 0, s[20:21]
	s_mov_b32 m0, s75
	v_lshl_add_u64 v[174:175], s[38:39], 0, v[174:175]
	v_readfirstlane_b32 s75, v146
	global_load_lds_dwordx4 v[176:177], off
	v_lshl_add_u64 v[174:175], v[174:175], 0, s[20:21]
	s_mov_b32 m0, s75
	s_nop 0
	global_load_lds_dwordx4 v[174:175], off
	s_waitcnt vmcnt(6)
	s_barrier
	v_mfma_f32_16x16x32_bf16 v[28:31], v[222:225], v[190:193], v[28:31]
	v_mfma_f32_16x16x32_bf16 v[24:27], v[230:233], v[190:193], v[24:27]
	v_mfma_f32_16x16x32_bf16 v[20:23], v[222:225], v[198:201], v[20:23]
	v_mfma_f32_16x16x32_bf16 v[16:19], v[230:233], v[198:201], v[16:19]
	v_mfma_f32_16x16x32_bf16 v[12:15], v[222:225], v[206:209], v[12:15]
	v_mfma_f32_16x16x32_bf16 v[8:11], v[230:233], v[206:209], v[8:11]
	v_mfma_f32_16x16x32_bf16 v[4:7], v[222:225], v[214:217], v[4:7]
	v_mfma_f32_16x16x32_bf16 v[0:3], v[230:233], v[214:217], v[0:3]
	v_mfma_f32_16x16x32_bf16 v[28:31], v[226:229], v[194:197], v[28:31]
	v_mfma_f32_16x16x32_bf16 v[24:27], v[234:237], v[194:197], v[24:27]
	v_mfma_f32_16x16x32_bf16 v[20:23], v[226:229], v[202:205], v[20:23]
	v_mfma_f32_16x16x32_bf16 v[16:19], v[234:237], v[202:205], v[16:19]
	v_mfma_f32_16x16x32_bf16 v[12:15], v[226:229], v[210:213], v[12:15]
	v_mfma_f32_16x16x32_bf16 v[8:11], v[234:237], v[210:213], v[8:11]
	v_mfma_f32_16x16x32_bf16 v[4:7], v[226:229], v[218:221], v[4:7]
	v_mfma_f32_16x16x32_bf16 v[0:3], v[234:237], v[218:221], v[0:3]
	v_add_u32_e32 v173, v157, v159
	v_add_u32_e32 v175, v157, v161
	s_barrier
	v_add_u32_e32 v174, v157, v160
	ds_read_b128 v[182:185], v173
	ds_read_b128 v[186:189], v174
	v_add_u32_e32 v176, v157, v162
	ds_read_b128 v[190:193], v175
	ds_read_b128 v[194:197], v176
	v_mov_b32_e32 v128, v130
	v_mov_b32_e32 v178, v131
	ds_read_b128 v[198:201], v132 offset:32768
	ds_read_b128 v[202:205], v133 offset:32768
	ds_read_b128 v[206:209], v135 offset:32768
	ds_read_b128 v[210:213], v136 offset:32768
	ds_read_b128 v[214:217], v137 offset:32768
	ds_read_b128 v[218:221], v138 offset:32768
	ds_read_b128 v[222:225], v139 offset:32768
	ds_read_b128 v[226:229], v140 offset:32768
	v_readfirstlane_b32 s75, v147
	v_lshl_add_u64 v[180:181], s[36:37], 0, v[128:129]
	v_mov_b32_e32 v179, v129
	v_lshl_add_u64 v[180:181], v[180:181], 0, s[22:23]
	s_mov_b32 m0, s75
	v_lshl_add_u64 v[178:179], s[36:37], 0, v[178:179]
	v_readfirstlane_b32 s75, v148
	global_load_lds_dwordx4 v[180:181], off
	v_lshl_add_u64 v[178:179], v[178:179], 0, s[22:23]
	s_mov_b32 m0, s75
	s_nop 0
	global_load_lds_dwordx4 v[178:179], off
	s_waitcnt lgkmcnt(8)
	s_barrier
	s_waitcnt lgkmcnt(0)
	v_mfma_f32_16x16x32_bf16 v[124:127], v[182:185], v[198:201], v[124:127]
	v_mfma_f32_16x16x32_bf16 v[120:123], v[190:193], v[198:201], v[120:123]
	v_mfma_f32_16x16x32_bf16 v[116:119], v[182:185], v[206:209], v[116:119]
	v_mfma_f32_16x16x32_bf16 v[112:115], v[190:193], v[206:209], v[112:115]
	v_mfma_f32_16x16x32_bf16 v[108:111], v[182:185], v[214:217], v[108:111]
	v_mfma_f32_16x16x32_bf16 v[104:107], v[190:193], v[214:217], v[104:107]
	v_mfma_f32_16x16x32_bf16 v[100:103], v[182:185], v[222:225], v[100:103]
	v_mfma_f32_16x16x32_bf16 v[96:99], v[190:193], v[222:225], v[96:99]
	v_mfma_f32_16x16x32_bf16 v[124:127], v[186:189], v[202:205], v[124:127]
	v_mfma_f32_16x16x32_bf16 v[120:123], v[194:197], v[202:205], v[120:123]
	v_mfma_f32_16x16x32_bf16 v[116:119], v[186:189], v[210:213], v[116:119]
	v_mfma_f32_16x16x32_bf16 v[112:115], v[194:197], v[210:213], v[112:115]
	v_mfma_f32_16x16x32_bf16 v[108:111], v[186:189], v[218:221], v[108:111]
	v_mfma_f32_16x16x32_bf16 v[104:107], v[194:197], v[218:221], v[104:107]
	v_mfma_f32_16x16x32_bf16 v[100:103], v[186:189], v[226:229], v[100:103]
	v_mfma_f32_16x16x32_bf16 v[96:99], v[194:197], v[226:229], v[96:99]
	s_barrier
	v_add_u32_e32 v177, v158, v159
	v_add_u32_e32 v179, v158, v161
	v_mov_b32_e32 v128, v130
	v_mov_b32_e32 v246, v131
	v_add_u32_e32 v178, v158, v160
	ds_read_b128 v[230:233], v177
	ds_read_b128 v[234:237], v178
	v_add_u32_e32 v180, v158, v162
	ds_read_b128 v[238:241], v179
	ds_read_b128 v[242:245], v180
	v_readfirstlane_b32 s75, v149
	v_lshl_add_u64 v[248:249], s[38:39], 0, v[128:129]
	v_mov_b32_e32 v247, v129
	v_lshl_add_u64 v[248:249], v[248:249], 0, s[24:25]
	s_mov_b32 m0, s75
	v_lshl_add_u64 v[246:247], s[38:39], 0, v[246:247]
	v_readfirstlane_b32 s75, v150
	global_load_lds_dwordx4 v[248:249], off
	v_lshl_add_u64 v[246:247], v[246:247], 0, s[24:25]
	s_mov_b32 m0, s75
	s_nop 0
	global_load_lds_dwordx4 v[246:247], off
	s_barrier
; #define LDA(dst, b, h) for (int m = 0; m < 4; ++m) for (int k = 0; k < 2; ++k) \
;     dst[m][k] = *reinterpret_cast<const bf16x8*>((char*)SA(b, h) + lds_byte(wr * 64 + m * 16 + fr, k * 32 + fq * 8))
; #define LDB(dst, b, h) for (int n = 0; n < 2; ++n) for (int k = 0; k < 2; ++k) \
;     dst[n][k] = *reinterpret_cast<const bf16x8*>((char*)SB(b, h) + lds_byte(wc * 32 + n * 16 + fr, k * 32 + fq * 8))
; #define MMA(ai, bj, At_, Bt_) do { __builtin_amdgcn_s_setprio(1); \
;     for (int m = 0; m < 4; ++m) for (int n = 0; n < 2; ++n) for (int k = 0; k < 2; ++k) \
;       acc[ai][bj][m][n] = MFMA16(Bt_[n][k], At_[m][k], acc[ai][bj][m][n]); \
;     __builtin_amdgcn_s_setprio(0); } while (0)
; #define WAIT_V(n) asm volatile("s_waitcnt vmcnt(" #n ")" ::: "memory")
; #define WAIT_L(n) asm volatile("s_waitcnt lgkmcnt(" #n ")" ::: "memory")
; #define BAR __builtin_amdgcn_s_barrier()
; #define SCHED __builtin_amdgcn_sched_barrier(0)
; template <int PART  , bool SYNC_FIRST = true>
; __device__ __forceinline__ void kloop_t(const u16* __restrict__ A, int lda, const u16* __restrict__ Bt, int ldb, int K, Acc& acc, const int wv) {
;     ...
;     BAR; WAIT_L(0); MMA(0, 1, At, B1); BAR;
;     LDA(At, 1, 1); STAGE(SA(1, 0), A, lda, 0, t + 3);
;     BAR; WAIT_L(0); MMA(1, 0, At, B0); BAR; SCHED;
;     STAGE(SB(1, 1), Bt, ldb, HALF, t + 3);
;     WAIT_V(6); BAR; MMA(1, 1, At, B1); BAR;
;   }
;   { LDB(B0, 0, 0); LDA(At, 0, 0); STAGE(SA(1, 1), A, lda, HALF, nt - 1);
	s_waitcnt lgkmcnt(0)
	v_mfma_f32_16x16x32_bf16 v[92:95], v[230:233], v[198:201], v[92:95]
	v_mfma_f32_16x16x32_bf16 v[88:91], v[238:241], v[198:201], v[88:91]
	v_mfma_f32_16x16x32_bf16 v[84:87], v[230:233], v[206:209], v[84:87]
	v_mfma_f32_16x16x32_bf16 v[80:83], v[238:241], v[206:209], v[80:83]
	v_mfma_f32_16x16x32_bf16 v[76:79], v[230:233], v[214:217], v[76:79]
	v_mfma_f32_16x16x32_bf16 v[72:75], v[238:241], v[214:217], v[72:75]
	v_mfma_f32_16x16x32_bf16 v[68:71], v[230:233], v[222:225], v[68:71]
	v_mfma_f32_16x16x32_bf16 v[64:67], v[238:241], v[222:225], v[64:67]
	v_mfma_f32_16x16x32_bf16 v[92:95], v[234:237], v[202:205], v[92:95]
	v_mfma_f32_16x16x32_bf16 v[88:91], v[242:245], v[202:205], v[88:91]
	v_mfma_f32_16x16x32_bf16 v[84:87], v[234:237], v[210:213], v[84:87]
	v_mfma_f32_16x16x32_bf16 v[80:83], v[242:245], v[210:213], v[80:83]
	v_mfma_f32_16x16x32_bf16 v[76:79], v[234:237], v[218:221], v[76:79]
	v_mfma_f32_16x16x32_bf16 v[72:75], v[242:245], v[218:221], v[72:75]
	v_mfma_f32_16x16x32_bf16 v[68:71], v[234:237], v[226:229], v[68:71]
	v_mfma_f32_16x16x32_bf16 v[64:67], v[242:245], v[226:229], v[64:67]
	v_mov_b32_e32 v128, v130
	v_mov_b32_e32 v246, v131
	s_barrier
	ds_read_b128 v[198:201], v132 offset:49152
	ds_read_b128 v[202:205], v133 offset:49152
	ds_read_b128 v[206:209], v135 offset:49152
	ds_read_b128 v[210:213], v136 offset:49152
	ds_read_b128 v[214:217], v137 offset:49152
	ds_read_b128 v[218:221], v138 offset:49152
	ds_read_b128 v[222:225], v139 offset:49152
	ds_read_b128 v[226:229], v140 offset:49152
	v_readfirstlane_b32 s75, v151
	v_lshl_add_u64 v[248:249], s[36:37], 0, v[128:129]
	v_mov_b32_e32 v247, v129
	v_lshl_add_u64 v[248:249], v[248:249], 0, s[26:27]
	s_mov_b32 m0, s75
	v_lshl_add_u64 v[246:247], s[36:37], 0, v[246:247]
	v_readfirstlane_b32 s36, v152
	global_load_lds_dwordx4 v[248:249], off
	v_lshl_add_u64 v[246:247], v[246:247], 0, s[26:27]
	s_mov_b32 m0, s36
	s_nop 0
	global_load_lds_dwordx4 v[246:247], off
	s_barrier
	s_waitcnt lgkmcnt(0)
	v_mfma_f32_16x16x32_bf16 v[60:63], v[182:185], v[198:201], v[60:63]
	v_mfma_f32_16x16x32_bf16 v[56:59], v[190:193], v[198:201], v[56:59]
	v_mfma_f32_16x16x32_bf16 v[52:55], v[182:185], v[206:209], v[52:55]
	v_mfma_f32_16x16x32_bf16 v[48:51], v[190:193], v[206:209], v[48:51]
	v_mfma_f32_16x16x32_bf16 v[44:47], v[182:185], v[214:217], v[44:47]
	v_mfma_f32_16x16x32_bf16 v[40:43], v[190:193], v[214:217], v[40:43]
	v_mfma_f32_16x16x32_bf16 v[36:39], v[182:185], v[222:225], v[36:39]
	v_mfma_f32_16x16x32_bf16 v[32:35], v[190:193], v[222:225], v[32:35]
	v_mfma_f32_16x16x32_bf16 v[60:63], v[186:189], v[202:205], v[60:63]
	v_mfma_f32_16x16x32_bf16 v[56:59], v[194:197], v[202:205], v[56:59]
	v_mfma_f32_16x16x32_bf16 v[52:55], v[186:189], v[210:213], v[52:55]
	v_mfma_f32_16x16x32_bf16 v[48:51], v[194:197], v[210:213], v[48:51]
	v_mfma_f32_16x16x32_bf16 v[44:47], v[186:189], v[218:221], v[44:47]
	v_mfma_f32_16x16x32_bf16 v[40:43], v[194:197], v[218:221], v[40:43]
	v_mfma_f32_16x16x32_bf16 v[36:39], v[186:189], v[226:229], v[36:39]
	v_mfma_f32_16x16x32_bf16 v[32:35], v[194:197], v[226:229], v[32:35]
	s_barrier
	v_mov_b32_e32 v128, v130
	v_mov_b32_e32 v182, v131
	v_readfirstlane_b32 s36, v153
	v_lshl_add_u64 v[184:185], s[38:39], 0, v[128:129]
	v_mov_b32_e32 v183, v129
	v_lshl_add_u64 v[184:185], v[184:185], 0, s[28:29]
	s_mov_b32 m0, s36
	v_lshl_add_u64 v[182:183], s[38:39], 0, v[182:183]
	v_readfirstlane_b32 s36, v154
	global_load_lds_dwordx4 v[184:185], off
	v_lshl_add_u64 v[182:183], v[182:183], 0, s[28:29]
	s_mov_b32 m0, s36
	s_nop 0
	global_load_lds_dwordx4 v[182:183], off
	s_waitcnt vmcnt(6)
	s_barrier
	v_mfma_f32_16x16x32_bf16 v[28:31], v[230:233], v[198:201], v[28:31]
	v_mfma_f32_16x16x32_bf16 v[24:27], v[238:241], v[198:201], v[24:27]
	v_mfma_f32_16x16x32_bf16 v[20:23], v[230:233], v[206:209], v[20:23]
	v_mfma_f32_16x16x32_bf16 v[16:19], v[238:241], v[206:209], v[16:19]
	v_mfma_f32_16x16x32_bf16 v[12:15], v[230:233], v[214:217], v[12:15]
	v_mfma_f32_16x16x32_bf16 v[8:11], v[238:241], v[214:217], v[8:11]
	v_mfma_f32_16x16x32_bf16 v[4:7], v[230:233], v[222:225], v[4:7]
	v_mfma_f32_16x16x32_bf16 v[0:3], v[238:241], v[222:225], v[0:3]
	v_mfma_f32_16x16x32_bf16 v[28:31], v[234:237], v[202:205], v[28:31]
	v_mfma_f32_16x16x32_bf16 v[24:27], v[242:245], v[202:205], v[24:27]
	v_mfma_f32_16x16x32_bf16 v[20:23], v[234:237], v[210:213], v[20:23]
	v_mfma_f32_16x16x32_bf16 v[16:19], v[242:245], v[210:213], v[16:19]
	v_mfma_f32_16x16x32_bf16 v[12:15], v[234:237], v[218:221], v[12:15]
	v_mfma_f32_16x16x32_bf16 v[8:11], v[242:245], v[218:221], v[8:11]
	v_mfma_f32_16x16x32_bf16 v[4:7], v[234:237], v[226:229], v[4:7]
	v_mfma_f32_16x16x32_bf16 v[0:3], v[242:245], v[226:229], v[0:3]
	s_add_i32 s74, s74, 2
	s_add_u32 s34, s34, 0x100
	s_addc_u32 s35, s35, 0
	s_cmp_lt_u32 s74, 12
	s_barrier
	s_cbranch_scc1 .LBB0_980
	s_add_u32 s30, s30, 0x40780
	v_readfirstlane_b32 s34, v167
	s_addc_u32 s31, s31, 0
	s_mov_b32 m0, s34
	v_readfirstlane_b32 s34, v168
	ds_read_b128 v[142:145], v163
	ds_read_b128 v[146:149], v164
	ds_read_b128 v[150:153], v165
	ds_read_b128 v[154:157], v166
	ds_read_b128 v[158:161], v132
	ds_read_b128 v[162:165], v133
	ds_read_b128 v[182:185], v135
	ds_read_b128 v[186:189], v136
	ds_read_b128 v[190:193], v137
	ds_read_b128 v[194:197], v138
	ds_read_b128 v[198:201], v139
	ds_read_b128 v[202:205], v140
	s_nop 0
	global_load_lds_dwordx4 v130, s[30:31]
	s_mov_b32 m0, s34
	s_nop 0
	global_load_lds_dwordx4 v131, s[30:31]
	s_barrier
; #define LDA(dst, b, h) for (int m = 0; m < 4; ++m) for (int k = 0; k < 2; ++k) \
;     dst[m][k] = *reinterpret_cast<const bf16x8*>((char*)SA(b, h) + lds_byte(wr * 64 + m * 16 + fr, k * 32 + fq * 8))
; #define LDB(dst, b, h) for (int n = 0; n < 2; ++n) for (int k = 0; k < 2; ++k) \
;     dst[n][k] = *reinterpret_cast<const bf16x8*>((char*)SB(b, h) + lds_byte(wc * 32 + n * 16 + fr, k * 32 + fq * 8))
; #define MMA(ai, bj, At_, Bt_) do { __builtin_amdgcn_s_setprio(1); \
;     for (int m = 0; m < 4; ++m) for (int n = 0; n < 2; ++n) for (int k = 0; k < 2; ++k) \
;       acc[ai][bj][m][n] = MFMA16(Bt_[n][k], At_[m][k], acc[ai][bj][m][n]); \
;     __builtin_amdgcn_s_setprio(0); } while (0)
; #define WAIT_V(n) asm volatile("s_waitcnt vmcnt(" #n ")" ::: "memory")
; #define WAIT_L(n) asm volatile("s_waitcnt lgkmcnt(" #n ")" ::: "memory")
; #define BAR __builtin_amdgcn_s_barrier()
; template <int PART  , bool SYNC_FIRST = true>
; __device__ __forceinline__ void kloop_t(const u16* __restrict__ A, int lda, const u16* __restrict__ Bt, int ldb, int K, Acc& acc, const int wv) {
;     ...
;     BAR; WAIT_L(0); MMA(0, 0, At, B0); BAR;
;     LDB(B1, 0, 1); BAR; WAIT_L(0); MMA(0, 1, At, B1); BAR;
;     LDA(At, 0, 1); WAIT_V(4); BAR; WAIT_L(0); MMA(1, 0, At, B0); MMA(1, 1, At, B1); BAR; }
	s_waitcnt lgkmcnt(0)
	v_mfma_f32_16x16x32_bf16 v[124:127], v[142:145], v[158:161], v[124:127]
	v_mfma_f32_16x16x32_bf16 v[116:119], v[142:145], v[182:185], v[116:119]
	v_mfma_f32_16x16x32_bf16 v[112:115], v[150:153], v[182:185], v[112:115]
	v_mfma_f32_16x16x32_bf16 v[100:103], v[142:145], v[198:201], v[100:103]
	v_mfma_f32_16x16x32_bf16 v[96:99], v[150:153], v[198:201], v[96:99]
	v_mfma_f32_16x16x32_bf16 v[124:127], v[146:149], v[162:165], v[124:127]
	v_mfma_f32_16x16x32_bf16 v[120:123], v[150:153], v[158:161], v[120:123]
	v_mfma_f32_16x16x32_bf16 v[116:119], v[146:149], v[186:189], v[116:119]
	v_mfma_f32_16x16x32_bf16 v[112:115], v[154:157], v[186:189], v[112:115]
	v_mfma_f32_16x16x32_bf16 v[108:111], v[142:145], v[190:193], v[108:111]
	v_mfma_f32_16x16x32_bf16 v[104:107], v[150:153], v[190:193], v[104:107]
	v_mfma_f32_16x16x32_bf16 v[100:103], v[146:149], v[202:205], v[100:103]
	v_mfma_f32_16x16x32_bf16 v[96:99], v[154:157], v[202:205], v[96:99]
	v_mfma_f32_16x16x32_bf16 v[206:209], v[154:157], v[162:165], v[120:123]
	v_mfma_f32_16x16x32_bf16 v[210:213], v[146:149], v[194:197], v[108:111]
	v_mfma_f32_16x16x32_bf16 v[214:217], v[154:157], v[194:197], v[104:107]
	s_barrier
	s_nop 0
	ds_read_b128 v[104:107], v169
	ds_read_b128 v[108:111], v170
	ds_read_b128 v[120:123], v171
	ds_read_b128 v[166:169], v172
	s_barrier
	s_waitcnt lgkmcnt(0)
	v_mfma_f32_16x16x32_bf16 v[84:87], v[104:107], v[182:185], v[84:87]
	v_mfma_f32_16x16x32_bf16 v[80:83], v[120:123], v[182:185], v[80:83]
	v_mfma_f32_16x16x32_bf16 v[68:71], v[104:107], v[198:201], v[68:71]
	v_mfma_f32_16x16x32_bf16 v[64:67], v[120:123], v[198:201], v[64:67]
	v_mfma_f32_16x16x32_bf16 v[92:95], v[104:107], v[158:161], v[92:95]
	v_mfma_f32_16x16x32_bf16 v[88:91], v[120:123], v[158:161], v[88:91]
	v_mfma_f32_16x16x32_bf16 v[84:87], v[108:111], v[186:189], v[84:87]
	v_mfma_f32_16x16x32_bf16 v[80:83], v[166:169], v[186:189], v[80:83]
	v_mfma_f32_16x16x32_bf16 v[76:79], v[104:107], v[190:193], v[76:79]
	v_mfma_f32_16x16x32_bf16 v[72:75], v[120:123], v[190:193], v[72:75]
	v_mfma_f32_16x16x32_bf16 v[68:71], v[108:111], v[202:205], v[68:71]
	v_mfma_f32_16x16x32_bf16 v[64:67], v[166:169], v[202:205], v[64:67]
	v_mfma_f32_16x16x32_bf16 v[218:221], v[108:111], v[162:165], v[92:95]
	v_mfma_f32_16x16x32_bf16 v[158:161], v[166:169], v[162:165], v[88:91]
	v_mfma_f32_16x16x32_bf16 v[162:165], v[108:111], v[194:197], v[76:79]
	v_mfma_f32_16x16x32_bf16 v[182:185], v[166:169], v[194:197], v[72:75]
	s_barrier
	s_nop 0
	ds_read_b128 v[72:75], v132 offset:16384
	ds_read_b128 v[76:79], v133 offset:16384
	ds_read_b128 v[88:91], v135 offset:16384
	ds_read_b128 v[92:95], v136 offset:16384
	ds_read_b128 v[186:189], v137 offset:16384
	ds_read_b128 v[190:193], v138 offset:16384
	ds_read_b128 v[194:197], v139 offset:16384
	ds_read_b128 v[198:201], v140 offset:16384
	s_waitcnt vmcnt(4)
	s_barrier
	s_waitcnt lgkmcnt(0)
	v_mfma_f32_16x16x32_bf16 v[60:63], v[142:145], v[72:75], v[60:63]
	v_mfma_f32_16x16x32_bf16 v[52:55], v[142:145], v[88:91], v[52:55]
	v_mfma_f32_16x16x32_bf16 v[48:51], v[150:153], v[88:91], v[48:51]
	v_mfma_f32_16x16x32_bf16 v[36:39], v[142:145], v[194:197], v[36:39]
	v_mfma_f32_16x16x32_bf16 v[32:35], v[150:153], v[194:197], v[32:35]
	v_mfma_f32_16x16x32_bf16 v[60:63], v[146:149], v[76:79], v[60:63]
	v_mfma_f32_16x16x32_bf16 v[56:59], v[150:153], v[72:75], v[56:59]
	v_mfma_f32_16x16x32_bf16 v[52:55], v[146:149], v[92:95], v[52:55]
	v_mfma_f32_16x16x32_bf16 v[48:51], v[154:157], v[92:95], v[48:51]
	v_mfma_f32_16x16x32_bf16 v[44:47], v[142:145], v[186:189], v[44:47]
	v_mfma_f32_16x16x32_bf16 v[40:43], v[150:153], v[186:189], v[40:43]
	v_mfma_f32_16x16x32_bf16 v[36:39], v[146:149], v[198:201], v[36:39]
	v_mfma_f32_16x16x32_bf16 v[32:35], v[154:157], v[198:201], v[32:35]
	v_mfma_f32_16x16x32_bf16 v[202:205], v[154:157], v[76:79], v[56:59]
	v_mfma_f32_16x16x32_bf16 v[222:225], v[146:149], v[190:193], v[44:47]
	v_mfma_f32_16x16x32_bf16 v[226:229], v[154:157], v[190:193], v[40:43]
	v_mfma_f32_16x16x32_bf16 v[20:23], v[104:107], v[88:91], v[20:23]
	v_mfma_f32_16x16x32_bf16 v[16:19], v[120:123], v[88:91], v[16:19]
	v_mfma_f32_16x16x32_bf16 v[4:7], v[104:107], v[194:197], v[4:7]
	v_mfma_f32_16x16x32_bf16 v[0:3], v[120:123], v[194:197], v[0:3]
	v_mfma_f32_16x16x32_bf16 v[28:31], v[104:107], v[72:75], v[28:31]
	v_mfma_f32_16x16x32_bf16 v[24:27], v[120:123], v[72:75], v[24:27]
	v_mfma_f32_16x16x32_bf16 v[20:23], v[108:111], v[92:95], v[20:23]
	v_mfma_f32_16x16x32_bf16 v[16:19], v[166:169], v[92:95], v[16:19]
	v_mfma_f32_16x16x32_bf16 v[12:15], v[104:107], v[186:189], v[12:15]
	v_mfma_f32_16x16x32_bf16 v[8:11], v[120:123], v[186:189], v[8:11]
	v_mfma_f32_16x16x32_bf16 v[4:7], v[108:111], v[198:201], v[4:7]
	v_mfma_f32_16x16x32_bf16 v[0:3], v[166:169], v[198:201], v[0:3]
	v_mfma_f32_16x16x32_bf16 v[142:145], v[108:111], v[76:79], v[28:31]
	v_mfma_f32_16x16x32_bf16 v[146:149], v[166:169], v[76:79], v[24:27]
	v_mfma_f32_16x16x32_bf16 v[150:153], v[108:111], v[190:193], v[12:15]
	v_mfma_f32_16x16x32_bf16 v[154:157], v[166:169], v[190:193], v[8:11]
	s_barrier
; #define LDA(dst, b, h) for (int m = 0; m < 4; ++m) for (int k = 0; k < 2; ++k) \
;     dst[m][k] = *reinterpret_cast<const bf16x8*>((char*)SA(b, h) + lds_byte(wr * 64 + m * 16 + fr, k * 32 + fq * 8))
; #define LDB(dst, b, h) for (int n = 0; n < 2; ++n) for (int k = 0; k < 2; ++k) \
;     dst[n][k] = *reinterpret_cast<const bf16x8*>((char*)SB(b, h) + lds_byte(wc * 32 + n * 16 + fr, k * 32 + fq * 8))
; #define MMA(ai, bj, At_, Bt_) do { __builtin_amdgcn_s_setprio(1); \
;     for (int m = 0; m < 4; ++m) for (int n = 0; n < 2; ++n) for (int k = 0; k < 2; ++k) \
;       acc[ai][bj][m][n] = MFMA16(Bt_[n][k], At_[m][k], acc[ai][bj][m][n]); \
;     __builtin_amdgcn_s_setprio(0); } while (0)
; #define WAIT_V(n) asm volatile("s_waitcnt vmcnt(" #n ")" ::: "memory")
; #define WAIT_L(n) asm volatile("s_waitcnt lgkmcnt(" #n ")" ::: "memory")
; #define BAR __builtin_amdgcn_s_barrier()
; template <int PART  , bool SYNC_FIRST = true>
; __device__ __forceinline__ void kloop_t(const u16* __restrict__ A, int lda, const u16* __restrict__ Bt, int ldb, int K, Acc& acc, const int wv) {
;     ...
;   { LDB(B0, 1, 0); LDA(At, 1, 0); WAIT_V(2); BAR; WAIT_L(0); MMA(0, 0, At, B0); BAR;
;     LDB(B1, 1, 1); WAIT_V(0); BAR; WAIT_L(0); MMA(0, 1, At, B1); BAR;
;     LDA(At, 1, 1); BAR; WAIT_L(0); MMA(1, 0, At, B0); MMA(1, 1, At, B1); BAR; }
;   if (wr == 0) BAR;
	s_nop 0
	ds_read_b128 v[8:11], v173
	ds_read_b128 v[12:15], v174
	ds_read_b128 v[166:169], v175
	ds_read_b128 v[170:173], v176
	ds_read_b128 v[24:27], v132 offset:32768
	ds_read_b128 v[28:31], v133 offset:32768
	ds_read_b128 v[40:43], v135 offset:32768
	ds_read_b128 v[44:47], v136 offset:32768
	ds_read_b128 v[56:59], v137 offset:32768
	ds_read_b128 v[186:189], v138 offset:32768
	ds_read_b128 v[190:193], v139 offset:32768
	ds_read_b128 v[194:197], v140 offset:32768
	s_waitcnt vmcnt(2)
	s_barrier
	s_waitcnt lgkmcnt(0)
	v_mfma_f32_16x16x32_bf16 v[72:75], v[8:11], v[24:27], v[124:127]
	v_mfma_f32_16x16x32_bf16 v[120:123], v[12:15], v[28:31], v[72:75]
	v_mfma_f32_16x16x32_bf16 v[72:75], v[166:169], v[24:27], v[206:209]
	v_mfma_f32_16x16x32_bf16 v[124:127], v[170:173], v[28:31], v[72:75]
	v_mfma_f32_16x16x32_bf16 v[72:75], v[8:11], v[40:43], v[116:119]
	v_mfma_f32_16x16x32_bf16 v[104:107], v[12:15], v[44:47], v[72:75]
	v_mfma_f32_16x16x32_bf16 v[72:75], v[166:169], v[40:43], v[112:115]
	v_mfma_f32_16x16x32_bf16 v[108:111], v[170:173], v[44:47], v[72:75]
	v_mfma_f32_16x16x32_bf16 v[72:75], v[8:11], v[56:59], v[210:213]
	v_mfma_f32_16x16x32_bf16 v[88:91], v[12:15], v[186:189], v[72:75]
	v_mfma_f32_16x16x32_bf16 v[72:75], v[166:169], v[56:59], v[214:217]
	v_mfma_f32_16x16x32_bf16 v[92:95], v[170:173], v[186:189], v[72:75]
	v_mfma_f32_16x16x32_bf16 v[72:75], v[8:11], v[190:193], v[100:103]
	v_mfma_f32_16x16x32_bf16 v[76:79], v[166:169], v[190:193], v[96:99]
	v_mfma_f32_16x16x32_bf16 v[72:75], v[12:15], v[194:197], v[72:75]
	v_mfma_f32_16x16x32_bf16 v[76:79], v[170:173], v[194:197], v[76:79]
	s_barrier
	ds_read_b128 v[174:177], v177
	ds_read_b128 v[198:201], v178
	ds_read_b128 v[206:209], v179
	ds_read_b128 v[178:181], v180
	s_waitcnt vmcnt(0)
	s_barrier
	s_waitcnt lgkmcnt(0)
	v_mfma_f32_16x16x32_bf16 v[96:99], v[174:177], v[24:27], v[218:221]
	v_mfma_f32_16x16x32_bf16 v[24:27], v[206:209], v[24:27], v[158:161]
	v_mfma_f32_16x16x32_bf16 v[112:115], v[178:181], v[28:31], v[24:27]
	v_mfma_f32_16x16x32_bf16 v[24:27], v[174:177], v[40:43], v[84:87]
	v_mfma_f32_16x16x32_bf16 v[100:103], v[198:201], v[44:47], v[24:27]
	v_mfma_f32_16x16x32_bf16 v[24:27], v[206:209], v[40:43], v[80:83]
	v_mfma_f32_16x16x32_bf16 v[116:119], v[198:201], v[28:31], v[96:99]
	v_mfma_f32_16x16x32_bf16 v[96:99], v[178:181], v[44:47], v[24:27]
	v_mfma_f32_16x16x32_bf16 v[24:27], v[174:177], v[56:59], v[162:165]
	v_mfma_f32_16x16x32_bf16 v[84:87], v[198:201], v[186:189], v[24:27]
	v_mfma_f32_16x16x32_bf16 v[24:27], v[206:209], v[56:59], v[182:185]
	v_mfma_f32_16x16x32_bf16 v[80:83], v[178:181], v[186:189], v[24:27]
	v_mfma_f32_16x16x32_bf16 v[24:27], v[174:177], v[190:193], v[68:71]
	v_mfma_f32_16x16x32_bf16 v[68:71], v[198:201], v[194:197], v[24:27]
	v_mfma_f32_16x16x32_bf16 v[24:27], v[206:209], v[190:193], v[64:67]
	v_mfma_f32_16x16x32_bf16 v[64:67], v[178:181], v[194:197], v[24:27]
	s_barrier
	ds_read_b128 v[158:161], v132 offset:49152
	ds_read_b128 v[130:133], v133 offset:49152
	ds_read_b128 v[162:165], v135 offset:49152
	ds_read_b128 v[182:185], v136 offset:49152
	ds_read_b128 v[186:189], v137 offset:49152
	ds_read_b128 v[190:193], v138 offset:49152
	ds_read_b128 v[136:139], v139 offset:49152
	ds_read_b128 v[194:197], v140 offset:49152
	s_barrier
	s_waitcnt lgkmcnt(0)
	v_mfma_f32_16x16x32_bf16 v[24:27], v[8:11], v[158:161], v[60:63]
	v_mfma_f32_16x16x32_bf16 v[56:59], v[12:15], v[130:133], v[24:27]
	v_mfma_f32_16x16x32_bf16 v[24:27], v[166:169], v[158:161], v[202:205]
	v_mfma_f32_16x16x32_bf16 v[60:63], v[170:173], v[130:133], v[24:27]
	v_mfma_f32_16x16x32_bf16 v[24:27], v[8:11], v[162:165], v[52:55]
	v_mfma_f32_16x16x32_bf16 v[40:43], v[12:15], v[182:185], v[24:27]
	v_mfma_f32_16x16x32_bf16 v[24:27], v[166:169], v[162:165], v[48:51]
	v_mfma_f32_16x16x32_bf16 v[44:47], v[170:173], v[182:185], v[24:27]
	v_mfma_f32_16x16x32_bf16 v[24:27], v[8:11], v[186:189], v[222:225]
	v_mfma_f32_16x16x32_bf16 v[8:11], v[8:11], v[136:139], v[36:39]
	v_mfma_f32_16x16x32_bf16 v[24:27], v[12:15], v[190:193], v[24:27]
	v_mfma_f32_16x16x32_bf16 v[28:31], v[166:169], v[186:189], v[226:229]
	v_mfma_f32_16x16x32_bf16 v[8:11], v[12:15], v[194:197], v[8:11]
	v_mfma_f32_16x16x32_bf16 v[12:15], v[166:169], v[136:139], v[32:35]
	v_mfma_f32_16x16x32_bf16 v[28:31], v[170:173], v[190:193], v[28:31]
	v_mfma_f32_16x16x32_bf16 v[12:15], v[170:173], v[194:197], v[12:15]
	v_mfma_f32_16x16x32_bf16 v[32:35], v[174:177], v[158:161], v[142:145]
	v_mfma_f32_16x16x32_bf16 v[52:55], v[198:201], v[130:133], v[32:35]
	v_mfma_f32_16x16x32_bf16 v[32:35], v[206:209], v[158:161], v[146:149]
	v_mfma_f32_16x16x32_bf16 v[16:19], v[206:209], v[162:165], v[16:19]
	v_mfma_f32_16x16x32_bf16 v[48:51], v[178:181], v[130:133], v[32:35]
	v_mfma_f32_16x16x32_bf16 v[20:23], v[174:177], v[162:165], v[20:23]
	v_mfma_f32_16x16x32_bf16 v[32:35], v[178:181], v[182:185], v[16:19]
	v_mfma_f32_16x16x32_bf16 v[16:19], v[174:177], v[186:189], v[150:153]
	v_mfma_f32_16x16x32_bf16 v[36:39], v[198:201], v[182:185], v[20:23]
	v_mfma_f32_16x16x32_bf16 v[20:23], v[198:201], v[190:193], v[16:19]
	v_mfma_f32_16x16x32_bf16 v[16:19], v[206:209], v[186:189], v[154:157]
	v_mfma_f32_16x16x32_bf16 v[4:7], v[174:177], v[136:139], v[4:7]
	v_mfma_f32_16x16x32_bf16 v[0:3], v[206:209], v[136:139], v[0:3]
	v_mfma_f32_16x16x32_bf16 v[16:19], v[178:181], v[190:193], v[16:19]
	v_mfma_f32_16x16x32_bf16 v[4:7], v[198:201], v[194:197], v[4:7]
	v_mfma_f32_16x16x32_bf16 v[0:3], v[178:181], v[194:197], v[0:3]
	s_andn2_b64 vcc, exec, s[0:1]
	s_barrier
	s_cbranch_vccnz .LBB0_983
	s_barrier

; __device__ __forceinline__ int lane_fresh() { int l; asm volatile("v_mbcnt_lo_u32_b32 %0, -1, 0\n\tv_mbcnt_hi_u32_b32 %0, -1, %0" : "=v"(l)); return l; }
; #define WAIT_V(n) asm volatile("s_waitcnt vmcnt(" #n ")" ::: "memory")
; #define WAIT_L(n) asm volatile("s_waitcnt lgkmcnt(" #n ")" ::: "memory")
; template <int PART  , bool SYNC_FIRST = true>
; __device__ __forceinline__ void kloop_t(const u16* __restrict__ A, int lda, const u16* __restrict__ Bt, int ldb, int K, Acc& acc, const int wv) {
;     ...
;   const int wid = wv, lane = lane_fresh(), ktid = wv * 64 + lane, wr = wid >> 2, wc = wid & 3, fr = lane & 15, fq = lane >> 4;
;   bf16x8 At[4][2], B0[2][2], B1[2][2];
;   const int nt = K / BK;
;   unsigned oA0, oA1, oB0, oB1;
;   { int r_, c_; stage_rc(ktid * 16, r_, c_); oA0 = (unsigned)(r_ * lda + c_) * 2u; oB0 = (unsigned)(r_ * ldb + c_) * 2u;
;     stage_rc(ktid * 16 + 8192, r_, c_); oA1 = (unsigned)(r_ * lda + c_) * 2u; oB1 = (unsigned)(r_ * ldb + c_) * 2u; }
;   if (PART != 2) {
;     if (SYNC_FIRST) { WAIT_V(0); WAIT_L(0); __syncthreads(); }
;     STAGE(SB(0, 0), Bt, ldb, 0, 0); STAGE(SA(0, 0), A, lda, 0, 0);
;     STAGE(SB(0, 1), Bt, ldb, HALF, 0); STAGE(SA(0, 1), A, lda, HALF, 0);
; __device__ __forceinline__ void phaseF(const Params& p, const int wv, const int rep) {
;     ...
;     auto fill_rs = [&](int t, int buf) {
;       const int tid = wv * 64 + lane_fresh();
;       if (tid < 256) {
;         const float* ps = PS + (size_t)((t & 63) * 256 + tid) * 16;
;         f32x4 a = *(const f32x4*)ps + *(const f32x4*)(ps + 4) + *(const f32x4*)(ps + 8) + *(const f32x4*)(ps + 12);
;         rs_l[buf * 256 + tid] = rsqrtf((a[0] + a[1] + a[2] + a[3]) * (1.f / 1024.f) + EPS);
;       }
;     };
;     int t_ = blockIdx.x, it = 0;
;     const int tend = 1024 * rep;
;     Acc acc;
;     if (t_ < tend) {
;       const int t = t_ & 1023;
;       fill_rs(t, 0);
;       kloop_t<1, true>(H2B + (size_t)((t & 63) * 256) * 1024, 1024, WUP + (size_t)((t >> 6) * 256) * 1024, 1024, 1024, acc, wv);
.LBB0_1063:
	s_or_b64 exec, exec, s[4:5]
	v_readlane_b32 s75, v251, 0
	s_lshl_b32 s4, s75, 19
	s_and_b32 s4, s4, 0x1f80000
	s_add_u32 s4, s8, s4
	s_addc_u32 s5, s9, 0
	s_lshl_b32 s12, s12, 13
	s_and_b32 s12, s12, 0x780000
	s_add_u32 s12, s33, s12
	s_addc_u32 s13, s44, 0
	v_mbcnt_lo_u32_b32 v0, -1, 0
	v_mbcnt_hi_u32_b32 v0, -1, v0
	s_lshl_b32 s53, s90, 10
	v_lshl_add_u32 v0, v0, 4, s53
	v_ashrrev_i32_e32 v1, 31, v0
	v_lshrrev_b32_e32 v1, 22, v1
	v_add_u32_e32 v1, v0, v1
	v_ashrrev_i32_e32 v1, 10, v1
	v_mul_i32_i24_e32 v2, 0x400, v1
	v_sub_u32_e32 v2, v0, v2
	v_lshrrev_b32_e32 v3, 4, v2
	v_bitop3_b32 v2, v3, v2, 32 bitop3:0x6c
	v_ashrrev_i32_e32 v4, 31, v2
	v_lshrrev_b32_e32 v4, 26, v4
	v_add_u32_e32 v4, v2, v4
	v_lshrrev_b32_e32 v5, 6, v4
	v_and_b32_e32 v4, 0xc0, v4
	v_lshlrev_b32_e32 v3, 3, v1
	v_lshlrev_b32_e32 v1, 5, v1
	v_sub_u32_e32 v2, v2, v4
	v_mov_b32_e32 v132, 1
	v_and_b32_e32 v3, 0x1ffff0, v3
	v_and_b32_e32 v1, 32, v1
	v_ashrrev_i16_sdwa v2, v132, sext(v2) dst_sel:DWORD dst_unused:UNUSED_PAD src0_sel:DWORD src1_sel:BYTE_0
	v_add_u32_sdwa v1, v1, sext(v2) dst_sel:DWORD dst_unused:UNUSED_PAD src0_sel:DWORD src1_sel:WORD_0
	v_add_lshl_u32 v2, v5, v3, 11
	v_lshl_add_u32 v1, v1, 1, v2
	v_add_u32_e32 v2, 0x2000, v0
	v_ashrrev_i32_e32 v3, 31, v2
	v_lshrrev_b32_e32 v3, 22, v3
	v_add_u32_e32 v3, v2, v3
	v_ashrrev_i32_e32 v3, 10, v3
	v_mul_i32_i24_e32 v4, 0x400, v3
	v_sub_u32_e32 v2, v2, v4
	v_lshrrev_b32_e32 v4, 4, v2
	v_bitop3_b32 v2, v4, v2, 32 bitop3:0x6c
	v_ashrrev_i32_e32 v5, 31, v2
	v_lshrrev_b32_e32 v5, 26, v5
	v_add_u32_e32 v5, v2, v5
	v_lshrrev_b32_e32 v6, 6, v5
	v_and_b32_e32 v5, 0xffc0, v5
	v_sub_u32_e32 v2, v2, v5
	v_lshrrev_b16_e32 v5, 7, v2
	v_and_b32_e32 v5, 1, v5
	v_lshlrev_b32_e32 v4, 3, v3
	v_lshlrev_b32_e32 v3, 5, v3
	v_add_u16_e32 v2, v2, v5
	v_and_b32_e32 v4, 0x1ffff0, v4
	v_and_b32_e32 v3, 32, v3
	v_ashrrev_i16_sdwa v2, v132, sext(v2) dst_sel:DWORD dst_unused:UNUSED_PAD src0_sel:DWORD src1_sel:BYTE_0
	v_add_u32_sdwa v2, v3, sext(v2) dst_sel:DWORD dst_unused:UNUSED_PAD src0_sel:DWORD src1_sel:WORD_0
	v_add_lshl_u32 v3, v6, v4, 11
	s_add_i32 s54, 16, 0x10000
	v_lshl_add_u32 v2, v2, 1, v3
	v_add_u32_e32 v5, s54, v0
	v_mov_b32_e32 v3, v1
	v_mov_b32_e32 v4, v2
	v_readfirstlane_b32 s14, v5
	s_waitcnt lgkmcnt(0)
	s_barrier
	s_mov_b32 m0, s14
	v_readlane_b32 s16, v251, 1
	global_load_lds_dwordx4 v3, s[12:13]
	v_add_u32_e32 v3, 0x2000, v5
	v_add_u32_e32 v5, 16, v0
	v_readfirstlane_b32 s14, v3
	s_mov_b32 m0, s14
	v_mov_b32_e32 v3, v1
	global_load_lds_dwordx4 v4, s[12:13]
	v_mov_b32_e32 v4, v2
	v_readfirstlane_b32 s14, v5
	s_mov_b32 m0, s14
	s_add_u32 s12, s12, 0x40000
	global_load_lds_dwordx4 v3, s[4:5]
	v_add_u32_e32 v3, 0x2000, v5
	s_addc_u32 s13, s13, 0
	s_add_i32 s55, 16, 0x14000
	v_readfirstlane_b32 s14, v3
	v_add_u32_e32 v0, s55, v0
	s_mov_b32 m0, s14
	v_readfirstlane_b32 s14, v0
	v_add_u32_e32 v0, 0x2000, v0
	global_load_lds_dwordx4 v4, s[4:5]
	v_mov_b32_e32 v3, v1
	v_mov_b32_e32 v4, v2
	s_mov_b32 m0, s14
	v_readfirstlane_b32 s14, v0
	v_add_u32_e32 v0, 0x4000, v5
	global_load_lds_dwordx4 v3, s[12:13]
	s_mov_b32 m0, s14
	s_add_u32 s4, s4, 0x40000
	global_load_lds_dwordx4 v4, s[12:13]
	v_readfirstlane_b32 s12, v0
	v_add_u32_e32 v0, 0x6000, v5
	s_addc_u32 s5, s5, 0
	s_mov_b32 m0, s12
	v_readfirstlane_b32 s12, v0
	s_mov_b32 s13, 0
	global_load_lds_dwordx4 v1, s[4:5]
	s_mov_b32 m0, s12
	s_lshr_b32 s12, s91, 8
	global_load_lds_dwordx4 v2, s[4:5]
	s_cmp_eq_u32 s12, 1
	s_cselect_b64 s[4:5], -1, 0
	s_lshl_b32 s14, s90, 2
	s_lshl_b32 s57, s12, 6
	s_and_b32 s56, s14, 12
	s_or_b32 s60, s57, 16
	s_or_b32 s62, s57, 32
	s_or_b32 s64, s57, 48
	s_or_b32 s58, s56, 2
	s_lshl_b32 s59, s12, 3
	s_lshr_b32 s61, s60, 3
	s_lshr_b32 s63, s62, 3
	s_lshr_b32 s65, s64, 3
	s_cmpk_lt_u32 s91, 0x100
	s_cselect_b64 s[14:15], -1, 0
	s_lshl_b32 s12, s90, 4
	s_and_b32 s66, s12, 0x3fffffc0
	s_lshl_b32 s12, s90, 5
	s_and_b32 s12, s12, 0x60
	v_cndmask_b32_e64 v0, 0, 1, s[4:5]
	s_lshl_b32 s67, s75, 8
	s_lshl_b32 s68, s16, 8
	s_lshl_b32 s69, s75, 2
	s_lshl_b32 s70, s16, 2
	v_cmp_ne_u32_e64 s[4:5], 1, v0
	v_mov_b32_e32 v129, 0
	s_mov_b64 s[16:17], 0x80
	s_add_i32 s71, 16, 0x18000
	s_add_i32 s72, 16, 0x1c000
	s_movk_i32 s73, 0x3c0
	s_mov_b64 s[18:19], 0xf3ee080
	s_mov_b64 s[20:21], 0x1600100
	s_mov_b64 s[22:23], 0xf3ae100
	s_mov_b64 s[24:25], 0x1640100
	s_mov_b64 s[26:27], 0xf3ee100
	s_mov_b64 s[28:29], 0x1600180
	s_mov_b64 s[30:31], 0xf3ae180
	s_mov_b64 s[34:35], 0x1640180
	v_mov_b32_e32 v133, 0x358637bd
	s_mov_b32 s74, 0x800000
	s_lshl_b32 s12, s12, 1
	s_mov_b32 s76, s13
	v_mbcnt_lo_u32_b32 v220, -1, 0
	v_mbcnt_hi_u32_b32 v220, -1, v220
	v_add_u32_e32 v220, s88, v220
	v_cmp_gt_i32_e32 vcc, s52, v220
	s_and_saveexec_b64 s[98:99], vcc
	s_cbranch_execz .Lfpro_skip
	v_lshl_add_u32 v220, v220, 2, 16
	v_add_u32_e32 v220, 0x20000, v220
	v_mov_b32_e32 v221, 0x358637bd
	s_waitcnt vmcnt(10)
	v_pk_add_f32 v[200:201], v[200:201], v[204:205]
	v_pk_add_f32 v[202:203], v[202:203], v[206:207]
	s_waitcnt vmcnt(9)
	v_pk_add_f32 v[200:201], v[200:201], v[208:209]
	v_pk_add_f32 v[202:203], v[202:203], v[210:211]
	s_waitcnt vmcnt(8)
	v_pk_add_f32 v[200:201], v[200:201], v[212:213]
	v_pk_add_f32 v[202:203], v[202:203], v[214:215]
	v_add_f32_e32 v200, v200, v201
	v_add_f32_e32 v200, v202, v200
	v_add_f32_e32 v200, v203, v200
	v_fmac_f32_e32 v221, 0x3a800000, v200
	v_mul_f32_e32 v200, 0x4b800000, v221
	v_cmp_gt_f32_e32 vcc, s74, v221
	s_nop 1
	v_cndmask_b32_e32 v221, v221, v200, vcc
	v_rsq_f32_e32 v221, v221
	s_nop 0
	v_mul_f32_e32 v200, 0x45800000, v221
	v_cndmask_b32_e32 v221, v221, v200, vcc
	ds_write_b32 v220, v221

; #define LDA(dst, b, h) for (int m = 0; m < 4; ++m) for (int k = 0; k < 2; ++k) \
;     dst[m][k] = *reinterpret_cast<const bf16x8*>((char*)SA(b, h) + lds_byte(wr * 64 + m * 16 + fr, k * 32 + fq * 8))
; #define LDB(dst, b, h) for (int n = 0; n < 2; ++n) for (int k = 0; k < 2; ++k) \
;     dst[n][k] = *reinterpret_cast<const bf16x8*>((char*)SB(b, h) + lds_byte(wc * 32 + n * 16 + fr, k * 32 + fq * 8))
; #define MMA(ai, bj, At_, Bt_) do { __builtin_amdgcn_s_setprio(1); \
;     for (int m = 0; m < 4; ++m) for (int n = 0; n < 2; ++n) for (int k = 0; k < 2; ++k) \
;       acc[ai][bj][m][n] = MFMA16(Bt_[n][k], At_[m][k], acc[ai][bj][m][n]); \
;     __builtin_amdgcn_s_setprio(0); } while (0)
; #define WAIT_L(n) asm volatile("s_waitcnt lgkmcnt(" #n ")" ::: "memory")
; #define BAR __builtin_amdgcn_s_barrier()
; #define SCHED __builtin_amdgcn_sched_barrier(0)
; template <int PART  , bool SYNC_FIRST = true>
; __device__ __forceinline__ void kloop_t(const u16* __restrict__ A, int lda, const u16* __restrict__ Bt, int ldb, int K, Acc& acc, const int wv) {
;     ...
;     LDB(B0, 0, 0); SCHED; LDA(At, 0, 0); STAGE(SA(1, 1), A, lda, HALF, t + 1);
;     WAIT_L(8); BAR; WAIT_L(0); MMA(0, 0, At, B0); BAR; SCHED;
;     LDB(B1, 0, 1); STAGE(SB(0, 0), Bt, ldb, 0, t + 2);
;     BAR; WAIT_L(0); MMA(0, 1, At, B1); BAR;
;     LDA(At, 0, 1); STAGE(SA(0, 0), A, lda, 0, t + 2);
.LBB0_1069:
	v_add_u32_e32 v158, v150, v154
	v_add_u32_e32 v160, v150, v156
	v_add_u32_e32 v159, v150, v155
	ds_read_b128 v[168:171], v158
	ds_read_b128 v[172:175], v159
	v_add_u32_e32 v161, v150, v157
	ds_read_b128 v[176:179], v160
	ds_read_b128 v[180:183], v161
	s_add_u32 s40, s38, s79
	v_mov_b32_e32 v128, v140
	v_mov_b32_e32 v164, v142
	s_addc_u32 s41, s39, 0
	ds_read_b128 v[184:187], v130
	ds_read_b128 v[188:191], v131
	ds_read_b128 v[192:195], v134
	ds_read_b128 v[196:199], v135
	ds_read_b128 v[200:203], v136
	ds_read_b128 v[204:207], v137
	ds_read_b128 v[208:211], v138
	ds_read_b128 v[212:215], v139
	v_mov_b32_e32 v165, v129
	v_lshl_add_u64 v[162:163], s[40:41], 0, v[128:129]
	v_lshl_add_u64 v[166:167], v[162:163], 0, s[18:19]
	v_add_u32_e32 v162, 0xc000, v145
	v_add_u32_e32 v163, 0xe000, v145
	v_readfirstlane_b32 s42, v162
	s_mov_b32 m0, s42
	v_lshl_add_u64 v[164:165], s[40:41], 0, v[164:165]
	v_readfirstlane_b32 s42, v163
	global_load_lds_dwordx4 v[166:167], off
	v_lshl_add_u64 v[164:165], v[164:165], 0, s[18:19]
	s_mov_b32 m0, s42
	s_nop 0
	global_load_lds_dwordx4 v[164:165], off
	s_waitcnt lgkmcnt(8)
	s_barrier
	s_waitcnt lgkmcnt(0)
	v_mfma_f32_16x16x32_bf16 v[124:127], v[168:171], v[184:187], v[124:127]
	v_mfma_f32_16x16x32_bf16 v[120:123], v[176:179], v[184:187], v[120:123]
	v_mfma_f32_16x16x32_bf16 v[116:119], v[168:171], v[192:195], v[116:119]
	v_mfma_f32_16x16x32_bf16 v[112:115], v[176:179], v[192:195], v[112:115]
	v_mfma_f32_16x16x32_bf16 v[108:111], v[168:171], v[200:203], v[108:111]
	v_mfma_f32_16x16x32_bf16 v[104:107], v[176:179], v[200:203], v[104:107]
	v_mfma_f32_16x16x32_bf16 v[100:103], v[168:171], v[208:211], v[100:103]
	v_mfma_f32_16x16x32_bf16 v[96:99], v[176:179], v[208:211], v[96:99]
	v_mfma_f32_16x16x32_bf16 v[124:127], v[172:175], v[188:191], v[124:127]
	v_mfma_f32_16x16x32_bf16 v[120:123], v[180:183], v[188:191], v[120:123]
	v_mfma_f32_16x16x32_bf16 v[116:119], v[172:175], v[196:199], v[116:119]
	v_mfma_f32_16x16x32_bf16 v[112:115], v[180:183], v[196:199], v[112:115]
	v_mfma_f32_16x16x32_bf16 v[108:111], v[172:175], v[204:207], v[108:111]
	v_mfma_f32_16x16x32_bf16 v[104:107], v[180:183], v[204:207], v[104:107]
	v_mfma_f32_16x16x32_bf16 v[100:103], v[172:175], v[212:215], v[100:103]
	v_mfma_f32_16x16x32_bf16 v[96:99], v[180:183], v[212:215], v[96:99]
	s_barrier
	v_add_u32_e32 v164, v151, v154
	v_add_u32_e32 v166, v151, v156
	v_mov_b32_e32 v128, v140
	v_mov_b32_e32 v232, v142
	s_add_u32 s42, s38, s80
	v_add_u32_e32 v165, v151, v155
	ds_read_b128 v[216:219], v164
	ds_read_b128 v[220:223], v165
	v_add_u32_e32 v167, v151, v157
	ds_read_b128 v[224:227], v166
	ds_read_b128 v[228:231], v167
	s_addc_u32 s43, s39, 0
	v_lshl_add_u64 v[234:235], s[42:43], 0, v[128:129]
	v_add_u32_e32 v128, s54, v141
	v_mov_b32_e32 v233, v129
	v_readfirstlane_b32 s82, v128
	v_add_u32_e32 v128, 0x2000, v128
	v_lshl_add_u64 v[234:235], v[234:235], 0, s[20:21]
	s_mov_b32 m0, s82
	v_lshl_add_u64 v[232:233], s[42:43], 0, v[232:233]
	v_readfirstlane_b32 s82, v128
	global_load_lds_dwordx4 v[234:235], off
	v_lshl_add_u64 v[232:233], v[232:233], 0, s[20:21]
	s_mov_b32 m0, s82
	s_nop 0
	global_load_lds_dwordx4 v[232:233], off
	s_barrier
	s_waitcnt lgkmcnt(0)
	v_mfma_f32_16x16x32_bf16 v[92:95], v[216:219], v[184:187], v[92:95]
	v_mfma_f32_16x16x32_bf16 v[88:91], v[224:227], v[184:187], v[88:91]
	v_mfma_f32_16x16x32_bf16 v[84:87], v[216:219], v[192:195], v[84:87]
	v_mfma_f32_16x16x32_bf16 v[80:83], v[224:227], v[192:195], v[80:83]
	v_mfma_f32_16x16x32_bf16 v[76:79], v[216:219], v[200:203], v[76:79]
	v_mfma_f32_16x16x32_bf16 v[72:75], v[224:227], v[200:203], v[72:75]
	v_mfma_f32_16x16x32_bf16 v[68:71], v[216:219], v[208:211], v[68:71]
	v_mfma_f32_16x16x32_bf16 v[64:67], v[224:227], v[208:211], v[64:67]
	v_mfma_f32_16x16x32_bf16 v[92:95], v[220:223], v[188:191], v[92:95]
	v_mfma_f32_16x16x32_bf16 v[88:91], v[228:231], v[188:191], v[88:91]
	v_mfma_f32_16x16x32_bf16 v[84:87], v[220:223], v[196:199], v[84:87]
	v_mfma_f32_16x16x32_bf16 v[80:83], v[228:231], v[196:199], v[80:83]
	v_mfma_f32_16x16x32_bf16 v[76:79], v[220:223], v[204:207], v[76:79]
	v_mfma_f32_16x16x32_bf16 v[72:75], v[228:231], v[204:207], v[72:75]
	v_mfma_f32_16x16x32_bf16 v[68:71], v[220:223], v[212:215], v[68:71]
	v_mfma_f32_16x16x32_bf16 v[64:67], v[228:231], v[212:215], v[64:67]
	v_mov_b32_e32 v128, v140
	v_mov_b32_e32 v232, v142
	s_barrier
	ds_read_b128 v[184:187], v130 offset:16384
	ds_read_b128 v[188:191], v131 offset:16384
	ds_read_b128 v[192:195], v134 offset:16384
	ds_read_b128 v[196:199], v135 offset:16384
	ds_read_b128 v[200:203], v136 offset:16384
	ds_read_b128 v[204:207], v137 offset:16384
	ds_read_b128 v[208:211], v138 offset:16384
	ds_read_b128 v[212:215], v139 offset:16384
	v_readfirstlane_b32 s82, v145
	v_lshl_add_u64 v[234:235], s[40:41], 0, v[128:129]
	v_mov_b32_e32 v233, v129
	v_add_u32_e32 v128, 0x2000, v145
	v_lshl_add_u64 v[234:235], v[234:235], 0, s[22:23]
	s_mov_b32 m0, s82
	v_lshl_add_u64 v[232:233], s[40:41], 0, v[232:233]
	v_readfirstlane_b32 s82, v128
	global_load_lds_dwordx4 v[234:235], off
	v_lshl_add_u64 v[232:233], v[232:233], 0, s[22:23]
	s_mov_b32 m0, s82
	s_nop 0
	global_load_lds_dwordx4 v[232:233], off
	s_barrier
; #define LDA(dst, b, h) for (int m = 0; m < 4; ++m) for (int k = 0; k < 2; ++k) \
;     dst[m][k] = *reinterpret_cast<const bf16x8*>((char*)SA(b, h) + lds_byte(wr * 64 + m * 16 + fr, k * 32 + fq * 8))
; #define LDB(dst, b, h) for (int n = 0; n < 2; ++n) for (int k = 0; k < 2; ++k) \
;     dst[n][k] = *reinterpret_cast<const bf16x8*>((char*)SB(b, h) + lds_byte(wc * 32 + n * 16 + fr, k * 32 + fq * 8))
; #define MMA(ai, bj, At_, Bt_) do { __builtin_amdgcn_s_setprio(1); \
;     for (int m = 0; m < 4; ++m) for (int n = 0; n < 2; ++n) for (int k = 0; k < 2; ++k) \
;       acc[ai][bj][m][n] = MFMA16(Bt_[n][k], At_[m][k], acc[ai][bj][m][n]); \
;     __builtin_amdgcn_s_setprio(0); } while (0)
; #define WAIT_V(n) asm volatile("s_waitcnt vmcnt(" #n ")" ::: "memory")
; #define WAIT_L(n) asm volatile("s_waitcnt lgkmcnt(" #n ")" ::: "memory")
; #define BAR __builtin_amdgcn_s_barrier()
; #define SCHED __builtin_amdgcn_sched_barrier(0)
; template <int PART  , bool SYNC_FIRST = true>
; __device__ __forceinline__ void kloop_t(const u16* __restrict__ A, int lda, const u16* __restrict__ Bt, int ldb, int K, Acc& acc, const int wv) {
;     ...
;     BAR; WAIT_L(0); MMA(1, 0, At, B0); BAR; SCHED;
;     STAGE(SB(0, 1), Bt, ldb, HALF, t + 2);
;     WAIT_V(6); BAR; MMA(1, 1, At, B1); BAR;
;     LDB(B0, 1, 0); SCHED; LDA(At, 1, 0); STAGE(SA(0, 1), A, lda, HALF, t + 2);
;     WAIT_L(8); BAR; WAIT_L(0); MMA(0, 0, At, B0); BAR; SCHED;
;     LDB(B1, 1, 1); STAGE(SB(1, 0), Bt, ldb, 0, t + 3);
	s_waitcnt lgkmcnt(0)
	v_mfma_f32_16x16x32_bf16 v[60:63], v[168:171], v[184:187], v[60:63]
	v_mfma_f32_16x16x32_bf16 v[56:59], v[176:179], v[184:187], v[56:59]
	v_mfma_f32_16x16x32_bf16 v[52:55], v[168:171], v[192:195], v[52:55]
	v_mfma_f32_16x16x32_bf16 v[48:51], v[176:179], v[192:195], v[48:51]
	v_mfma_f32_16x16x32_bf16 v[44:47], v[168:171], v[200:203], v[44:47]
	v_mfma_f32_16x16x32_bf16 v[40:43], v[176:179], v[200:203], v[40:43]
	v_mfma_f32_16x16x32_bf16 v[36:39], v[168:171], v[208:211], v[36:39]
	v_mfma_f32_16x16x32_bf16 v[32:35], v[176:179], v[208:211], v[32:35]
	v_mfma_f32_16x16x32_bf16 v[60:63], v[172:175], v[188:191], v[60:63]
	v_mfma_f32_16x16x32_bf16 v[56:59], v[180:183], v[188:191], v[56:59]
	v_mfma_f32_16x16x32_bf16 v[52:55], v[172:175], v[196:199], v[52:55]
	v_mfma_f32_16x16x32_bf16 v[48:51], v[180:183], v[196:199], v[48:51]
	v_mfma_f32_16x16x32_bf16 v[44:47], v[172:175], v[204:207], v[44:47]
	v_mfma_f32_16x16x32_bf16 v[40:43], v[180:183], v[204:207], v[40:43]
	v_mfma_f32_16x16x32_bf16 v[36:39], v[172:175], v[212:215], v[36:39]
	v_mfma_f32_16x16x32_bf16 v[32:35], v[180:183], v[212:215], v[32:35]
	s_barrier
	v_mov_b32_e32 v128, v140
	v_mov_b32_e32 v168, v142
	v_mov_b32_e32 v169, v129
	v_lshl_add_u64 v[170:171], s[42:43], 0, v[128:129]
	v_add_u32_e32 v128, s55, v141
	v_lshl_add_u64 v[170:171], v[170:171], 0, s[24:25]
	v_readfirstlane_b32 s82, v128
	v_add_u32_e32 v128, 0x2000, v128
	s_mov_b32 m0, s82
	v_lshl_add_u64 v[168:169], s[42:43], 0, v[168:169]
	v_readfirstlane_b32 s82, v128
	global_load_lds_dwordx4 v[170:171], off
	v_lshl_add_u64 v[168:169], v[168:169], 0, s[24:25]
	s_mov_b32 m0, s82
	s_nop 0
	global_load_lds_dwordx4 v[168:169], off
	s_waitcnt vmcnt(6)
	s_barrier
	v_mfma_f32_16x16x32_bf16 v[28:31], v[216:219], v[184:187], v[28:31]
	v_mfma_f32_16x16x32_bf16 v[24:27], v[224:227], v[184:187], v[24:27]
	v_mfma_f32_16x16x32_bf16 v[20:23], v[216:219], v[192:195], v[20:23]
	v_mfma_f32_16x16x32_bf16 v[16:19], v[224:227], v[192:195], v[16:19]
	v_mfma_f32_16x16x32_bf16 v[12:15], v[216:219], v[200:203], v[12:15]
	v_mfma_f32_16x16x32_bf16 v[8:11], v[224:227], v[200:203], v[8:11]
	v_mfma_f32_16x16x32_bf16 v[4:7], v[216:219], v[208:211], v[4:7]
	v_mfma_f32_16x16x32_bf16 v[0:3], v[224:227], v[208:211], v[0:3]
	v_mfma_f32_16x16x32_bf16 v[28:31], v[220:223], v[188:191], v[28:31]
	v_mfma_f32_16x16x32_bf16 v[24:27], v[228:231], v[188:191], v[24:27]
	v_mfma_f32_16x16x32_bf16 v[20:23], v[220:223], v[196:199], v[20:23]
	v_mfma_f32_16x16x32_bf16 v[16:19], v[228:231], v[196:199], v[16:19]
	v_mfma_f32_16x16x32_bf16 v[12:15], v[220:223], v[204:207], v[12:15]
	v_mfma_f32_16x16x32_bf16 v[8:11], v[228:231], v[204:207], v[8:11]
	v_mfma_f32_16x16x32_bf16 v[4:7], v[220:223], v[212:215], v[4:7]
	v_mfma_f32_16x16x32_bf16 v[0:3], v[228:231], v[212:215], v[0:3]
	v_add_u32_e32 v168, v152, v154
	v_add_u32_e32 v170, v152, v156
	s_barrier
	v_add_u32_e32 v169, v152, v155
	ds_read_b128 v[176:179], v168
	ds_read_b128 v[180:183], v169
	v_add_u32_e32 v171, v152, v157
	ds_read_b128 v[184:187], v170
	ds_read_b128 v[188:191], v171
	v_mov_b32_e32 v128, v140
	v_mov_b32_e32 v172, v142
	ds_read_b128 v[192:195], v130 offset:32768
	ds_read_b128 v[196:199], v131 offset:32768
	ds_read_b128 v[200:203], v134 offset:32768
	ds_read_b128 v[204:207], v135 offset:32768
	ds_read_b128 v[208:211], v136 offset:32768
	ds_read_b128 v[212:215], v137 offset:32768
	ds_read_b128 v[216:219], v138 offset:32768
	ds_read_b128 v[220:223], v139 offset:32768
	v_mov_b32_e32 v173, v129
	v_lshl_add_u64 v[174:175], s[40:41], 0, v[128:129]
	v_add_u32_e32 v128, 0x4000, v145
	v_lshl_add_u64 v[174:175], v[174:175], 0, s[26:27]
	v_readfirstlane_b32 s82, v128
	v_add_u32_e32 v128, 0x6000, v145
	s_mov_b32 m0, s82
	v_lshl_add_u64 v[172:173], s[40:41], 0, v[172:173]
	v_readfirstlane_b32 s82, v128
	global_load_lds_dwordx4 v[174:175], off
	v_lshl_add_u64 v[172:173], v[172:173], 0, s[26:27]
	s_mov_b32 m0, s82
	s_nop 0
	global_load_lds_dwordx4 v[172:173], off
	s_waitcnt lgkmcnt(8)
	s_barrier
	s_waitcnt lgkmcnt(0)
	v_mfma_f32_16x16x32_bf16 v[124:127], v[176:179], v[192:195], v[124:127]
	v_mfma_f32_16x16x32_bf16 v[120:123], v[184:187], v[192:195], v[120:123]
	v_mfma_f32_16x16x32_bf16 v[116:119], v[176:179], v[200:203], v[116:119]
	v_mfma_f32_16x16x32_bf16 v[112:115], v[184:187], v[200:203], v[112:115]
	v_mfma_f32_16x16x32_bf16 v[108:111], v[176:179], v[208:211], v[108:111]
	v_mfma_f32_16x16x32_bf16 v[104:107], v[184:187], v[208:211], v[104:107]
	v_mfma_f32_16x16x32_bf16 v[100:103], v[176:179], v[216:219], v[100:103]
	v_mfma_f32_16x16x32_bf16 v[96:99], v[184:187], v[216:219], v[96:99]
	v_mfma_f32_16x16x32_bf16 v[124:127], v[180:183], v[196:199], v[124:127]
	v_mfma_f32_16x16x32_bf16 v[120:123], v[188:191], v[196:199], v[120:123]
	v_mfma_f32_16x16x32_bf16 v[116:119], v[180:183], v[204:207], v[116:119]
	v_mfma_f32_16x16x32_bf16 v[112:115], v[188:191], v[204:207], v[112:115]
	v_mfma_f32_16x16x32_bf16 v[108:111], v[180:183], v[212:215], v[108:111]
	v_mfma_f32_16x16x32_bf16 v[104:107], v[188:191], v[212:215], v[104:107]
	v_mfma_f32_16x16x32_bf16 v[100:103], v[180:183], v[220:223], v[100:103]
	v_mfma_f32_16x16x32_bf16 v[96:99], v[188:191], v[220:223], v[96:99]
	s_barrier
	v_add_u32_e32 v172, v153, v154
	v_add_u32_e32 v174, v153, v156
	v_mov_b32_e32 v128, v140
	v_mov_b32_e32 v240, v142
	v_add_u32_e32 v173, v153, v155
	ds_read_b128 v[224:227], v172
	ds_read_b128 v[228:231], v173
	v_add_u32_e32 v175, v153, v157
	ds_read_b128 v[232:235], v174
	ds_read_b128 v[236:239], v175
	v_readfirstlane_b32 s82, v143
	v_lshl_add_u64 v[242:243], s[42:43], 0, v[128:129]
	v_mov_b32_e32 v241, v129
	v_lshl_add_u64 v[242:243], v[242:243], 0, s[28:29]
	s_mov_b32 m0, s82
	v_lshl_add_u64 v[240:241], s[42:43], 0, v[240:241]
	v_readfirstlane_b32 s82, v144
	global_load_lds_dwordx4 v[242:243], off
	v_lshl_add_u64 v[240:241], v[240:241], 0, s[28:29]
	s_mov_b32 m0, s82
	s_nop 0
	global_load_lds_dwordx4 v[240:241], off
	s_barrier
; #define LDA(dst, b, h) for (int m = 0; m < 4; ++m) for (int k = 0; k < 2; ++k) \
;     dst[m][k] = *reinterpret_cast<const bf16x8*>((char*)SA(b, h) + lds_byte(wr * 64 + m * 16 + fr, k * 32 + fq * 8))
; #define LDB(dst, b, h) for (int n = 0; n < 2; ++n) for (int k = 0; k < 2; ++k) \
;     dst[n][k] = *reinterpret_cast<const bf16x8*>((char*)SB(b, h) + lds_byte(wc * 32 + n * 16 + fr, k * 32 + fq * 8))
; #define MMA(ai, bj, At_, Bt_) do { __builtin_amdgcn_s_setprio(1); \
;     for (int m = 0; m < 4; ++m) for (int n = 0; n < 2; ++n) for (int k = 0; k < 2; ++k) \
;       acc[ai][bj][m][n] = MFMA16(Bt_[n][k], At_[m][k], acc[ai][bj][m][n]); \
;     __builtin_amdgcn_s_setprio(0); } while (0)
; #define WAIT_V(n) asm volatile("s_waitcnt vmcnt(" #n ")" ::: "memory")
; #define WAIT_L(n) asm volatile("s_waitcnt lgkmcnt(" #n ")" ::: "memory")
; #define BAR __builtin_amdgcn_s_barrier()
; #define SCHED __builtin_amdgcn_sched_barrier(0)
; template <int PART  , bool SYNC_FIRST = true>
; __device__ __forceinline__ void kloop_t(const u16* __restrict__ A, int lda, const u16* __restrict__ Bt, int ldb, int K, Acc& acc, const int wv) {
;     ...
;     BAR; WAIT_L(0); MMA(0, 1, At, B1); BAR;
;     LDA(At, 1, 1); STAGE(SA(1, 0), A, lda, 0, t + 3);
;     BAR; WAIT_L(0); MMA(1, 0, At, B0); BAR; SCHED;
;     STAGE(SB(1, 1), Bt, ldb, HALF, t + 3);
;     WAIT_V(6); BAR; MMA(1, 1, At, B1); BAR;
;   }
;   { LDB(B0, 0, 0); LDA(At, 0, 0); STAGE(SA(1, 1), A, lda, HALF, nt - 1);
	s_waitcnt lgkmcnt(0)
	v_mfma_f32_16x16x32_bf16 v[92:95], v[224:227], v[192:195], v[92:95]
	v_mfma_f32_16x16x32_bf16 v[88:91], v[232:235], v[192:195], v[88:91]
	v_mfma_f32_16x16x32_bf16 v[84:87], v[224:227], v[200:203], v[84:87]
	v_mfma_f32_16x16x32_bf16 v[80:83], v[232:235], v[200:203], v[80:83]
	v_mfma_f32_16x16x32_bf16 v[76:79], v[224:227], v[208:211], v[76:79]
	v_mfma_f32_16x16x32_bf16 v[72:75], v[232:235], v[208:211], v[72:75]
	v_mfma_f32_16x16x32_bf16 v[68:71], v[224:227], v[216:219], v[68:71]
	v_mfma_f32_16x16x32_bf16 v[64:67], v[232:235], v[216:219], v[64:67]
	v_mfma_f32_16x16x32_bf16 v[92:95], v[228:231], v[196:199], v[92:95]
	v_mfma_f32_16x16x32_bf16 v[88:91], v[236:239], v[196:199], v[88:91]
	v_mfma_f32_16x16x32_bf16 v[84:87], v[228:231], v[204:207], v[84:87]
	v_mfma_f32_16x16x32_bf16 v[80:83], v[236:239], v[204:207], v[80:83]
	v_mfma_f32_16x16x32_bf16 v[76:79], v[228:231], v[212:215], v[76:79]
	v_mfma_f32_16x16x32_bf16 v[72:75], v[236:239], v[212:215], v[72:75]
	v_mfma_f32_16x16x32_bf16 v[68:71], v[228:231], v[220:223], v[68:71]
	v_mfma_f32_16x16x32_bf16 v[64:67], v[236:239], v[220:223], v[64:67]
	v_mov_b32_e32 v128, v140
	v_mov_b32_e32 v240, v142
	s_barrier
	ds_read_b128 v[192:195], v130 offset:49152
	ds_read_b128 v[196:199], v131 offset:49152
	ds_read_b128 v[200:203], v134 offset:49152
	ds_read_b128 v[204:207], v135 offset:49152
	ds_read_b128 v[208:211], v136 offset:49152
	ds_read_b128 v[212:215], v137 offset:49152
	ds_read_b128 v[216:219], v138 offset:49152
	ds_read_b128 v[220:223], v139 offset:49152
	v_readfirstlane_b32 s82, v146
	v_lshl_add_u64 v[242:243], s[40:41], 0, v[128:129]
	v_mov_b32_e32 v241, v129
	v_lshl_add_u64 v[242:243], v[242:243], 0, s[30:31]
	s_mov_b32 m0, s82
	v_lshl_add_u64 v[240:241], s[40:41], 0, v[240:241]
	v_readfirstlane_b32 s40, v147
	global_load_lds_dwordx4 v[242:243], off
	v_lshl_add_u64 v[240:241], v[240:241], 0, s[30:31]
	s_mov_b32 m0, s40
	s_nop 0
	global_load_lds_dwordx4 v[240:241], off
	s_barrier
	s_waitcnt lgkmcnt(0)
	v_mfma_f32_16x16x32_bf16 v[60:63], v[176:179], v[192:195], v[60:63]
	v_mfma_f32_16x16x32_bf16 v[56:59], v[184:187], v[192:195], v[56:59]
	v_mfma_f32_16x16x32_bf16 v[52:55], v[176:179], v[200:203], v[52:55]
	v_mfma_f32_16x16x32_bf16 v[48:51], v[184:187], v[200:203], v[48:51]
	v_mfma_f32_16x16x32_bf16 v[44:47], v[176:179], v[208:211], v[44:47]
	v_mfma_f32_16x16x32_bf16 v[40:43], v[184:187], v[208:211], v[40:43]
	v_mfma_f32_16x16x32_bf16 v[36:39], v[176:179], v[216:219], v[36:39]
	v_mfma_f32_16x16x32_bf16 v[32:35], v[184:187], v[216:219], v[32:35]
	v_mfma_f32_16x16x32_bf16 v[60:63], v[180:183], v[196:199], v[60:63]
	v_mfma_f32_16x16x32_bf16 v[56:59], v[188:191], v[196:199], v[56:59]
	v_mfma_f32_16x16x32_bf16 v[52:55], v[180:183], v[204:207], v[52:55]
	v_mfma_f32_16x16x32_bf16 v[48:51], v[188:191], v[204:207], v[48:51]
	v_mfma_f32_16x16x32_bf16 v[44:47], v[180:183], v[212:215], v[44:47]
	v_mfma_f32_16x16x32_bf16 v[40:43], v[188:191], v[212:215], v[40:43]
	v_mfma_f32_16x16x32_bf16 v[36:39], v[180:183], v[220:223], v[36:39]
	v_mfma_f32_16x16x32_bf16 v[32:35], v[188:191], v[220:223], v[32:35]
	s_barrier
	v_mov_b32_e32 v128, v140
	v_mov_b32_e32 v176, v142
	v_readfirstlane_b32 s40, v148
	v_lshl_add_u64 v[178:179], s[42:43], 0, v[128:129]
	v_mov_b32_e32 v177, v129
	v_lshl_add_u64 v[178:179], v[178:179], 0, s[34:35]
	s_mov_b32 m0, s40
	v_lshl_add_u64 v[176:177], s[42:43], 0, v[176:177]
	v_readfirstlane_b32 s40, v149
	global_load_lds_dwordx4 v[178:179], off
	v_lshl_add_u64 v[176:177], v[176:177], 0, s[34:35]
	s_mov_b32 m0, s40
	s_nop 0
	global_load_lds_dwordx4 v[176:177], off
	s_waitcnt vmcnt(6)
	s_barrier
	v_mfma_f32_16x16x32_bf16 v[28:31], v[224:227], v[192:195], v[28:31]
	v_mfma_f32_16x16x32_bf16 v[24:27], v[232:235], v[192:195], v[24:27]
	v_mfma_f32_16x16x32_bf16 v[20:23], v[224:227], v[200:203], v[20:23]
	v_mfma_f32_16x16x32_bf16 v[16:19], v[232:235], v[200:203], v[16:19]
	v_mfma_f32_16x16x32_bf16 v[12:15], v[224:227], v[208:211], v[12:15]
	v_mfma_f32_16x16x32_bf16 v[8:11], v[232:235], v[208:211], v[8:11]
	v_mfma_f32_16x16x32_bf16 v[4:7], v[224:227], v[216:219], v[4:7]
	v_mfma_f32_16x16x32_bf16 v[0:3], v[232:235], v[216:219], v[0:3]
	v_mfma_f32_16x16x32_bf16 v[28:31], v[228:231], v[196:199], v[28:31]
	v_mfma_f32_16x16x32_bf16 v[24:27], v[236:239], v[196:199], v[24:27]
	v_mfma_f32_16x16x32_bf16 v[20:23], v[228:231], v[204:207], v[20:23]
	v_mfma_f32_16x16x32_bf16 v[16:19], v[236:239], v[204:207], v[16:19]
	v_mfma_f32_16x16x32_bf16 v[12:15], v[228:231], v[212:215], v[12:15]
	v_mfma_f32_16x16x32_bf16 v[8:11], v[236:239], v[212:215], v[8:11]
	v_mfma_f32_16x16x32_bf16 v[4:7], v[228:231], v[220:223], v[4:7]
	v_mfma_f32_16x16x32_bf16 v[0:3], v[236:239], v[220:223], v[0:3]
	s_add_i32 s81, s81, 2
	s_add_u32 s38, s38, 0x100
	s_addc_u32 s39, s39, 0
	s_cmp_lt_u32 s81, 12
	s_barrier
	s_cbranch_scc1 .LBB0_1069
	s_add_u32 s36, s36, 0x40780
	v_readfirstlane_b32 s38, v162
	s_addc_u32 s37, s37, 0
	s_mov_b32 m0, s38
	v_readfirstlane_b32 s38, v163
	ds_read_b128 v[144:147], v158
	ds_read_b128 v[148:151], v159
	ds_read_b128 v[152:155], v160
	ds_read_b128 v[156:159], v161
	ds_read_b128 v[176:179], v130
	ds_read_b128 v[180:183], v131
	ds_read_b128 v[184:187], v134
	ds_read_b128 v[188:191], v135
	ds_read_b128 v[192:195], v136
	ds_read_b128 v[196:199], v137
	ds_read_b128 v[200:203], v138
	ds_read_b128 v[204:207], v139
	s_nop 0
	global_load_lds_dwordx4 v140, s[36:37]
	s_mov_b32 m0, s38
	s_nop 0
	global_load_lds_dwordx4 v142, s[36:37]
	s_barrier
; #define LDA(dst, b, h) for (int m = 0; m < 4; ++m) for (int k = 0; k < 2; ++k) \
;     dst[m][k] = *reinterpret_cast<const bf16x8*>((char*)SA(b, h) + lds_byte(wr * 64 + m * 16 + fr, k * 32 + fq * 8))
; #define LDB(dst, b, h) for (int n = 0; n < 2; ++n) for (int k = 0; k < 2; ++k) \
;     dst[n][k] = *reinterpret_cast<const bf16x8*>((char*)SB(b, h) + lds_byte(wc * 32 + n * 16 + fr, k * 32 + fq * 8))
; #define MMA(ai, bj, At_, Bt_) do { __builtin_amdgcn_s_setprio(1); \
;     for (int m = 0; m < 4; ++m) for (int n = 0; n < 2; ++n) for (int k = 0; k < 2; ++k) \
;       acc[ai][bj][m][n] = MFMA16(Bt_[n][k], At_[m][k], acc[ai][bj][m][n]); \
;     __builtin_amdgcn_s_setprio(0); } while (0)
; #define WAIT_V(n) asm volatile("s_waitcnt vmcnt(" #n ")" ::: "memory")
; #define WAIT_L(n) asm volatile("s_waitcnt lgkmcnt(" #n ")" ::: "memory")
; #define BAR __builtin_amdgcn_s_barrier()
; template <int PART  , bool SYNC_FIRST = true>
; __device__ __forceinline__ void kloop_t(const u16* __restrict__ A, int lda, const u16* __restrict__ Bt, int ldb, int K, Acc& acc, const int wv) {
;     ...
;     BAR; WAIT_L(0); MMA(0, 0, At, B0); BAR;
;     LDB(B1, 0, 1); BAR; WAIT_L(0); MMA(0, 1, At, B1); BAR;
;     LDA(At, 0, 1); WAIT_V(4); BAR; WAIT_L(0); MMA(1, 0, At, B0); MMA(1, 1, At, B1); BAR; }
	s_waitcnt lgkmcnt(0)
	v_mfma_f32_16x16x32_bf16 v[124:127], v[144:147], v[176:179], v[124:127]
	v_mfma_f32_16x16x32_bf16 v[120:123], v[152:155], v[176:179], v[120:123]
	v_mfma_f32_16x16x32_bf16 v[116:119], v[144:147], v[184:187], v[116:119]
	v_mfma_f32_16x16x32_bf16 v[112:115], v[152:155], v[184:187], v[112:115]
	v_mfma_f32_16x16x32_bf16 v[100:103], v[144:147], v[200:203], v[100:103]
	v_mfma_f32_16x16x32_bf16 v[96:99], v[152:155], v[200:203], v[96:99]
	v_mfma_f32_16x16x32_bf16 v[124:127], v[148:151], v[180:183], v[124:127]
	v_mfma_f32_16x16x32_bf16 v[120:123], v[156:159], v[180:183], v[120:123]
	v_mfma_f32_16x16x32_bf16 v[116:119], v[148:151], v[188:191], v[116:119]
	v_mfma_f32_16x16x32_bf16 v[112:115], v[156:159], v[188:191], v[112:115]
	v_mfma_f32_16x16x32_bf16 v[108:111], v[144:147], v[192:195], v[108:111]
	v_mfma_f32_16x16x32_bf16 v[104:107], v[152:155], v[192:195], v[104:107]
	v_mfma_f32_16x16x32_bf16 v[100:103], v[148:151], v[204:207], v[100:103]
	v_mfma_f32_16x16x32_bf16 v[96:99], v[156:159], v[204:207], v[96:99]
	v_mfma_f32_16x16x32_bf16 v[140:143], v[148:151], v[196:199], v[108:111]
	v_mfma_f32_16x16x32_bf16 v[160:163], v[156:159], v[196:199], v[104:107]
	s_barrier
	s_nop 1
	ds_read_b128 v[104:107], v164
	ds_read_b128 v[108:111], v165
	ds_read_b128 v[208:211], v166
	ds_read_b128 v[164:167], v167
	s_barrier
	s_waitcnt lgkmcnt(0)
	v_mfma_f32_16x16x32_bf16 v[84:87], v[104:107], v[184:187], v[84:87]
	v_mfma_f32_16x16x32_bf16 v[80:83], v[208:211], v[184:187], v[80:83]
	v_mfma_f32_16x16x32_bf16 v[68:71], v[104:107], v[200:203], v[68:71]
	v_mfma_f32_16x16x32_bf16 v[64:67], v[208:211], v[200:203], v[64:67]
	v_mfma_f32_16x16x32_bf16 v[92:95], v[104:107], v[176:179], v[92:95]
	v_mfma_f32_16x16x32_bf16 v[88:91], v[208:211], v[176:179], v[88:91]
	v_mfma_f32_16x16x32_bf16 v[84:87], v[108:111], v[188:191], v[84:87]
	v_mfma_f32_16x16x32_bf16 v[80:83], v[164:167], v[188:191], v[80:83]
	v_mfma_f32_16x16x32_bf16 v[76:79], v[104:107], v[192:195], v[76:79]
	v_mfma_f32_16x16x32_bf16 v[72:75], v[208:211], v[192:195], v[72:75]
	v_mfma_f32_16x16x32_bf16 v[68:71], v[108:111], v[204:207], v[68:71]
	v_mfma_f32_16x16x32_bf16 v[64:67], v[164:167], v[204:207], v[64:67]
	v_mfma_f32_16x16x32_bf16 v[212:215], v[108:111], v[180:183], v[92:95]
	v_mfma_f32_16x16x32_bf16 v[176:179], v[164:167], v[180:183], v[88:91]
	v_mfma_f32_16x16x32_bf16 v[180:183], v[108:111], v[196:199], v[76:79]
	v_mfma_f32_16x16x32_bf16 v[184:187], v[164:167], v[196:199], v[72:75]
	s_barrier
	s_nop 0
	ds_read_b128 v[72:75], v130 offset:16384
	ds_read_b128 v[76:79], v131 offset:16384
	ds_read_b128 v[88:91], v134 offset:16384
	ds_read_b128 v[92:95], v135 offset:16384
	ds_read_b128 v[188:191], v136 offset:16384
	ds_read_b128 v[192:195], v137 offset:16384
	ds_read_b128 v[196:199], v138 offset:16384
	ds_read_b128 v[200:203], v139 offset:16384
	s_waitcnt vmcnt(4)
	s_barrier
	s_waitcnt lgkmcnt(0)
	v_mfma_f32_16x16x32_bf16 v[60:63], v[144:147], v[72:75], v[60:63]
	v_mfma_f32_16x16x32_bf16 v[56:59], v[152:155], v[72:75], v[56:59]
	v_mfma_f32_16x16x32_bf16 v[52:55], v[144:147], v[88:91], v[52:55]
	v_mfma_f32_16x16x32_bf16 v[48:51], v[152:155], v[88:91], v[48:51]
	v_mfma_f32_16x16x32_bf16 v[36:39], v[144:147], v[196:199], v[36:39]
	v_mfma_f32_16x16x32_bf16 v[32:35], v[152:155], v[196:199], v[32:35]
	v_mfma_f32_16x16x32_bf16 v[60:63], v[148:151], v[76:79], v[60:63]
	v_mfma_f32_16x16x32_bf16 v[56:59], v[156:159], v[76:79], v[56:59]
	v_mfma_f32_16x16x32_bf16 v[52:55], v[148:151], v[92:95], v[52:55]
	v_mfma_f32_16x16x32_bf16 v[48:51], v[156:159], v[92:95], v[48:51]
	v_mfma_f32_16x16x32_bf16 v[44:47], v[144:147], v[188:191], v[44:47]
	v_mfma_f32_16x16x32_bf16 v[40:43], v[152:155], v[188:191], v[40:43]
	v_mfma_f32_16x16x32_bf16 v[36:39], v[148:151], v[200:203], v[36:39]
	v_mfma_f32_16x16x32_bf16 v[32:35], v[156:159], v[200:203], v[32:35]
	v_mfma_f32_16x16x32_bf16 v[204:207], v[148:151], v[192:195], v[44:47]
	v_mfma_f32_16x16x32_bf16 v[216:219], v[156:159], v[192:195], v[40:43]
	v_mfma_f32_16x16x32_bf16 v[20:23], v[104:107], v[88:91], v[20:23]
	v_mfma_f32_16x16x32_bf16 v[16:19], v[208:211], v[88:91], v[16:19]
	v_mfma_f32_16x16x32_bf16 v[4:7], v[104:107], v[196:199], v[4:7]
	v_mfma_f32_16x16x32_bf16 v[0:3], v[208:211], v[196:199], v[0:3]
	v_mfma_f32_16x16x32_bf16 v[28:31], v[104:107], v[72:75], v[28:31]
	v_mfma_f32_16x16x32_bf16 v[24:27], v[208:211], v[72:75], v[24:27]
	v_mfma_f32_16x16x32_bf16 v[20:23], v[108:111], v[92:95], v[20:23]
	v_mfma_f32_16x16x32_bf16 v[16:19], v[164:167], v[92:95], v[16:19]
	v_mfma_f32_16x16x32_bf16 v[12:15], v[104:107], v[188:191], v[12:15]
	v_mfma_f32_16x16x32_bf16 v[8:11], v[208:211], v[188:191], v[8:11]
	v_mfma_f32_16x16x32_bf16 v[4:7], v[108:111], v[200:203], v[4:7]
	v_mfma_f32_16x16x32_bf16 v[0:3], v[164:167], v[200:203], v[0:3]
	v_mfma_f32_16x16x32_bf16 v[144:147], v[108:111], v[76:79], v[28:31]
	v_mfma_f32_16x16x32_bf16 v[148:151], v[164:167], v[76:79], v[24:27]
	v_mfma_f32_16x16x32_bf16 v[152:155], v[108:111], v[192:195], v[12:15]
	v_mfma_f32_16x16x32_bf16 v[156:159], v[164:167], v[192:195], v[8:11]
	s_barrier
; #define LDA(dst, b, h) for (int m = 0; m < 4; ++m) for (int k = 0; k < 2; ++k) \
;     dst[m][k] = *reinterpret_cast<const bf16x8*>((char*)SA(b, h) + lds_byte(wr * 64 + m * 16 + fr, k * 32 + fq * 8))
; #define LDB(dst, b, h) for (int n = 0; n < 2; ++n) for (int k = 0; k < 2; ++k) \
;     dst[n][k] = *reinterpret_cast<const bf16x8*>((char*)SB(b, h) + lds_byte(wc * 32 + n * 16 + fr, k * 32 + fq * 8))
; #define MMA(ai, bj, At_, Bt_) do { __builtin_amdgcn_s_setprio(1); \
;     for (int m = 0; m < 4; ++m) for (int n = 0; n < 2; ++n) for (int k = 0; k < 2; ++k) \
;       acc[ai][bj][m][n] = MFMA16(Bt_[n][k], At_[m][k], acc[ai][bj][m][n]); \
;     __builtin_amdgcn_s_setprio(0); } while (0)
; #define WAIT_V(n) asm volatile("s_waitcnt vmcnt(" #n ")" ::: "memory")
; #define WAIT_L(n) asm volatile("s_waitcnt lgkmcnt(" #n ")" ::: "memory")
; #define BAR __builtin_amdgcn_s_barrier()
; template <int PART  , bool SYNC_FIRST = true>
; __device__ __forceinline__ void kloop_t(const u16* __restrict__ A, int lda, const u16* __restrict__ Bt, int ldb, int K, Acc& acc, const int wv) {
;     ...
;   { LDB(B0, 1, 0); LDA(At, 1, 0); WAIT_V(2); BAR; WAIT_L(0); MMA(0, 0, At, B0); BAR;
;     LDB(B1, 1, 1); WAIT_V(0); BAR; WAIT_L(0); MMA(0, 1, At, B1); BAR;
;     LDA(At, 1, 1); BAR; WAIT_L(0); MMA(1, 0, At, B0); MMA(1, 1, At, B1); BAR; }
;   if (wr == 0) BAR;
	s_nop 0
	ds_read_b128 v[8:11], v168
	ds_read_b128 v[12:15], v169
	ds_read_b128 v[164:167], v170
	ds_read_b128 v[168:171], v171
	ds_read_b128 v[24:27], v130 offset:32768
	ds_read_b128 v[28:31], v131 offset:32768
	ds_read_b128 v[40:43], v134 offset:32768
	ds_read_b128 v[44:47], v135 offset:32768
	ds_read_b128 v[188:191], v136 offset:32768
	ds_read_b128 v[192:195], v137 offset:32768
	ds_read_b128 v[196:199], v138 offset:32768
	ds_read_b128 v[200:203], v139 offset:32768
	s_waitcnt vmcnt(2)
	s_barrier
	s_waitcnt lgkmcnt(0)
	v_mfma_f32_16x16x32_bf16 v[72:75], v[8:11], v[24:27], v[124:127]
	v_mfma_f32_16x16x32_bf16 v[124:127], v[12:15], v[28:31], v[72:75]
	v_mfma_f32_16x16x32_bf16 v[72:75], v[164:167], v[24:27], v[120:123]
	v_mfma_f32_16x16x32_bf16 v[120:123], v[168:171], v[28:31], v[72:75]
	v_mfma_f32_16x16x32_bf16 v[72:75], v[8:11], v[40:43], v[116:119]
	v_mfma_f32_16x16x32_bf16 v[108:111], v[12:15], v[44:47], v[72:75]
	v_mfma_f32_16x16x32_bf16 v[72:75], v[164:167], v[40:43], v[112:115]
	v_mfma_f32_16x16x32_bf16 v[104:107], v[168:171], v[44:47], v[72:75]
	v_mfma_f32_16x16x32_bf16 v[72:75], v[8:11], v[188:191], v[140:143]
	v_mfma_f32_16x16x32_bf16 v[92:95], v[12:15], v[192:195], v[72:75]
	v_mfma_f32_16x16x32_bf16 v[72:75], v[164:167], v[188:191], v[160:163]
	v_mfma_f32_16x16x32_bf16 v[88:91], v[168:171], v[192:195], v[72:75]
	v_mfma_f32_16x16x32_bf16 v[72:75], v[8:11], v[196:199], v[100:103]
	v_mfma_f32_16x16x32_bf16 v[76:79], v[12:15], v[200:203], v[72:75]
	v_mfma_f32_16x16x32_bf16 v[72:75], v[164:167], v[196:199], v[96:99]
	v_mfma_f32_16x16x32_bf16 v[72:75], v[168:171], v[200:203], v[72:75]
	s_barrier
	ds_read_b128 v[140:143], v172
	ds_read_b128 v[160:163], v173
	ds_read_b128 v[208:211], v174
	ds_read_b128 v[172:175], v175
	s_waitcnt vmcnt(0)
	s_barrier
	s_waitcnt lgkmcnt(0)
	v_mfma_f32_16x16x32_bf16 v[96:99], v[140:143], v[24:27], v[212:215]
	v_mfma_f32_16x16x32_bf16 v[24:27], v[208:211], v[24:27], v[176:179]
	v_mfma_f32_16x16x32_bf16 v[112:115], v[172:175], v[28:31], v[24:27]
	v_mfma_f32_16x16x32_bf16 v[24:27], v[140:143], v[40:43], v[84:87]
	v_mfma_f32_16x16x32_bf16 v[100:103], v[160:163], v[44:47], v[24:27]
	v_mfma_f32_16x16x32_bf16 v[24:27], v[208:211], v[40:43], v[80:83]
	v_mfma_f32_16x16x32_bf16 v[116:119], v[160:163], v[28:31], v[96:99]
	v_mfma_f32_16x16x32_bf16 v[96:99], v[172:175], v[44:47], v[24:27]
	v_mfma_f32_16x16x32_bf16 v[24:27], v[140:143], v[188:191], v[180:183]
	v_mfma_f32_16x16x32_bf16 v[84:87], v[160:163], v[192:195], v[24:27]
	v_mfma_f32_16x16x32_bf16 v[24:27], v[208:211], v[188:191], v[184:187]
	v_mfma_f32_16x16x32_bf16 v[80:83], v[172:175], v[192:195], v[24:27]
	v_mfma_f32_16x16x32_bf16 v[24:27], v[140:143], v[196:199], v[68:71]
	v_mfma_f32_16x16x32_bf16 v[68:71], v[160:163], v[200:203], v[24:27]
	v_mfma_f32_16x16x32_bf16 v[24:27], v[208:211], v[196:199], v[64:67]
	v_mfma_f32_16x16x32_bf16 v[64:67], v[172:175], v[200:203], v[24:27]
	s_barrier
	ds_read_b128 v[176:179], v130 offset:49152
	ds_read_b128 v[180:183], v131 offset:49152
	ds_read_b128 v[184:187], v134 offset:49152
	ds_read_b128 v[188:191], v135 offset:49152
	ds_read_b128 v[192:195], v136 offset:49152
	ds_read_b128 v[134:137], v137 offset:49152
	ds_read_b128 v[196:199], v138 offset:49152
	ds_read_b128 v[200:203], v139 offset:49152
	s_barrier
	s_waitcnt lgkmcnt(0)
	v_mfma_f32_16x16x32_bf16 v[24:27], v[8:11], v[176:179], v[60:63]
	v_mfma_f32_16x16x32_bf16 v[60:63], v[12:15], v[180:183], v[24:27]
	v_mfma_f32_16x16x32_bf16 v[24:27], v[164:167], v[176:179], v[56:59]
	v_mfma_f32_16x16x32_bf16 v[56:59], v[168:171], v[180:183], v[24:27]
	v_mfma_f32_16x16x32_bf16 v[24:27], v[8:11], v[184:187], v[52:55]
	v_mfma_f32_16x16x32_bf16 v[44:47], v[12:15], v[188:191], v[24:27]
	v_mfma_f32_16x16x32_bf16 v[24:27], v[164:167], v[184:187], v[48:51]
	v_mfma_f32_16x16x32_bf16 v[40:43], v[168:171], v[188:191], v[24:27]
	v_mfma_f32_16x16x32_bf16 v[24:27], v[8:11], v[192:195], v[204:207]
	v_mfma_f32_16x16x32_bf16 v[8:11], v[8:11], v[196:199], v[36:39]
	v_mfma_f32_16x16x32_bf16 v[28:31], v[12:15], v[134:137], v[24:27]
	v_mfma_f32_16x16x32_bf16 v[24:27], v[164:167], v[192:195], v[216:219]
	v_mfma_f32_16x16x32_bf16 v[12:15], v[12:15], v[200:203], v[8:11]
	v_mfma_f32_16x16x32_bf16 v[8:11], v[164:167], v[196:199], v[32:35]
	v_mfma_f32_16x16x32_bf16 v[24:27], v[168:171], v[134:137], v[24:27]
	v_mfma_f32_16x16x32_bf16 v[8:11], v[168:171], v[200:203], v[8:11]
	v_mfma_f32_16x16x32_bf16 v[32:35], v[140:143], v[176:179], v[144:147]
	v_mfma_f32_16x16x32_bf16 v[52:55], v[160:163], v[180:183], v[32:35]
	v_mfma_f32_16x16x32_bf16 v[32:35], v[208:211], v[176:179], v[148:151]
	v_mfma_f32_16x16x32_bf16 v[16:19], v[208:211], v[184:187], v[16:19]
	v_mfma_f32_16x16x32_bf16 v[48:51], v[172:175], v[180:183], v[32:35]
	v_mfma_f32_16x16x32_bf16 v[20:23], v[140:143], v[184:187], v[20:23]
	v_mfma_f32_16x16x32_bf16 v[32:35], v[172:175], v[188:191], v[16:19]
	v_mfma_f32_16x16x32_bf16 v[16:19], v[140:143], v[192:195], v[152:155]
	v_mfma_f32_16x16x32_bf16 v[36:39], v[160:163], v[188:191], v[20:23]
	v_mfma_f32_16x16x32_bf16 v[20:23], v[160:163], v[134:137], v[16:19]
	v_mfma_f32_16x16x32_bf16 v[16:19], v[208:211], v[192:195], v[156:159]
	v_mfma_f32_16x16x32_bf16 v[4:7], v[140:143], v[196:199], v[4:7]
	v_mfma_f32_16x16x32_bf16 v[0:3], v[208:211], v[196:199], v[0:3]
	v_mfma_f32_16x16x32_bf16 v[16:19], v[172:175], v[134:137], v[16:19]
	v_mfma_f32_16x16x32_bf16 v[4:7], v[160:163], v[200:203], v[4:7]
	v_mfma_f32_16x16x32_bf16 v[0:3], v[172:175], v[200:203], v[0:3]
	s_andn2_b64 vcc, exec, s[14:15]
	s_barrier
	s_cbranch_vccnz .LBB0_1072
	s_barrier

; #define LDA(dst, b, h) for (int m = 0; m < 4; ++m) for (int k = 0; k < 2; ++k) \
;     dst[m][k] = *reinterpret_cast<const bf16x8*>((char*)SA(b, h) + lds_byte(wr * 64 + m * 16 + fr, k * 32 + fq * 8))
; #define LDB(dst, b, h) for (int n = 0; n < 2; ++n) for (int k = 0; k < 2; ++k) \
;     dst[n][k] = *reinterpret_cast<const bf16x8*>((char*)SB(b, h) + lds_byte(wc * 32 + n * 16 + fr, k * 32 + fq * 8))
; #define MMA(ai, bj, At_, Bt_) do { __builtin_amdgcn_s_setprio(1); \
;     for (int m = 0; m < 4; ++m) for (int n = 0; n < 2; ++n) for (int k = 0; k < 2; ++k) \
;       acc[ai][bj][m][n] = MFMA16(Bt_[n][k], At_[m][k], acc[ai][bj][m][n]); \
;     __builtin_amdgcn_s_setprio(0); } while (0)
; #define WAIT_L(n) asm volatile("s_waitcnt lgkmcnt(" #n ")" ::: "memory")
; #define BAR __builtin_amdgcn_s_barrier()
; #define SCHED __builtin_amdgcn_sched_barrier(0)
; template <int PART  , bool SYNC_FIRST = true>
; __device__ __forceinline__ void kloop_t(const u16* __restrict__ A, int lda, const u16* __restrict__ Bt, int ldb, int K, Acc& acc, const int wv) {
;     ...
;     LDB(B0, 0, 0); SCHED; LDA(At, 0, 0); STAGE(SA(1, 1), A, lda, HALF, t + 1);
;     WAIT_L(8); BAR; WAIT_L(0); MMA(0, 0, At, B0); BAR; SCHED;
;     LDB(B1, 0, 1); STAGE(SB(0, 0), Bt, ldb, 0, t + 2);
;     BAR; WAIT_L(0); MMA(0, 1, At, B1); BAR;
;     LDA(At, 0, 1); STAGE(SA(0, 0), A, lda, 0, t + 2);
.LBB0_1139:
	v_add_u32_e32 v164, v156, v160
	v_add_u32_e32 v166, v156, v162
	v_add_u32_e32 v165, v156, v161
	ds_read_b128 v[174:177], v164
	ds_read_b128 v[178:181], v165
	v_add_u32_e32 v167, v156, v163
	ds_read_b128 v[182:185], v166
	ds_read_b128 v[186:189], v167
	s_add_u32 s44, s42, s56
	v_mov_b32_e32 v170, v131
	v_mov_b32_e32 v128, v130
	s_addc_u32 s45, s43, 0
	ds_read_b128 v[190:193], v132
	ds_read_b128 v[194:197], v133
	ds_read_b128 v[198:201], v134
	ds_read_b128 v[202:205], v135
	ds_read_b128 v[206:209], v136
	ds_read_b128 v[210:213], v137
	ds_read_b128 v[214:217], v138
	ds_read_b128 v[218:221], v139
	v_mov_b32_e32 v171, v129
	v_lshl_add_u64 v[168:169], s[44:45], 0, v[128:129]
	v_lshl_add_u64 v[172:173], v[168:169], 0, s[24:25]
	v_add_u32_e32 v168, 0xc000, v144
	v_add_u32_e32 v169, 0xe000, v144
	v_readfirstlane_b32 s52, v168
	s_mov_b32 m0, s52
	v_lshl_add_u64 v[170:171], s[44:45], 0, v[170:171]
	v_readfirstlane_b32 s52, v169
	global_load_lds_dwordx4 v[172:173], off
	v_lshl_add_u64 v[170:171], v[170:171], 0, s[24:25]
	s_mov_b32 m0, s52
	s_nop 0
	global_load_lds_dwordx4 v[170:171], off
	s_waitcnt lgkmcnt(8)
	s_barrier
	s_waitcnt lgkmcnt(0)
	v_mfma_f32_16x16x32_bf16 v[124:127], v[174:177], v[190:193], v[124:127]
	v_mfma_f32_16x16x32_bf16 v[120:123], v[182:185], v[190:193], v[120:123]
	v_mfma_f32_16x16x32_bf16 v[116:119], v[174:177], v[198:201], v[116:119]
	v_mfma_f32_16x16x32_bf16 v[112:115], v[182:185], v[198:201], v[112:115]
	v_mfma_f32_16x16x32_bf16 v[108:111], v[174:177], v[206:209], v[108:111]
	v_mfma_f32_16x16x32_bf16 v[104:107], v[182:185], v[206:209], v[104:107]
	v_mfma_f32_16x16x32_bf16 v[100:103], v[174:177], v[214:217], v[100:103]
	v_mfma_f32_16x16x32_bf16 v[96:99], v[182:185], v[214:217], v[96:99]
	v_mfma_f32_16x16x32_bf16 v[124:127], v[178:181], v[194:197], v[124:127]
	v_mfma_f32_16x16x32_bf16 v[120:123], v[186:189], v[194:197], v[120:123]
	v_mfma_f32_16x16x32_bf16 v[116:119], v[178:181], v[202:205], v[116:119]
	v_mfma_f32_16x16x32_bf16 v[112:115], v[186:189], v[202:205], v[112:115]
	v_mfma_f32_16x16x32_bf16 v[108:111], v[178:181], v[210:213], v[108:111]
	v_mfma_f32_16x16x32_bf16 v[104:107], v[186:189], v[210:213], v[104:107]
	v_mfma_f32_16x16x32_bf16 v[100:103], v[178:181], v[218:221], v[100:103]
	v_mfma_f32_16x16x32_bf16 v[96:99], v[186:189], v[218:221], v[96:99]
	s_barrier
	s_add_u32 s52, s42, s55
	v_add_u32_e32 v170, v157, v160
	v_add_u32_e32 v172, v157, v162
	v_mov_b32_e32 v238, v131
	v_mov_b32_e32 v128, v130
	s_addc_u32 s53, s43, 0
	v_add_u32_e32 v171, v157, v161
	ds_read_b128 v[222:225], v170
	ds_read_b128 v[226:229], v171
	v_add_u32_e32 v173, v157, v163
	ds_read_b128 v[230:233], v172
	ds_read_b128 v[234:237], v173
	v_readfirstlane_b32 s87, v142
	v_lshl_add_u64 v[240:241], s[52:53], 0, v[128:129]
	v_mov_b32_e32 v239, v129
	v_lshl_add_u64 v[240:241], v[240:241], 0, s[26:27]
	s_mov_b32 m0, s87
	v_lshl_add_u64 v[238:239], s[52:53], 0, v[238:239]
	v_readfirstlane_b32 s87, v143
	global_load_lds_dwordx4 v[240:241], off
	v_lshl_add_u64 v[238:239], v[238:239], 0, s[26:27]
	s_mov_b32 m0, s87
	s_nop 0
	global_load_lds_dwordx4 v[238:239], off
	s_barrier
	s_waitcnt lgkmcnt(0)
	v_mfma_f32_16x16x32_bf16 v[92:95], v[222:225], v[190:193], v[92:95]
	v_mfma_f32_16x16x32_bf16 v[88:91], v[230:233], v[190:193], v[88:91]
	v_mfma_f32_16x16x32_bf16 v[84:87], v[222:225], v[198:201], v[84:87]
	v_mfma_f32_16x16x32_bf16 v[80:83], v[230:233], v[198:201], v[80:83]
	v_mfma_f32_16x16x32_bf16 v[76:79], v[222:225], v[206:209], v[76:79]
	v_mfma_f32_16x16x32_bf16 v[72:75], v[230:233], v[206:209], v[72:75]
	v_mfma_f32_16x16x32_bf16 v[68:71], v[222:225], v[214:217], v[68:71]
	v_mfma_f32_16x16x32_bf16 v[64:67], v[230:233], v[214:217], v[64:67]
	v_mfma_f32_16x16x32_bf16 v[92:95], v[226:229], v[194:197], v[92:95]
	v_mfma_f32_16x16x32_bf16 v[88:91], v[234:237], v[194:197], v[88:91]
	v_mfma_f32_16x16x32_bf16 v[84:87], v[226:229], v[202:205], v[84:87]
	v_mfma_f32_16x16x32_bf16 v[80:83], v[234:237], v[202:205], v[80:83]
	v_mfma_f32_16x16x32_bf16 v[76:79], v[226:229], v[210:213], v[76:79]
	v_mfma_f32_16x16x32_bf16 v[72:75], v[234:237], v[210:213], v[72:75]
	v_mfma_f32_16x16x32_bf16 v[68:71], v[226:229], v[218:221], v[68:71]
	v_mfma_f32_16x16x32_bf16 v[64:67], v[234:237], v[218:221], v[64:67]
	v_mov_b32_e32 v238, v131
	v_mov_b32_e32 v128, v130
	s_barrier
	ds_read_b128 v[190:193], v132 offset:16384
	ds_read_b128 v[194:197], v133 offset:16384
	ds_read_b128 v[198:201], v134 offset:16384
	ds_read_b128 v[202:205], v135 offset:16384
	ds_read_b128 v[206:209], v136 offset:16384
	ds_read_b128 v[210:213], v137 offset:16384
	ds_read_b128 v[214:217], v138 offset:16384
	ds_read_b128 v[218:221], v139 offset:16384
	v_readfirstlane_b32 s87, v144
	v_lshl_add_u64 v[240:241], s[44:45], 0, v[128:129]
	v_mov_b32_e32 v239, v129
	v_lshl_add_u64 v[240:241], v[240:241], 0, s[28:29]
	s_mov_b32 m0, s87
	v_lshl_add_u64 v[238:239], s[44:45], 0, v[238:239]
	v_readfirstlane_b32 s87, v145
	global_load_lds_dwordx4 v[240:241], off
	v_lshl_add_u64 v[238:239], v[238:239], 0, s[28:29]
	s_mov_b32 m0, s87
	s_nop 0
	global_load_lds_dwordx4 v[238:239], off
	s_barrier
; #define LDA(dst, b, h) for (int m = 0; m < 4; ++m) for (int k = 0; k < 2; ++k) \
;     dst[m][k] = *reinterpret_cast<const bf16x8*>((char*)SA(b, h) + lds_byte(wr * 64 + m * 16 + fr, k * 32 + fq * 8))
; #define LDB(dst, b, h) for (int n = 0; n < 2; ++n) for (int k = 0; k < 2; ++k) \
;     dst[n][k] = *reinterpret_cast<const bf16x8*>((char*)SB(b, h) + lds_byte(wc * 32 + n * 16 + fr, k * 32 + fq * 8))
; #define MMA(ai, bj, At_, Bt_) do { __builtin_amdgcn_s_setprio(1); \
;     for (int m = 0; m < 4; ++m) for (int n = 0; n < 2; ++n) for (int k = 0; k < 2; ++k) \
;       acc[ai][bj][m][n] = MFMA16(Bt_[n][k], At_[m][k], acc[ai][bj][m][n]); \
;     __builtin_amdgcn_s_setprio(0); } while (0)
; #define WAIT_V(n) asm volatile("s_waitcnt vmcnt(" #n ")" ::: "memory")
; #define WAIT_L(n) asm volatile("s_waitcnt lgkmcnt(" #n ")" ::: "memory")
; #define BAR __builtin_amdgcn_s_barrier()
; #define SCHED __builtin_amdgcn_sched_barrier(0)
; template <int PART  , bool SYNC_FIRST = true>
; __device__ __forceinline__ void kloop_t(const u16* __restrict__ A, int lda, const u16* __restrict__ Bt, int ldb, int K, Acc& acc, const int wv) {
;     ...
;     BAR; WAIT_L(0); MMA(1, 0, At, B0); BAR; SCHED;
;     STAGE(SB(0, 1), Bt, ldb, HALF, t + 2);
;     WAIT_V(6); BAR; MMA(1, 1, At, B1); BAR;
;     LDB(B0, 1, 0); SCHED; LDA(At, 1, 0); STAGE(SA(0, 1), A, lda, HALF, t + 2);
;     WAIT_L(8); BAR; WAIT_L(0); MMA(0, 0, At, B0); BAR; SCHED;
;     LDB(B1, 1, 1); STAGE(SB(1, 0), Bt, ldb, 0, t + 3);
	s_waitcnt lgkmcnt(0)
	v_mfma_f32_16x16x32_bf16 v[60:63], v[174:177], v[190:193], v[60:63]
	v_mfma_f32_16x16x32_bf16 v[56:59], v[182:185], v[190:193], v[56:59]
	v_mfma_f32_16x16x32_bf16 v[52:55], v[174:177], v[198:201], v[52:55]
	v_mfma_f32_16x16x32_bf16 v[48:51], v[182:185], v[198:201], v[48:51]
	v_mfma_f32_16x16x32_bf16 v[44:47], v[174:177], v[206:209], v[44:47]
	v_mfma_f32_16x16x32_bf16 v[40:43], v[182:185], v[206:209], v[40:43]
	v_mfma_f32_16x16x32_bf16 v[36:39], v[174:177], v[214:217], v[36:39]
	v_mfma_f32_16x16x32_bf16 v[32:35], v[182:185], v[214:217], v[32:35]
	v_mfma_f32_16x16x32_bf16 v[60:63], v[178:181], v[194:197], v[60:63]
	v_mfma_f32_16x16x32_bf16 v[56:59], v[186:189], v[194:197], v[56:59]
	v_mfma_f32_16x16x32_bf16 v[52:55], v[178:181], v[202:205], v[52:55]
	v_mfma_f32_16x16x32_bf16 v[48:51], v[186:189], v[202:205], v[48:51]
	v_mfma_f32_16x16x32_bf16 v[44:47], v[178:181], v[210:213], v[44:47]
	v_mfma_f32_16x16x32_bf16 v[40:43], v[186:189], v[210:213], v[40:43]
	v_mfma_f32_16x16x32_bf16 v[36:39], v[178:181], v[218:221], v[36:39]
	v_mfma_f32_16x16x32_bf16 v[32:35], v[186:189], v[218:221], v[32:35]
	s_barrier
	v_mov_b32_e32 v174, v131
	v_mov_b32_e32 v128, v130
	v_readfirstlane_b32 s87, v146
	v_lshl_add_u64 v[176:177], s[52:53], 0, v[128:129]
	v_mov_b32_e32 v175, v129
	v_lshl_add_u64 v[176:177], v[176:177], 0, s[30:31]
	s_mov_b32 m0, s87
	v_lshl_add_u64 v[174:175], s[52:53], 0, v[174:175]
	v_readfirstlane_b32 s87, v147
	global_load_lds_dwordx4 v[176:177], off
	v_lshl_add_u64 v[174:175], v[174:175], 0, s[30:31]
	s_mov_b32 m0, s87
	s_nop 0
	global_load_lds_dwordx4 v[174:175], off
	s_waitcnt vmcnt(6)
	s_barrier
	v_mfma_f32_16x16x32_bf16 v[28:31], v[222:225], v[190:193], v[28:31]
	v_mfma_f32_16x16x32_bf16 v[24:27], v[230:233], v[190:193], v[24:27]
	v_mfma_f32_16x16x32_bf16 v[20:23], v[222:225], v[198:201], v[20:23]
	v_mfma_f32_16x16x32_bf16 v[16:19], v[230:233], v[198:201], v[16:19]
	v_mfma_f32_16x16x32_bf16 v[12:15], v[222:225], v[206:209], v[12:15]
	v_mfma_f32_16x16x32_bf16 v[8:11], v[230:233], v[206:209], v[8:11]
	v_mfma_f32_16x16x32_bf16 v[4:7], v[222:225], v[214:217], v[4:7]
	v_mfma_f32_16x16x32_bf16 v[0:3], v[230:233], v[214:217], v[0:3]
	v_mfma_f32_16x16x32_bf16 v[28:31], v[226:229], v[194:197], v[28:31]
	v_mfma_f32_16x16x32_bf16 v[24:27], v[234:237], v[194:197], v[24:27]
	v_mfma_f32_16x16x32_bf16 v[20:23], v[226:229], v[202:205], v[20:23]
	v_mfma_f32_16x16x32_bf16 v[16:19], v[234:237], v[202:205], v[16:19]
	v_mfma_f32_16x16x32_bf16 v[12:15], v[226:229], v[210:213], v[12:15]
	v_mfma_f32_16x16x32_bf16 v[8:11], v[234:237], v[210:213], v[8:11]
	v_mfma_f32_16x16x32_bf16 v[4:7], v[226:229], v[218:221], v[4:7]
	v_mfma_f32_16x16x32_bf16 v[0:3], v[234:237], v[218:221], v[0:3]
	v_add_u32_e32 v174, v158, v160
	v_add_u32_e32 v176, v158, v162
	s_barrier
	v_add_u32_e32 v175, v158, v161
	ds_read_b128 v[182:185], v174
	ds_read_b128 v[186:189], v175
	v_add_u32_e32 v177, v158, v163
	ds_read_b128 v[190:193], v176
	ds_read_b128 v[194:197], v177
	v_mov_b32_e32 v178, v131
	v_mov_b32_e32 v128, v130
	ds_read_b128 v[198:201], v132 offset:32768
	ds_read_b128 v[202:205], v133 offset:32768
	ds_read_b128 v[206:209], v134 offset:32768
	ds_read_b128 v[210:213], v135 offset:32768
	ds_read_b128 v[214:217], v136 offset:32768
	ds_read_b128 v[218:221], v137 offset:32768
	ds_read_b128 v[222:225], v138 offset:32768
	ds_read_b128 v[226:229], v139 offset:32768
	v_readfirstlane_b32 s87, v148
	v_lshl_add_u64 v[180:181], s[44:45], 0, v[128:129]
	v_mov_b32_e32 v179, v129
	v_lshl_add_u64 v[180:181], v[180:181], 0, s[34:35]
	s_mov_b32 m0, s87
	v_lshl_add_u64 v[178:179], s[44:45], 0, v[178:179]
	v_readfirstlane_b32 s87, v149
	global_load_lds_dwordx4 v[180:181], off
	v_lshl_add_u64 v[178:179], v[178:179], 0, s[34:35]
	s_mov_b32 m0, s87
	s_nop 0
	global_load_lds_dwordx4 v[178:179], off
	s_waitcnt lgkmcnt(8)
	s_barrier
	s_waitcnt lgkmcnt(0)
	v_mfma_f32_16x16x32_bf16 v[124:127], v[182:185], v[198:201], v[124:127]
	v_mfma_f32_16x16x32_bf16 v[120:123], v[190:193], v[198:201], v[120:123]
	v_mfma_f32_16x16x32_bf16 v[116:119], v[182:185], v[206:209], v[116:119]
	v_mfma_f32_16x16x32_bf16 v[112:115], v[190:193], v[206:209], v[112:115]
	v_mfma_f32_16x16x32_bf16 v[108:111], v[182:185], v[214:217], v[108:111]
	v_mfma_f32_16x16x32_bf16 v[104:107], v[190:193], v[214:217], v[104:107]
	v_mfma_f32_16x16x32_bf16 v[100:103], v[182:185], v[222:225], v[100:103]
	v_mfma_f32_16x16x32_bf16 v[96:99], v[190:193], v[222:225], v[96:99]
	v_mfma_f32_16x16x32_bf16 v[124:127], v[186:189], v[202:205], v[124:127]
	v_mfma_f32_16x16x32_bf16 v[120:123], v[194:197], v[202:205], v[120:123]
	v_mfma_f32_16x16x32_bf16 v[116:119], v[186:189], v[210:213], v[116:119]
	v_mfma_f32_16x16x32_bf16 v[112:115], v[194:197], v[210:213], v[112:115]
	v_mfma_f32_16x16x32_bf16 v[108:111], v[186:189], v[218:221], v[108:111]
	v_mfma_f32_16x16x32_bf16 v[104:107], v[194:197], v[218:221], v[104:107]
	v_mfma_f32_16x16x32_bf16 v[100:103], v[186:189], v[226:229], v[100:103]
	v_mfma_f32_16x16x32_bf16 v[96:99], v[194:197], v[226:229], v[96:99]
	s_barrier
	v_add_u32_e32 v178, v159, v160
	v_add_u32_e32 v180, v159, v162
	v_mov_b32_e32 v246, v131
	v_mov_b32_e32 v128, v130
	v_add_u32_e32 v179, v159, v161
	ds_read_b128 v[230:233], v178
	ds_read_b128 v[234:237], v179
	v_add_u32_e32 v181, v159, v163
	ds_read_b128 v[238:241], v180
	ds_read_b128 v[242:245], v181
	v_readfirstlane_b32 s87, v150
	v_lshl_add_u64 v[248:249], s[52:53], 0, v[128:129]
	v_mov_b32_e32 v247, v129
	v_lshl_add_u64 v[248:249], v[248:249], 0, s[36:37]
	s_mov_b32 m0, s87
	v_lshl_add_u64 v[246:247], s[52:53], 0, v[246:247]
	v_readfirstlane_b32 s87, v151
	global_load_lds_dwordx4 v[248:249], off
	v_lshl_add_u64 v[246:247], v[246:247], 0, s[36:37]
	s_mov_b32 m0, s87
	s_nop 0
	global_load_lds_dwordx4 v[246:247], off
	s_barrier
; #define LDA(dst, b, h) for (int m = 0; m < 4; ++m) for (int k = 0; k < 2; ++k) \
;     dst[m][k] = *reinterpret_cast<const bf16x8*>((char*)SA(b, h) + lds_byte(wr * 64 + m * 16 + fr, k * 32 + fq * 8))
; #define LDB(dst, b, h) for (int n = 0; n < 2; ++n) for (int k = 0; k < 2; ++k) \
;     dst[n][k] = *reinterpret_cast<const bf16x8*>((char*)SB(b, h) + lds_byte(wc * 32 + n * 16 + fr, k * 32 + fq * 8))
; #define MMA(ai, bj, At_, Bt_) do { __builtin_amdgcn_s_setprio(1); \
;     for (int m = 0; m < 4; ++m) for (int n = 0; n < 2; ++n) for (int k = 0; k < 2; ++k) \
;       acc[ai][bj][m][n] = MFMA16(Bt_[n][k], At_[m][k], acc[ai][bj][m][n]); \
;     __builtin_amdgcn_s_setprio(0); } while (0)
; #define WAIT_V(n) asm volatile("s_waitcnt vmcnt(" #n ")" ::: "memory")
; #define WAIT_L(n) asm volatile("s_waitcnt lgkmcnt(" #n ")" ::: "memory")
; #define BAR __builtin_amdgcn_s_barrier()
; #define SCHED __builtin_amdgcn_sched_barrier(0)
; template <int PART  , bool SYNC_FIRST = true>
; __device__ __forceinline__ void kloop_t(const u16* __restrict__ A, int lda, const u16* __restrict__ Bt, int ldb, int K, Acc& acc, const int wv) {
;     ...
;     BAR; WAIT_L(0); MMA(0, 1, At, B1); BAR;
;     LDA(At, 1, 1); STAGE(SA(1, 0), A, lda, 0, t + 3);
;     BAR; WAIT_L(0); MMA(1, 0, At, B0); BAR; SCHED;
;     STAGE(SB(1, 1), Bt, ldb, HALF, t + 3);
;     WAIT_V(6); BAR; MMA(1, 1, At, B1); BAR;
;   }
;   { LDB(B0, 0, 0); LDA(At, 0, 0); STAGE(SA(1, 1), A, lda, HALF, nt - 1);
	s_waitcnt lgkmcnt(0)
	v_mfma_f32_16x16x32_bf16 v[92:95], v[230:233], v[198:201], v[92:95]
	v_mfma_f32_16x16x32_bf16 v[88:91], v[238:241], v[198:201], v[88:91]
	v_mfma_f32_16x16x32_bf16 v[84:87], v[230:233], v[206:209], v[84:87]
	v_mfma_f32_16x16x32_bf16 v[80:83], v[238:241], v[206:209], v[80:83]
	v_mfma_f32_16x16x32_bf16 v[76:79], v[230:233], v[214:217], v[76:79]
	v_mfma_f32_16x16x32_bf16 v[72:75], v[238:241], v[214:217], v[72:75]
	v_mfma_f32_16x16x32_bf16 v[68:71], v[230:233], v[222:225], v[68:71]
	v_mfma_f32_16x16x32_bf16 v[64:67], v[238:241], v[222:225], v[64:67]
	v_mfma_f32_16x16x32_bf16 v[92:95], v[234:237], v[202:205], v[92:95]
	v_mfma_f32_16x16x32_bf16 v[88:91], v[242:245], v[202:205], v[88:91]
	v_mfma_f32_16x16x32_bf16 v[84:87], v[234:237], v[210:213], v[84:87]
	v_mfma_f32_16x16x32_bf16 v[80:83], v[242:245], v[210:213], v[80:83]
	v_mfma_f32_16x16x32_bf16 v[76:79], v[234:237], v[218:221], v[76:79]
	v_mfma_f32_16x16x32_bf16 v[72:75], v[242:245], v[218:221], v[72:75]
	v_mfma_f32_16x16x32_bf16 v[68:71], v[234:237], v[226:229], v[68:71]
	v_mfma_f32_16x16x32_bf16 v[64:67], v[242:245], v[226:229], v[64:67]
	v_mov_b32_e32 v246, v131
	v_mov_b32_e32 v128, v130
	s_barrier
	ds_read_b128 v[198:201], v132 offset:49152
	ds_read_b128 v[202:205], v133 offset:49152
	ds_read_b128 v[206:209], v134 offset:49152
	ds_read_b128 v[210:213], v135 offset:49152
	ds_read_b128 v[214:217], v136 offset:49152
	ds_read_b128 v[218:221], v137 offset:49152
	ds_read_b128 v[222:225], v138 offset:49152
	ds_read_b128 v[226:229], v139 offset:49152
	v_readfirstlane_b32 s87, v152
	v_lshl_add_u64 v[248:249], s[44:45], 0, v[128:129]
	v_mov_b32_e32 v247, v129
	v_lshl_add_u64 v[248:249], v[248:249], 0, s[38:39]
	s_mov_b32 m0, s87
	v_lshl_add_u64 v[246:247], s[44:45], 0, v[246:247]
	v_readfirstlane_b32 s44, v153
	global_load_lds_dwordx4 v[248:249], off
	v_lshl_add_u64 v[246:247], v[246:247], 0, s[38:39]
	s_mov_b32 m0, s44
	s_nop 0
	global_load_lds_dwordx4 v[246:247], off
	s_barrier
	s_waitcnt lgkmcnt(0)
	v_mfma_f32_16x16x32_bf16 v[60:63], v[182:185], v[198:201], v[60:63]
	v_mfma_f32_16x16x32_bf16 v[56:59], v[190:193], v[198:201], v[56:59]
	v_mfma_f32_16x16x32_bf16 v[52:55], v[182:185], v[206:209], v[52:55]
	v_mfma_f32_16x16x32_bf16 v[48:51], v[190:193], v[206:209], v[48:51]
	v_mfma_f32_16x16x32_bf16 v[44:47], v[182:185], v[214:217], v[44:47]
	v_mfma_f32_16x16x32_bf16 v[40:43], v[190:193], v[214:217], v[40:43]
	v_mfma_f32_16x16x32_bf16 v[36:39], v[182:185], v[222:225], v[36:39]
	v_mfma_f32_16x16x32_bf16 v[32:35], v[190:193], v[222:225], v[32:35]
	v_mfma_f32_16x16x32_bf16 v[60:63], v[186:189], v[202:205], v[60:63]
	v_mfma_f32_16x16x32_bf16 v[56:59], v[194:197], v[202:205], v[56:59]
	v_mfma_f32_16x16x32_bf16 v[52:55], v[186:189], v[210:213], v[52:55]
	v_mfma_f32_16x16x32_bf16 v[48:51], v[194:197], v[210:213], v[48:51]
	v_mfma_f32_16x16x32_bf16 v[44:47], v[186:189], v[218:221], v[44:47]
	v_mfma_f32_16x16x32_bf16 v[40:43], v[194:197], v[218:221], v[40:43]
	v_mfma_f32_16x16x32_bf16 v[36:39], v[186:189], v[226:229], v[36:39]
	v_mfma_f32_16x16x32_bf16 v[32:35], v[194:197], v[226:229], v[32:35]
	s_barrier
	v_mov_b32_e32 v182, v131
	v_mov_b32_e32 v128, v130
	v_readfirstlane_b32 s44, v154
	v_lshl_add_u64 v[184:185], s[52:53], 0, v[128:129]
	v_mov_b32_e32 v183, v129
	v_lshl_add_u64 v[184:185], v[184:185], 0, s[40:41]
	s_mov_b32 m0, s44
	v_lshl_add_u64 v[182:183], s[52:53], 0, v[182:183]
	v_readfirstlane_b32 s44, v155
	global_load_lds_dwordx4 v[184:185], off
	v_lshl_add_u64 v[182:183], v[182:183], 0, s[40:41]
	s_mov_b32 m0, s44
	s_nop 0
	global_load_lds_dwordx4 v[182:183], off
	s_waitcnt vmcnt(6)
	s_barrier
	v_mfma_f32_16x16x32_bf16 v[28:31], v[230:233], v[198:201], v[28:31]
	v_mfma_f32_16x16x32_bf16 v[24:27], v[238:241], v[198:201], v[24:27]
	v_mfma_f32_16x16x32_bf16 v[20:23], v[230:233], v[206:209], v[20:23]
	v_mfma_f32_16x16x32_bf16 v[16:19], v[238:241], v[206:209], v[16:19]
	v_mfma_f32_16x16x32_bf16 v[12:15], v[230:233], v[214:217], v[12:15]
	v_mfma_f32_16x16x32_bf16 v[8:11], v[238:241], v[214:217], v[8:11]
	v_mfma_f32_16x16x32_bf16 v[4:7], v[230:233], v[222:225], v[4:7]
	v_mfma_f32_16x16x32_bf16 v[0:3], v[238:241], v[222:225], v[0:3]
	v_mfma_f32_16x16x32_bf16 v[28:31], v[234:237], v[202:205], v[28:31]
	v_mfma_f32_16x16x32_bf16 v[24:27], v[242:245], v[202:205], v[24:27]
	v_mfma_f32_16x16x32_bf16 v[20:23], v[234:237], v[210:213], v[20:23]
	v_mfma_f32_16x16x32_bf16 v[16:19], v[242:245], v[210:213], v[16:19]
	v_mfma_f32_16x16x32_bf16 v[12:15], v[234:237], v[218:221], v[12:15]
	v_mfma_f32_16x16x32_bf16 v[8:11], v[242:245], v[218:221], v[8:11]
	v_mfma_f32_16x16x32_bf16 v[4:7], v[234:237], v[226:229], v[4:7]
	v_mfma_f32_16x16x32_bf16 v[0:3], v[242:245], v[226:229], v[0:3]
	s_add_i32 s57, s57, 2
	s_add_u32 s42, s42, 0x100
	s_addc_u32 s43, s43, 0
	s_cmp_lt_u32 s57, 60
	s_barrier
	s_cbranch_scc1 .LBB0_1139
	s_add_u32 s4, s4, 0x101f80
	v_readfirstlane_b32 s42, v168
	s_addc_u32 s5, s5, 0
	s_mov_b32 m0, s42
	v_readfirstlane_b32 s42, v169
	ds_read_b128 v[142:145], v164
	ds_read_b128 v[146:149], v165
	ds_read_b128 v[150:153], v166
	ds_read_b128 v[154:157], v167
	ds_read_b128 v[158:161], v132
	ds_read_b128 v[162:165], v133
	ds_read_b128 v[182:185], v134
	ds_read_b128 v[186:189], v135
	ds_read_b128 v[190:193], v136
	ds_read_b128 v[194:197], v137
	ds_read_b128 v[198:201], v138
	ds_read_b128 v[202:205], v139
	s_nop 0
	global_load_lds_dwordx4 v130, s[4:5]
	s_mov_b32 m0, s42
	s_nop 0
	global_load_lds_dwordx4 v131, s[4:5]
	s_barrier
; #define LDA(dst, b, h) for (int m = 0; m < 4; ++m) for (int k = 0; k < 2; ++k) \
;     dst[m][k] = *reinterpret_cast<const bf16x8*>((char*)SA(b, h) + lds_byte(wr * 64 + m * 16 + fr, k * 32 + fq * 8))
; #define LDB(dst, b, h) for (int n = 0; n < 2; ++n) for (int k = 0; k < 2; ++k) \
;     dst[n][k] = *reinterpret_cast<const bf16x8*>((char*)SB(b, h) + lds_byte(wc * 32 + n * 16 + fr, k * 32 + fq * 8))
; #define MMA(ai, bj, At_, Bt_) do { __builtin_amdgcn_s_setprio(1); \
;     for (int m = 0; m < 4; ++m) for (int n = 0; n < 2; ++n) for (int k = 0; k < 2; ++k) \
;       acc[ai][bj][m][n] = MFMA16(Bt_[n][k], At_[m][k], acc[ai][bj][m][n]); \
;     __builtin_amdgcn_s_setprio(0); } while (0)
; #define WAIT_V(n) asm volatile("s_waitcnt vmcnt(" #n ")" ::: "memory")
; #define WAIT_L(n) asm volatile("s_waitcnt lgkmcnt(" #n ")" ::: "memory")
; #define BAR __builtin_amdgcn_s_barrier()
; template <int PART  , bool SYNC_FIRST = true>
; __device__ __forceinline__ void kloop_t(const u16* __restrict__ A, int lda, const u16* __restrict__ Bt, int ldb, int K, Acc& acc, const int wv) {
;     ...
;     BAR; WAIT_L(0); MMA(0, 0, At, B0); BAR;
;     LDB(B1, 0, 1); BAR; WAIT_L(0); MMA(0, 1, At, B1); BAR;
;     LDA(At, 0, 1); WAIT_V(4); BAR; WAIT_L(0); MMA(1, 0, At, B0); MMA(1, 1, At, B1); BAR; }
	s_waitcnt lgkmcnt(0)
	v_mfma_f32_16x16x32_bf16 v[124:127], v[142:145], v[158:161], v[124:127]
	v_mfma_f32_16x16x32_bf16 v[120:123], v[150:153], v[158:161], v[120:123]
	v_mfma_f32_16x16x32_bf16 v[108:111], v[142:145], v[190:193], v[108:111]
	v_mfma_f32_16x16x32_bf16 v[104:107], v[150:153], v[190:193], v[104:107]
	v_mfma_f32_16x16x32_bf16 v[124:127], v[146:149], v[162:165], v[124:127]
	v_mfma_f32_16x16x32_bf16 v[120:123], v[154:157], v[162:165], v[120:123]
	v_mfma_f32_16x16x32_bf16 v[116:119], v[142:145], v[182:185], v[116:119]
	v_mfma_f32_16x16x32_bf16 v[112:115], v[150:153], v[182:185], v[112:115]
	v_mfma_f32_16x16x32_bf16 v[108:111], v[146:149], v[194:197], v[108:111]
	v_mfma_f32_16x16x32_bf16 v[104:107], v[154:157], v[194:197], v[104:107]
	v_mfma_f32_16x16x32_bf16 v[100:103], v[142:145], v[198:201], v[100:103]
	v_mfma_f32_16x16x32_bf16 v[96:99], v[150:153], v[198:201], v[96:99]
	v_mfma_f32_16x16x32_bf16 v[166:169], v[146:149], v[186:189], v[116:119]
	v_mfma_f32_16x16x32_bf16 v[206:209], v[154:157], v[186:189], v[112:115]
	v_mfma_f32_16x16x32_bf16 v[210:213], v[146:149], v[202:205], v[100:103]
	v_mfma_f32_16x16x32_bf16 v[214:217], v[154:157], v[202:205], v[96:99]
	s_barrier
	s_nop 1
	ds_read_b128 v[96:99], v170
	ds_read_b128 v[100:103], v171
	ds_read_b128 v[112:115], v172
	ds_read_b128 v[116:119], v173
	s_barrier
	s_waitcnt lgkmcnt(0)
	v_mfma_f32_16x16x32_bf16 v[92:95], v[96:99], v[158:161], v[92:95]
	v_mfma_f32_16x16x32_bf16 v[88:91], v[112:115], v[158:161], v[88:91]
	v_mfma_f32_16x16x32_bf16 v[76:79], v[96:99], v[190:193], v[76:79]
	v_mfma_f32_16x16x32_bf16 v[72:75], v[112:115], v[190:193], v[72:75]
	v_mfma_f32_16x16x32_bf16 v[92:95], v[100:103], v[162:165], v[92:95]
	v_mfma_f32_16x16x32_bf16 v[88:91], v[116:119], v[162:165], v[88:91]
	v_mfma_f32_16x16x32_bf16 v[84:87], v[96:99], v[182:185], v[84:87]
	v_mfma_f32_16x16x32_bf16 v[80:83], v[112:115], v[182:185], v[80:83]
	v_mfma_f32_16x16x32_bf16 v[76:79], v[100:103], v[194:197], v[76:79]
	v_mfma_f32_16x16x32_bf16 v[72:75], v[116:119], v[194:197], v[72:75]
	v_mfma_f32_16x16x32_bf16 v[68:71], v[96:99], v[198:201], v[68:71]
	v_mfma_f32_16x16x32_bf16 v[64:67], v[112:115], v[198:201], v[64:67]
	v_mfma_f32_16x16x32_bf16 v[158:161], v[100:103], v[186:189], v[84:87]
	v_mfma_f32_16x16x32_bf16 v[162:165], v[116:119], v[186:189], v[80:83]
	v_mfma_f32_16x16x32_bf16 v[170:173], v[100:103], v[202:205], v[68:71]
	v_mfma_f32_16x16x32_bf16 v[182:185], v[116:119], v[202:205], v[64:67]
	s_barrier
	s_nop 1
	ds_read_b128 v[64:67], v132 offset:16384
	ds_read_b128 v[68:71], v133 offset:16384
	ds_read_b128 v[80:83], v134 offset:16384
	ds_read_b128 v[84:87], v135 offset:16384
	ds_read_b128 v[186:189], v136 offset:16384
	ds_read_b128 v[190:193], v137 offset:16384
	ds_read_b128 v[194:197], v138 offset:16384
	ds_read_b128 v[198:201], v139 offset:16384
	s_waitcnt vmcnt(4)
	s_barrier
	s_waitcnt lgkmcnt(0)
	v_mfma_f32_16x16x32_bf16 v[60:63], v[142:145], v[64:67], v[60:63]
	v_mfma_f32_16x16x32_bf16 v[56:59], v[150:153], v[64:67], v[56:59]
	v_mfma_f32_16x16x32_bf16 v[44:47], v[142:145], v[186:189], v[44:47]
	v_mfma_f32_16x16x32_bf16 v[40:43], v[150:153], v[186:189], v[40:43]
	v_mfma_f32_16x16x32_bf16 v[60:63], v[146:149], v[68:71], v[60:63]
	v_mfma_f32_16x16x32_bf16 v[56:59], v[154:157], v[68:71], v[56:59]
	v_mfma_f32_16x16x32_bf16 v[52:55], v[142:145], v[80:83], v[52:55]
	v_mfma_f32_16x16x32_bf16 v[48:51], v[150:153], v[80:83], v[48:51]
	v_mfma_f32_16x16x32_bf16 v[44:47], v[146:149], v[190:193], v[44:47]
	v_mfma_f32_16x16x32_bf16 v[40:43], v[154:157], v[190:193], v[40:43]
	v_mfma_f32_16x16x32_bf16 v[36:39], v[142:145], v[194:197], v[36:39]
	v_mfma_f32_16x16x32_bf16 v[32:35], v[150:153], v[194:197], v[32:35]
	v_mfma_f32_16x16x32_bf16 v[202:205], v[146:149], v[84:87], v[52:55]
	v_mfma_f32_16x16x32_bf16 v[218:221], v[154:157], v[84:87], v[48:51]
	v_mfma_f32_16x16x32_bf16 v[142:145], v[146:149], v[198:201], v[36:39]
	v_mfma_f32_16x16x32_bf16 v[146:149], v[154:157], v[198:201], v[32:35]
	v_mfma_f32_16x16x32_bf16 v[28:31], v[96:99], v[64:67], v[28:31]
	v_mfma_f32_16x16x32_bf16 v[24:27], v[112:115], v[64:67], v[24:27]
	v_mfma_f32_16x16x32_bf16 v[12:15], v[96:99], v[186:189], v[12:15]
	v_mfma_f32_16x16x32_bf16 v[8:11], v[112:115], v[186:189], v[8:11]
	v_mfma_f32_16x16x32_bf16 v[28:31], v[100:103], v[68:71], v[28:31]
	v_mfma_f32_16x16x32_bf16 v[24:27], v[116:119], v[68:71], v[24:27]
	v_mfma_f32_16x16x32_bf16 v[20:23], v[96:99], v[80:83], v[20:23]
	v_mfma_f32_16x16x32_bf16 v[16:19], v[112:115], v[80:83], v[16:19]
	v_mfma_f32_16x16x32_bf16 v[12:15], v[100:103], v[190:193], v[12:15]
	v_mfma_f32_16x16x32_bf16 v[8:11], v[116:119], v[190:193], v[8:11]
	v_mfma_f32_16x16x32_bf16 v[4:7], v[96:99], v[194:197], v[4:7]
	v_mfma_f32_16x16x32_bf16 v[0:3], v[112:115], v[194:197], v[0:3]
	v_mfma_f32_16x16x32_bf16 v[150:153], v[100:103], v[84:87], v[20:23]
	v_mfma_f32_16x16x32_bf16 v[154:157], v[116:119], v[84:87], v[16:19]
	v_mfma_f32_16x16x32_bf16 v[186:189], v[100:103], v[198:201], v[4:7]
	v_mfma_f32_16x16x32_bf16 v[190:193], v[116:119], v[198:201], v[0:3]
	s_barrier
; #define LDA(dst, b, h) for (int m = 0; m < 4; ++m) for (int k = 0; k < 2; ++k) \
;     dst[m][k] = *reinterpret_cast<const bf16x8*>((char*)SA(b, h) + lds_byte(wr * 64 + m * 16 + fr, k * 32 + fq * 8))
; #define LDB(dst, b, h) for (int n = 0; n < 2; ++n) for (int k = 0; k < 2; ++k) \
;     dst[n][k] = *reinterpret_cast<const bf16x8*>((char*)SB(b, h) + lds_byte(wc * 32 + n * 16 + fr, k * 32 + fq * 8))
; #define MMA(ai, bj, At_, Bt_) do { __builtin_amdgcn_s_setprio(1); \
;     for (int m = 0; m < 4; ++m) for (int n = 0; n < 2; ++n) for (int k = 0; k < 2; ++k) \
;       acc[ai][bj][m][n] = MFMA16(Bt_[n][k], At_[m][k], acc[ai][bj][m][n]); \
;     __builtin_amdgcn_s_setprio(0); } while (0)
; #define WAIT_V(n) asm volatile("s_waitcnt vmcnt(" #n ")" ::: "memory")
; #define WAIT_L(n) asm volatile("s_waitcnt lgkmcnt(" #n ")" ::: "memory")
; #define BAR __builtin_amdgcn_s_barrier()
; template <int PART  , bool SYNC_FIRST = true>
; __device__ __forceinline__ void kloop_t(const u16* __restrict__ A, int lda, const u16* __restrict__ Bt, int ldb, int K, Acc& acc, const int wv) {
;     ...
;   { LDB(B0, 1, 0); LDA(At, 1, 0); WAIT_V(2); BAR; WAIT_L(0); MMA(0, 0, At, B0); BAR;
;     LDB(B1, 1, 1); WAIT_V(0); BAR; WAIT_L(0); MMA(0, 1, At, B1); BAR;
;     LDA(At, 1, 1); BAR; WAIT_L(0); MMA(1, 0, At, B0); MMA(1, 1, At, B1); BAR; }
;   if (wr == 0) BAR;
	s_nop 1
	ds_read_b128 v[0:3], v174
	ds_read_b128 v[4:7], v175
	ds_read_b128 v[194:197], v176
	ds_read_b128 v[174:177], v177
	ds_read_b128 v[16:19], v132 offset:32768
	ds_read_b128 v[20:23], v133 offset:32768
	ds_read_b128 v[32:35], v134 offset:32768
	ds_read_b128 v[36:39], v135 offset:32768
	ds_read_b128 v[48:51], v136 offset:32768
	ds_read_b128 v[52:55], v137 offset:32768
	ds_read_b128 v[198:201], v138 offset:32768
	ds_read_b128 v[222:225], v139 offset:32768
	s_waitcnt vmcnt(2)
	s_barrier
	s_waitcnt lgkmcnt(0)
	v_mfma_f32_16x16x32_bf16 v[64:67], v[0:3], v[16:19], v[124:127]
	v_mfma_f32_16x16x32_bf16 v[112:115], v[4:7], v[20:23], v[64:67]
	v_mfma_f32_16x16x32_bf16 v[64:67], v[194:197], v[16:19], v[120:123]
	v_mfma_f32_16x16x32_bf16 v[116:119], v[174:177], v[20:23], v[64:67]
	v_mfma_f32_16x16x32_bf16 v[64:67], v[0:3], v[32:35], v[166:169]
	v_mfma_f32_16x16x32_bf16 v[96:99], v[4:7], v[36:39], v[64:67]
	v_mfma_f32_16x16x32_bf16 v[64:67], v[194:197], v[32:35], v[206:209]
	v_mfma_f32_16x16x32_bf16 v[100:103], v[174:177], v[36:39], v[64:67]
	v_mfma_f32_16x16x32_bf16 v[64:67], v[0:3], v[48:51], v[108:111]
	v_mfma_f32_16x16x32_bf16 v[80:83], v[4:7], v[52:55], v[64:67]
	v_mfma_f32_16x16x32_bf16 v[64:67], v[194:197], v[48:51], v[104:107]
	v_mfma_f32_16x16x32_bf16 v[84:87], v[174:177], v[52:55], v[64:67]
	v_mfma_f32_16x16x32_bf16 v[64:67], v[0:3], v[198:201], v[210:213]
	v_mfma_f32_16x16x32_bf16 v[68:71], v[194:197], v[198:201], v[214:217]
	v_mfma_f32_16x16x32_bf16 v[64:67], v[4:7], v[222:225], v[64:67]
	v_mfma_f32_16x16x32_bf16 v[68:71], v[174:177], v[222:225], v[68:71]
	s_barrier
	ds_read_b128 v[166:169], v178
	ds_read_b128 v[206:209], v179
	ds_read_b128 v[210:213], v180
	ds_read_b128 v[178:181], v181
	s_waitcnt vmcnt(0)
	s_barrier
	s_waitcnt lgkmcnt(0)
	v_mfma_f32_16x16x32_bf16 v[92:95], v[166:169], v[16:19], v[92:95]
	v_mfma_f32_16x16x32_bf16 v[16:19], v[210:213], v[16:19], v[88:91]
	v_mfma_f32_16x16x32_bf16 v[124:127], v[178:181], v[20:23], v[16:19]
	v_mfma_f32_16x16x32_bf16 v[16:19], v[166:169], v[32:35], v[158:161]
	v_mfma_f32_16x16x32_bf16 v[104:107], v[206:209], v[36:39], v[16:19]
	v_mfma_f32_16x16x32_bf16 v[16:19], v[210:213], v[32:35], v[162:165]
	v_mfma_f32_16x16x32_bf16 v[108:111], v[178:181], v[36:39], v[16:19]
	v_mfma_f32_16x16x32_bf16 v[16:19], v[166:169], v[48:51], v[76:79]
	v_mfma_f32_16x16x32_bf16 v[88:91], v[206:209], v[52:55], v[16:19]
	v_mfma_f32_16x16x32_bf16 v[16:19], v[210:213], v[48:51], v[72:75]
	v_mfma_f32_16x16x32_bf16 v[120:123], v[206:209], v[20:23], v[92:95]
	v_mfma_f32_16x16x32_bf16 v[92:95], v[178:181], v[52:55], v[16:19]
	v_mfma_f32_16x16x32_bf16 v[16:19], v[166:169], v[198:201], v[170:173]
	v_mfma_f32_16x16x32_bf16 v[72:75], v[206:209], v[222:225], v[16:19]
	v_mfma_f32_16x16x32_bf16 v[16:19], v[210:213], v[198:201], v[182:185]
	v_mfma_f32_16x16x32_bf16 v[76:79], v[178:181], v[222:225], v[16:19]
	s_barrier
	ds_read_b128 v[158:161], v132 offset:49152
	ds_read_b128 v[130:133], v133 offset:49152
	ds_read_b128 v[162:165], v134 offset:49152
	ds_read_b128 v[170:173], v135 offset:49152
	ds_read_b128 v[182:185], v136 offset:49152
	ds_read_b128 v[134:137], v137 offset:49152
	ds_read_b128 v[198:201], v138 offset:49152
	ds_read_b128 v[214:217], v139 offset:49152
	s_barrier
	s_waitcnt lgkmcnt(0)
	v_mfma_f32_16x16x32_bf16 v[16:19], v[0:3], v[158:161], v[60:63]
	v_mfma_f32_16x16x32_bf16 v[48:51], v[4:7], v[130:133], v[16:19]
	v_mfma_f32_16x16x32_bf16 v[16:19], v[194:197], v[158:161], v[56:59]
	v_mfma_f32_16x16x32_bf16 v[52:55], v[174:177], v[130:133], v[16:19]
	v_mfma_f32_16x16x32_bf16 v[16:19], v[0:3], v[162:165], v[202:205]
	v_mfma_f32_16x16x32_bf16 v[32:35], v[4:7], v[170:173], v[16:19]
	v_mfma_f32_16x16x32_bf16 v[16:19], v[194:197], v[162:165], v[218:221]
	v_mfma_f32_16x16x32_bf16 v[36:39], v[174:177], v[170:173], v[16:19]
	v_mfma_f32_16x16x32_bf16 v[16:19], v[0:3], v[182:185], v[44:47]
	v_mfma_f32_16x16x32_bf16 v[0:3], v[0:3], v[198:201], v[142:145]
	v_mfma_f32_16x16x32_bf16 v[16:19], v[4:7], v[134:137], v[16:19]
	v_mfma_f32_16x16x32_bf16 v[20:23], v[194:197], v[182:185], v[40:43]
	v_mfma_f32_16x16x32_bf16 v[0:3], v[4:7], v[214:217], v[0:3]
	v_mfma_f32_16x16x32_bf16 v[4:7], v[194:197], v[198:201], v[146:149]
	v_mfma_f32_16x16x32_bf16 v[20:23], v[174:177], v[134:137], v[20:23]
	v_mfma_f32_16x16x32_bf16 v[4:7], v[174:177], v[214:217], v[4:7]
	v_mfma_f32_16x16x32_bf16 v[24:27], v[210:213], v[158:161], v[24:27]
	v_mfma_f32_16x16x32_bf16 v[60:63], v[178:181], v[130:133], v[24:27]
	v_mfma_f32_16x16x32_bf16 v[24:27], v[166:169], v[162:165], v[150:153]
	v_mfma_f32_16x16x32_bf16 v[28:31], v[166:169], v[158:161], v[28:31]
	v_mfma_f32_16x16x32_bf16 v[40:43], v[206:209], v[170:173], v[24:27]
	v_mfma_f32_16x16x32_bf16 v[24:27], v[210:213], v[162:165], v[154:157]
	v_mfma_f32_16x16x32_bf16 v[12:15], v[166:169], v[182:185], v[12:15]
	v_mfma_f32_16x16x32_bf16 v[8:11], v[210:213], v[182:185], v[8:11]
	v_mfma_f32_16x16x32_bf16 v[56:59], v[206:209], v[130:133], v[28:31]
	v_mfma_f32_16x16x32_bf16 v[44:47], v[178:181], v[170:173], v[24:27]
	v_mfma_f32_16x16x32_bf16 v[24:27], v[206:209], v[134:137], v[12:15]
	v_mfma_f32_16x16x32_bf16 v[28:31], v[178:181], v[134:137], v[8:11]
	v_mfma_f32_16x16x32_bf16 v[8:11], v[166:169], v[198:201], v[186:189]
	v_mfma_f32_16x16x32_bf16 v[12:15], v[210:213], v[198:201], v[190:193]
	v_mfma_f32_16x16x32_bf16 v[8:11], v[206:209], v[214:217], v[8:11]
	v_mfma_f32_16x16x32_bf16 v[12:15], v[178:181], v[214:217], v[12:15]
	s_andn2_b64 vcc, exec, s[16:17]
	s_barrier
	s_cbranch_vccnz .LBB0_1142
	s_barrier
